# E2: peeled first K-loop iteration with C=0 MFMAs, removes 128 v_mov accumulator clears per tile (on top of E1)
# speedup vs baseline: 1.0053x; 1.0053x over previous
.LBB0_303:
	s_lshl_b32 s18, s91, 20
	s_and_b64 s[8:9], s[34:35], exec
	s_cselect_b32 s8, s18, s94
	s_lshl_b32 s19, s90, 20
	s_and_b64 s[42:43], s[34:35], exec
	s_cselect_b32 s9, s19, s95
	s_add_i32 s94, s94, 0x80080
	s_addk_i32 s95, 0x100
	s_mov_b32 vcc_lo, -2
	ds_read_b128 v[142:145], v136
	ds_read_b128 v[170:173], v136 offset:1024
	ds_read_b128 v[174:177], v136 offset:2048
	ds_read_b128 v[178:181], v136 offset:3072
	ds_read_b128 v[182:185], v137
	ds_read_b128 v[186:189], v137 offset:1024
	ds_read_b128 v[190:193], v137 offset:2048
	ds_read_b128 v[194:197], v137 offset:3072
	s_add_i32 s42, s94, 0xfff80080
	s_cmp_eq_u32 vcc_lo, 28
	s_cselect_b32 s97, s8, s42
	s_cselect_b32 s52, s9, s95
	s_or_b32 vcc_hi, s97, 0x80
	s_mov_b32 m0, s72
	ds_read_b128 v[198:201], v138
	ds_read_b128 v[202:205], v138 offset:1024
	ds_read_b128 v[228:231], v138 offset:2048
	ds_read_b128 v[232:235], v138 offset:3072
	ds_read_b128 v[236:239], v138 offset:4096
	ds_read_b128 v[240:243], v138 offset:5120
	ds_read_b128 v[244:247], v138 offset:6144
	ds_read_b128 v[248:251], v138 offset:7168
	buffer_load_dwordx4 v132, s[60:63], s94 offen lds
	s_mov_b32 m0, s47
	s_nop 0
	buffer_load_dwordx4 v134, s[60:63], s94 offen lds
	s_waitcnt vmcnt(8)
	s_waitcnt lgkmcnt(0)
	s_setprio 1
	s_barrier
	v_mfma_f32_16x16x32_bf16 v[114:117], v[142:145], v[198:201], 0
	v_mfma_f32_16x16x32_bf16 v[110:113], v[174:177], v[198:201], 0
	v_mfma_f32_16x16x32_bf16 v[106:109], v[142:145], v[228:231], 0
	v_mfma_f32_16x16x32_bf16 v[102:105], v[174:177], v[228:231], 0
	v_mfma_f32_16x16x32_bf16 v[94:97], v[142:145], v[236:239], 0
	v_mfma_f32_16x16x32_bf16 v[86:89], v[174:177], v[236:239], 0
	v_mfma_f32_16x16x32_bf16 v[78:81], v[142:145], v[244:247], 0
	v_mfma_f32_16x16x32_bf16 v[70:73], v[174:177], v[244:247], 0
	v_mfma_f32_16x16x32_bf16 v[114:117], v[170:173], v[202:205], v[114:117]
	v_mfma_f32_16x16x32_bf16 v[110:113], v[178:181], v[202:205], v[110:113]
	v_mfma_f32_16x16x32_bf16 v[106:109], v[170:173], v[232:235], v[106:109]
	v_mfma_f32_16x16x32_bf16 v[102:105], v[178:181], v[232:235], v[102:105]
	v_mfma_f32_16x16x32_bf16 v[94:97], v[170:173], v[240:243], v[94:97]
	v_mfma_f32_16x16x32_bf16 v[86:89], v[178:181], v[240:243], v[86:89]
	v_mfma_f32_16x16x32_bf16 v[78:81], v[170:173], v[248:251], v[78:81]
	v_mfma_f32_16x16x32_bf16 v[70:73], v[178:181], v[248:251], v[70:73]
	v_mfma_f32_16x16x32_bf16 v[126:129], v[182:185], v[198:201], 0
	v_mfma_f32_16x16x32_bf16 v[122:125], v[190:193], v[198:201], 0
	v_mfma_f32_16x16x32_bf16 v[118:121], v[182:185], v[228:231], 0
	v_mfma_f32_16x16x32_bf16 v[98:101], v[190:193], v[228:231], 0
	v_mfma_f32_16x16x32_bf16 v[90:93], v[182:185], v[236:239], 0
	v_mfma_f32_16x16x32_bf16 v[82:85], v[190:193], v[236:239], 0
	v_mfma_f32_16x16x32_bf16 v[74:77], v[182:185], v[244:247], 0
	v_mfma_f32_16x16x32_bf16 v[66:69], v[190:193], v[244:247], 0
	v_mfma_f32_16x16x32_bf16 v[126:129], v[186:189], v[202:205], v[126:129]
	v_mfma_f32_16x16x32_bf16 v[122:125], v[194:197], v[202:205], v[122:125]
	v_mfma_f32_16x16x32_bf16 v[118:121], v[186:189], v[232:235], v[118:121]
	v_mfma_f32_16x16x32_bf16 v[98:101], v[194:197], v[232:235], v[98:101]
	v_mfma_f32_16x16x32_bf16 v[90:93], v[186:189], v[240:243], v[90:93]
	v_mfma_f32_16x16x32_bf16 v[82:85], v[194:197], v[240:243], v[82:85]
	v_mfma_f32_16x16x32_bf16 v[74:77], v[186:189], v[248:251], v[74:77]
	v_mfma_f32_16x16x32_bf16 v[66:69], v[194:197], v[248:251], v[66:69]
	s_barrier
	s_setprio 0
	s_mov_b32 m0, s13
	s_mov_b32 s42, s62
	s_mov_b32 s43, s63
	ds_read_b128 v[198:201], v138 offset:16384
	ds_read_b128 v[202:205], v138 offset:17408
	ds_read_b128 v[228:231], v138 offset:18432
	ds_read_b128 v[232:235], v138 offset:19456
	ds_read_b128 v[236:239], v138 offset:20480
	ds_read_b128 v[240:243], v138 offset:21504
	ds_read_b128 v[244:247], v138 offset:22528
	ds_read_b128 v[248:251], v138 offset:23552
	buffer_load_dwordx4 v133, s[40:43], s52 offen lds
	s_mov_b32 m0, s14
	s_add_i32 s96, s52, 0x80000
	buffer_load_dwordx4 v135, s[40:43], s52 offen lds
	s_mov_b32 m0, s15
	s_nop 0
	buffer_load_dwordx4 v133, s[40:43], s96 offen lds
	s_mov_b32 m0, s16
	s_nop 0
	buffer_load_dwordx4 v135, s[40:43], s96 offen lds
	s_mov_b32 m0, s2
	s_nop 0
	buffer_load_dwordx4 v132, s[60:63], s97 offen lds
	s_mov_b32 m0, s21
	s_nop 0
	buffer_load_dwordx4 v134, s[60:63], s97 offen lds
	s_waitcnt vmcnt(8)
	s_waitcnt lgkmcnt(0)
	s_setprio 1
	s_barrier
	v_mfma_f32_16x16x32_bf16 v[62:65], v[142:145], v[198:201], 0
	v_mfma_f32_16x16x32_bf16 v[54:57], v[174:177], v[198:201], 0
	v_mfma_f32_16x16x32_bf16 v[46:49], v[142:145], v[228:231], 0
	v_mfma_f32_16x16x32_bf16 v[38:41], v[174:177], v[228:231], 0
	v_mfma_f32_16x16x32_bf16 v[30:33], v[142:145], v[236:239], 0
	v_mfma_f32_16x16x32_bf16 v[22:25], v[174:177], v[236:239], 0
	v_mfma_f32_16x16x32_bf16 v[14:17], v[142:145], v[244:247], 0
	v_mfma_f32_16x16x32_bf16 v[6:9], v[174:177], v[244:247], 0
	v_mfma_f32_16x16x32_bf16 v[62:65], v[170:173], v[202:205], v[62:65]
	v_mfma_f32_16x16x32_bf16 v[54:57], v[178:181], v[202:205], v[54:57]
	v_mfma_f32_16x16x32_bf16 v[46:49], v[170:173], v[232:235], v[46:49]
	v_mfma_f32_16x16x32_bf16 v[38:41], v[178:181], v[232:235], v[38:41]
	v_mfma_f32_16x16x32_bf16 v[30:33], v[170:173], v[240:243], v[30:33]
	v_mfma_f32_16x16x32_bf16 v[22:25], v[178:181], v[240:243], v[22:25]
	v_mfma_f32_16x16x32_bf16 v[14:17], v[170:173], v[248:251], v[14:17]
	v_mfma_f32_16x16x32_bf16 v[6:9], v[178:181], v[248:251], v[6:9]
	v_mfma_f32_16x16x32_bf16 v[58:61], v[182:185], v[198:201], 0
	v_mfma_f32_16x16x32_bf16 v[50:53], v[190:193], v[198:201], 0
	v_mfma_f32_16x16x32_bf16 v[42:45], v[182:185], v[228:231], 0
	v_mfma_f32_16x16x32_bf16 v[34:37], v[190:193], v[228:231], 0
	v_mfma_f32_16x16x32_bf16 v[26:29], v[182:185], v[236:239], 0
	v_mfma_f32_16x16x32_bf16 v[18:21], v[190:193], v[236:239], 0
	v_mfma_f32_16x16x32_bf16 v[10:13], v[182:185], v[244:247], 0
	v_mfma_f32_16x16x32_bf16 v[2:5], v[190:193], v[244:247], 0
	v_mfma_f32_16x16x32_bf16 v[58:61], v[186:189], v[202:205], v[58:61]
	v_mfma_f32_16x16x32_bf16 v[50:53], v[194:197], v[202:205], v[50:53]
	v_mfma_f32_16x16x32_bf16 v[42:45], v[186:189], v[232:235], v[42:45]
	v_mfma_f32_16x16x32_bf16 v[34:37], v[194:197], v[232:235], v[34:37]
	v_mfma_f32_16x16x32_bf16 v[26:29], v[186:189], v[240:243], v[26:29]
	v_mfma_f32_16x16x32_bf16 v[18:21], v[194:197], v[240:243], v[18:21]
	v_mfma_f32_16x16x32_bf16 v[10:13], v[186:189], v[248:251], v[10:13]
	v_mfma_f32_16x16x32_bf16 v[2:5], v[194:197], v[248:251], v[2:5]
	s_barrier
	s_setprio 0
	ds_read_b128 v[142:145], v139
	ds_read_b128 v[170:173], v139 offset:1024
	ds_read_b128 v[174:177], v139 offset:2048
	ds_read_b128 v[178:181], v139 offset:3072
	ds_read_b128 v[182:185], v140
	ds_read_b128 v[186:189], v140 offset:1024
	ds_read_b128 v[190:193], v140 offset:2048
	ds_read_b128 v[194:197], v140 offset:3072
	s_add_i32 s97, s97, 0x80000
	s_mov_b32 m0, s23
	ds_read_b128 v[198:201], v138 offset:32768
	ds_read_b128 v[202:205], v138 offset:33792
	ds_read_b128 v[228:231], v138 offset:34816
	ds_read_b128 v[232:235], v138 offset:35840
	ds_read_b128 v[236:239], v138 offset:36864
	ds_read_b128 v[240:243], v138 offset:37888
	ds_read_b128 v[244:247], v138 offset:38912
	ds_read_b128 v[248:251], v138 offset:39936
	buffer_load_dwordx4 v132, s[60:63], s97 offen lds
	s_mov_b32 m0, s24
	s_nop 0
	buffer_load_dwordx4 v134, s[60:63], s97 offen lds
	s_waitcnt vmcnt(8)
	s_waitcnt lgkmcnt(0)
	s_setprio 1
	s_barrier
	v_mfma_f32_16x16x32_bf16 v[114:117], v[142:145], v[198:201], v[114:117]
	v_mfma_f32_16x16x32_bf16 v[110:113], v[174:177], v[198:201], v[110:113]
	v_mfma_f32_16x16x32_bf16 v[106:109], v[142:145], v[228:231], v[106:109]
	v_mfma_f32_16x16x32_bf16 v[102:105], v[174:177], v[228:231], v[102:105]
	v_mfma_f32_16x16x32_bf16 v[94:97], v[142:145], v[236:239], v[94:97]
	v_mfma_f32_16x16x32_bf16 v[86:89], v[174:177], v[236:239], v[86:89]
	v_mfma_f32_16x16x32_bf16 v[78:81], v[142:145], v[244:247], v[78:81]
	v_mfma_f32_16x16x32_bf16 v[70:73], v[174:177], v[244:247], v[70:73]
	v_mfma_f32_16x16x32_bf16 v[114:117], v[170:173], v[202:205], v[114:117]
	v_mfma_f32_16x16x32_bf16 v[110:113], v[178:181], v[202:205], v[110:113]
	v_mfma_f32_16x16x32_bf16 v[106:109], v[170:173], v[232:235], v[106:109]
	v_mfma_f32_16x16x32_bf16 v[102:105], v[178:181], v[232:235], v[102:105]
	v_mfma_f32_16x16x32_bf16 v[94:97], v[170:173], v[240:243], v[94:97]
	v_mfma_f32_16x16x32_bf16 v[86:89], v[178:181], v[240:243], v[86:89]
	v_mfma_f32_16x16x32_bf16 v[78:81], v[170:173], v[248:251], v[78:81]
	v_mfma_f32_16x16x32_bf16 v[70:73], v[178:181], v[248:251], v[70:73]
	v_mfma_f32_16x16x32_bf16 v[126:129], v[182:185], v[198:201], v[126:129]
	v_mfma_f32_16x16x32_bf16 v[122:125], v[190:193], v[198:201], v[122:125]
	v_mfma_f32_16x16x32_bf16 v[118:121], v[182:185], v[228:231], v[118:121]
	v_mfma_f32_16x16x32_bf16 v[98:101], v[190:193], v[228:231], v[98:101]
	v_mfma_f32_16x16x32_bf16 v[90:93], v[182:185], v[236:239], v[90:93]
	v_mfma_f32_16x16x32_bf16 v[82:85], v[190:193], v[236:239], v[82:85]
	v_mfma_f32_16x16x32_bf16 v[74:77], v[182:185], v[244:247], v[74:77]
	v_mfma_f32_16x16x32_bf16 v[66:69], v[190:193], v[244:247], v[66:69]
	v_mfma_f32_16x16x32_bf16 v[126:129], v[186:189], v[202:205], v[126:129]
	v_mfma_f32_16x16x32_bf16 v[122:125], v[194:197], v[202:205], v[122:125]
	v_mfma_f32_16x16x32_bf16 v[118:121], v[186:189], v[232:235], v[118:121]
	v_mfma_f32_16x16x32_bf16 v[98:101], v[194:197], v[232:235], v[98:101]
	v_mfma_f32_16x16x32_bf16 v[90:93], v[186:189], v[240:243], v[90:93]
	v_mfma_f32_16x16x32_bf16 v[82:85], v[194:197], v[240:243], v[82:85]
	v_mfma_f32_16x16x32_bf16 v[74:77], v[186:189], v[248:251], v[74:77]
	v_mfma_f32_16x16x32_bf16 v[66:69], v[194:197], v[248:251], v[66:69]
	s_barrier
	s_setprio 0
	s_mov_b32 m0, s31
	s_or_b32 s53, s52, 0x80
	ds_read_b128 v[198:201], v138 offset:49152
	ds_read_b128 v[202:205], v138 offset:50176
	ds_read_b128 v[228:231], v138 offset:51200
	ds_read_b128 v[232:235], v138 offset:52224
	ds_read_b128 v[236:239], v138 offset:53248
	ds_read_b128 v[240:243], v138 offset:54272
	ds_read_b128 v[244:247], v138 offset:55296
	ds_read_b128 v[248:251], v138 offset:56320
	buffer_load_dwordx4 v133, s[40:43], s53 offen lds
	s_mov_b32 m0, s33
	s_add_i32 s52, s52, 0x80080
	buffer_load_dwordx4 v135, s[40:43], s53 offen lds
	s_mov_b32 m0, s68
	s_nop 0
	buffer_load_dwordx4 v133, s[40:43], s52 offen lds
	s_mov_b32 m0, s69
	s_nop 0
	buffer_load_dwordx4 v135, s[40:43], s52 offen lds
	s_mov_b32 m0, s36
	s_nop 0
	buffer_load_dwordx4 v132, s[60:63], vcc_hi offen lds
	s_mov_b32 m0, s37
	s_nop 0
	buffer_load_dwordx4 v134, s[60:63], vcc_hi offen lds
	s_waitcnt vmcnt(8)
	s_waitcnt lgkmcnt(0)
	s_setprio 1
	s_barrier
	v_mfma_f32_16x16x32_bf16 v[62:65], v[142:145], v[198:201], v[62:65]
	v_mfma_f32_16x16x32_bf16 v[54:57], v[174:177], v[198:201], v[54:57]
	v_mfma_f32_16x16x32_bf16 v[46:49], v[142:145], v[228:231], v[46:49]
	v_mfma_f32_16x16x32_bf16 v[38:41], v[174:177], v[228:231], v[38:41]
	v_mfma_f32_16x16x32_bf16 v[30:33], v[142:145], v[236:239], v[30:33]
	v_mfma_f32_16x16x32_bf16 v[22:25], v[174:177], v[236:239], v[22:25]
	v_mfma_f32_16x16x32_bf16 v[14:17], v[142:145], v[244:247], v[14:17]
	v_mfma_f32_16x16x32_bf16 v[6:9], v[174:177], v[244:247], v[6:9]
	v_mfma_f32_16x16x32_bf16 v[62:65], v[170:173], v[202:205], v[62:65]
	v_mfma_f32_16x16x32_bf16 v[54:57], v[178:181], v[202:205], v[54:57]
	v_mfma_f32_16x16x32_bf16 v[46:49], v[170:173], v[232:235], v[46:49]
	v_mfma_f32_16x16x32_bf16 v[38:41], v[178:181], v[232:235], v[38:41]
	v_mfma_f32_16x16x32_bf16 v[30:33], v[170:173], v[240:243], v[30:33]
	v_mfma_f32_16x16x32_bf16 v[22:25], v[178:181], v[240:243], v[22:25]
	v_mfma_f32_16x16x32_bf16 v[14:17], v[170:173], v[248:251], v[14:17]
	v_mfma_f32_16x16x32_bf16 v[6:9], v[178:181], v[248:251], v[6:9]
	v_mfma_f32_16x16x32_bf16 v[58:61], v[182:185], v[198:201], v[58:61]
	v_mfma_f32_16x16x32_bf16 v[50:53], v[190:193], v[198:201], v[50:53]
	v_mfma_f32_16x16x32_bf16 v[42:45], v[182:185], v[228:231], v[42:45]
	v_mfma_f32_16x16x32_bf16 v[34:37], v[190:193], v[228:231], v[34:37]
	v_mfma_f32_16x16x32_bf16 v[26:29], v[182:185], v[236:239], v[26:29]
	v_mfma_f32_16x16x32_bf16 v[18:21], v[190:193], v[236:239], v[18:21]
	v_mfma_f32_16x16x32_bf16 v[10:13], v[182:185], v[244:247], v[10:13]
	v_mfma_f32_16x16x32_bf16 v[2:5], v[190:193], v[244:247], v[2:5]
	v_mfma_f32_16x16x32_bf16 v[58:61], v[186:189], v[202:205], v[58:61]
	v_mfma_f32_16x16x32_bf16 v[50:53], v[194:197], v[202:205], v[50:53]
	v_mfma_f32_16x16x32_bf16 v[42:45], v[186:189], v[232:235], v[42:45]
	v_mfma_f32_16x16x32_bf16 v[34:37], v[194:197], v[232:235], v[34:37]
	v_mfma_f32_16x16x32_bf16 v[26:29], v[186:189], v[240:243], v[26:29]
	v_mfma_f32_16x16x32_bf16 v[18:21], v[194:197], v[240:243], v[18:21]
	v_mfma_f32_16x16x32_bf16 v[10:13], v[186:189], v[248:251], v[10:13]
	v_mfma_f32_16x16x32_bf16 v[2:5], v[194:197], v[248:251], v[2:5]
	s_barrier
	s_setprio 0
	s_add_i32 vcc_lo, vcc_lo, 2
	s_addk_i32 s94, 0x100
	s_addk_i32 s95, 0x100
	s_cmp_gt_u32 vcc_lo, 29

.LBB0_579:
	s_mul_i32 s73, s72, 0x2c0000
	s_and_b64 s[8:9], s[42:43], exec
	s_mul_i32 s84, s71, 0x2c0000
	s_cselect_b32 s8, s73, s21
	s_cselect_b32 s9, s84, s13
	s_addk_i32 s13, 0x100
	s_add_i32 s21, s21, 0xc000
	s_mov_b32 s22, -2
	s_waitcnt lgkmcnt(0)
	v_add_u32_e32 v154, 0x10000, v140
	ds_read_b128 v[132:135], v154
	ds_read_b128 v[142:145], v154 offset:1024
	ds_read_b128 v[170:173], v154 offset:2048
	ds_read_b128 v[174:177], v154 offset:3072
	v_add_u32_e32 v154, 0x14000, v140
	ds_read_b128 v[178:181], v154
	ds_read_b128 v[182:185], v154 offset:1024
	ds_read_b128 v[186:189], v154 offset:2048
	ds_read_b128 v[190:193], v154 offset:3072
	s_add_i32 s23, s21, 0x4000
	s_cmpk_eq_i32 s22, 0x54
	s_cselect_b32 s27, s8, s23
	s_cselect_b32 s26, s9, s13
	s_or_b32 s23, s27, 0x8000
	s_mov_b32 m0, s68
	ds_read_b128 v[194:197], v141
	ds_read_b128 v[198:201], v141 offset:1024
	ds_read_b128 v[202:205], v141 offset:2048
	ds_read_b128 v[228:231], v141 offset:3072
	ds_read_b128 v[232:235], v141 offset:4096
	ds_read_b128 v[236:239], v141 offset:5120
	ds_read_b128 v[240:243], v141 offset:6144
	ds_read_b128 v[244:247], v141 offset:7168
	buffer_load_dwordx4 v136, s[60:63], s21 offen lds
	s_mov_b32 m0, s70
	s_nop 0
	buffer_load_dwordx4 v138, s[60:63], s21 offen lds
	s_waitcnt vmcnt(8)
	s_waitcnt lgkmcnt(0)
	s_setprio 1
	s_barrier
	v_mfma_f32_16x16x32_bf16 v[126:129], v[132:135], v[194:197], 0
	v_mfma_f32_16x16x32_bf16 v[106:109], v[170:173], v[194:197], 0
	v_mfma_f32_16x16x32_bf16 v[118:121], v[132:135], v[202:205], 0
	v_mfma_f32_16x16x32_bf16 v[114:117], v[170:173], v[202:205], 0
	v_mfma_f32_16x16x32_bf16 v[94:97], v[132:135], v[232:235], 0
	v_mfma_f32_16x16x32_bf16 v[90:93], v[170:173], v[232:235], 0
	v_mfma_f32_16x16x32_bf16 v[78:81], v[132:135], v[240:243], 0
	v_mfma_f32_16x16x32_bf16 v[74:77], v[170:173], v[240:243], 0
	v_mfma_f32_16x16x32_bf16 v[126:129], v[142:145], v[198:201], v[126:129]
	v_mfma_f32_16x16x32_bf16 v[106:109], v[174:177], v[198:201], v[106:109]
	v_mfma_f32_16x16x32_bf16 v[118:121], v[142:145], v[228:231], v[118:121]
	v_mfma_f32_16x16x32_bf16 v[114:117], v[174:177], v[228:231], v[114:117]
	v_mfma_f32_16x16x32_bf16 v[94:97], v[142:145], v[236:239], v[94:97]
	v_mfma_f32_16x16x32_bf16 v[90:93], v[174:177], v[236:239], v[90:93]
	v_mfma_f32_16x16x32_bf16 v[78:81], v[142:145], v[244:247], v[78:81]
	v_mfma_f32_16x16x32_bf16 v[74:77], v[174:177], v[244:247], v[74:77]
	v_mfma_f32_16x16x32_bf16 v[122:125], v[178:181], v[194:197], 0
	v_mfma_f32_16x16x32_bf16 v[110:113], v[186:189], v[194:197], 0
	v_mfma_f32_16x16x32_bf16 v[102:105], v[178:181], v[202:205], 0
	v_mfma_f32_16x16x32_bf16 v[98:101], v[186:189], v[202:205], 0
	v_mfma_f32_16x16x32_bf16 v[86:89], v[178:181], v[232:235], 0
	v_mfma_f32_16x16x32_bf16 v[82:85], v[186:189], v[232:235], 0
	v_mfma_f32_16x16x32_bf16 v[70:73], v[178:181], v[240:243], 0
	v_mfma_f32_16x16x32_bf16 v[66:69], v[186:189], v[240:243], 0
	v_mfma_f32_16x16x32_bf16 v[122:125], v[182:185], v[198:201], v[122:125]
	v_mfma_f32_16x16x32_bf16 v[110:113], v[190:193], v[198:201], v[110:113]
	v_mfma_f32_16x16x32_bf16 v[102:105], v[182:185], v[228:231], v[102:105]
	v_mfma_f32_16x16x32_bf16 v[98:101], v[190:193], v[228:231], v[98:101]
	v_mfma_f32_16x16x32_bf16 v[86:89], v[182:185], v[236:239], v[86:89]
	v_mfma_f32_16x16x32_bf16 v[82:85], v[190:193], v[236:239], v[82:85]
	v_mfma_f32_16x16x32_bf16 v[70:73], v[182:185], v[244:247], v[70:73]
	v_mfma_f32_16x16x32_bf16 v[66:69], v[190:193], v[244:247], v[66:69]
	s_barrier
	s_setprio 0
	s_mov_b32 m0, s15
	s_mov_b32 s46, s62
	s_mov_b32 s47, s63
	ds_read_b128 v[194:197], v141 offset:16384
	ds_read_b128 v[198:201], v141 offset:17408
	ds_read_b128 v[202:205], v141 offset:18432
	ds_read_b128 v[228:231], v141 offset:19456
	ds_read_b128 v[232:235], v141 offset:20480
	ds_read_b128 v[236:239], v141 offset:21504
	ds_read_b128 v[240:243], v141 offset:22528
	ds_read_b128 v[244:247], v141 offset:23552
	buffer_load_dwordx4 v137, s[44:47], s26 offen lds
	s_mov_b32 m0, s16
	s_add_i32 s52, s26, 0x160000
	buffer_load_dwordx4 v139, s[44:47], s26 offen lds
	s_mov_b32 m0, s18
	s_nop 0
	buffer_load_dwordx4 v137, s[44:47], s52 offen lds
	s_mov_b32 m0, s19
	s_nop 0
	buffer_load_dwordx4 v139, s[44:47], s52 offen lds
	s_mov_b32 m0, s14
	s_nop 0
	buffer_load_dwordx4 v136, s[60:63], s27 offen lds
	s_mov_b32 m0, s24
	s_nop 0
	buffer_load_dwordx4 v138, s[60:63], s27 offen lds
	s_waitcnt vmcnt(8)
	s_waitcnt lgkmcnt(0)
	s_setprio 1
	s_barrier
	v_mfma_f32_16x16x32_bf16 v[62:65], v[132:135], v[194:197], 0
	v_mfma_f32_16x16x32_bf16 v[58:61], v[170:173], v[194:197], 0
	v_mfma_f32_16x16x32_bf16 v[46:49], v[132:135], v[202:205], 0
	v_mfma_f32_16x16x32_bf16 v[42:45], v[170:173], v[202:205], 0
	v_mfma_f32_16x16x32_bf16 v[30:33], v[132:135], v[232:235], 0
	v_mfma_f32_16x16x32_bf16 v[26:29], v[170:173], v[232:235], 0
	v_mfma_f32_16x16x32_bf16 v[14:17], v[132:135], v[240:243], 0
	v_mfma_f32_16x16x32_bf16 v[10:13], v[170:173], v[240:243], 0
	v_mfma_f32_16x16x32_bf16 v[62:65], v[142:145], v[198:201], v[62:65]
	v_mfma_f32_16x16x32_bf16 v[58:61], v[174:177], v[198:201], v[58:61]
	v_mfma_f32_16x16x32_bf16 v[46:49], v[142:145], v[228:231], v[46:49]
	v_mfma_f32_16x16x32_bf16 v[42:45], v[174:177], v[228:231], v[42:45]
	v_mfma_f32_16x16x32_bf16 v[30:33], v[142:145], v[236:239], v[30:33]
	v_mfma_f32_16x16x32_bf16 v[26:29], v[174:177], v[236:239], v[26:29]
	v_mfma_f32_16x16x32_bf16 v[14:17], v[142:145], v[244:247], v[14:17]
	v_mfma_f32_16x16x32_bf16 v[10:13], v[174:177], v[244:247], v[10:13]
	v_mfma_f32_16x16x32_bf16 v[54:57], v[178:181], v[194:197], 0
	v_mfma_f32_16x16x32_bf16 v[50:53], v[186:189], v[194:197], 0
	v_mfma_f32_16x16x32_bf16 v[38:41], v[178:181], v[202:205], 0
	v_mfma_f32_16x16x32_bf16 v[34:37], v[186:189], v[202:205], 0
	v_mfma_f32_16x16x32_bf16 v[22:25], v[178:181], v[232:235], 0
	v_mfma_f32_16x16x32_bf16 v[18:21], v[186:189], v[232:235], 0
	v_mfma_f32_16x16x32_bf16 v[6:9], v[178:181], v[240:243], 0
	v_mfma_f32_16x16x32_bf16 v[2:5], v[186:189], v[240:243], 0
	v_mfma_f32_16x16x32_bf16 v[54:57], v[182:185], v[198:201], v[54:57]
	v_mfma_f32_16x16x32_bf16 v[50:53], v[190:193], v[198:201], v[50:53]
	v_mfma_f32_16x16x32_bf16 v[38:41], v[182:185], v[228:231], v[38:41]
	v_mfma_f32_16x16x32_bf16 v[34:37], v[190:193], v[228:231], v[34:37]
	v_mfma_f32_16x16x32_bf16 v[22:25], v[182:185], v[236:239], v[22:25]
	v_mfma_f32_16x16x32_bf16 v[18:21], v[190:193], v[236:239], v[18:21]
	v_mfma_f32_16x16x32_bf16 v[6:9], v[182:185], v[244:247], v[6:9]
	v_mfma_f32_16x16x32_bf16 v[2:5], v[190:193], v[244:247], v[2:5]
	s_barrier
	s_setprio 0
	v_add_u32_e32 v154, 0x18000, v140
	ds_read_b128 v[132:135], v154
	ds_read_b128 v[142:145], v154 offset:1024
	ds_read_b128 v[170:173], v154 offset:2048
	ds_read_b128 v[174:177], v154 offset:3072
	v_add_u32_e32 v154, 0x1c000, v140
	ds_read_b128 v[178:181], v154
	ds_read_b128 v[182:185], v154 offset:1024
	ds_read_b128 v[186:189], v154 offset:2048
	ds_read_b128 v[190:193], v154 offset:3072
	s_bitset1_b32 s27, 14
	s_mov_b32 m0, s25
	ds_read_b128 v[194:197], v141 offset:32768
	ds_read_b128 v[198:201], v141 offset:33792
	ds_read_b128 v[202:205], v141 offset:34816
	ds_read_b128 v[228:231], v141 offset:35840
	ds_read_b128 v[232:235], v141 offset:36864
	ds_read_b128 v[236:239], v141 offset:37888
	ds_read_b128 v[240:243], v141 offset:38912
	ds_read_b128 v[244:247], v141 offset:39936
	buffer_load_dwordx4 v136, s[60:63], s27 offen lds
	s_mov_b32 m0, s30
	s_nop 0
	buffer_load_dwordx4 v138, s[60:63], s27 offen lds
	s_waitcnt vmcnt(8)
	s_waitcnt lgkmcnt(0)
	s_setprio 1
	s_barrier
	v_mfma_f32_16x16x32_bf16 v[126:129], v[132:135], v[194:197], v[126:129]
	v_mfma_f32_16x16x32_bf16 v[106:109], v[170:173], v[194:197], v[106:109]
	v_mfma_f32_16x16x32_bf16 v[118:121], v[132:135], v[202:205], v[118:121]
	v_mfma_f32_16x16x32_bf16 v[114:117], v[170:173], v[202:205], v[114:117]
	v_mfma_f32_16x16x32_bf16 v[94:97], v[132:135], v[232:235], v[94:97]
	v_mfma_f32_16x16x32_bf16 v[90:93], v[170:173], v[232:235], v[90:93]
	v_mfma_f32_16x16x32_bf16 v[78:81], v[132:135], v[240:243], v[78:81]
	v_mfma_f32_16x16x32_bf16 v[74:77], v[170:173], v[240:243], v[74:77]
	v_mfma_f32_16x16x32_bf16 v[126:129], v[142:145], v[198:201], v[126:129]
	v_mfma_f32_16x16x32_bf16 v[106:109], v[174:177], v[198:201], v[106:109]
	v_mfma_f32_16x16x32_bf16 v[118:121], v[142:145], v[228:231], v[118:121]
	v_mfma_f32_16x16x32_bf16 v[114:117], v[174:177], v[228:231], v[114:117]
	v_mfma_f32_16x16x32_bf16 v[94:97], v[142:145], v[236:239], v[94:97]
	v_mfma_f32_16x16x32_bf16 v[90:93], v[174:177], v[236:239], v[90:93]
	v_mfma_f32_16x16x32_bf16 v[78:81], v[142:145], v[244:247], v[78:81]
	v_mfma_f32_16x16x32_bf16 v[74:77], v[174:177], v[244:247], v[74:77]
	v_mfma_f32_16x16x32_bf16 v[122:125], v[178:181], v[194:197], v[122:125]
	v_mfma_f32_16x16x32_bf16 v[110:113], v[186:189], v[194:197], v[110:113]
	v_mfma_f32_16x16x32_bf16 v[102:105], v[178:181], v[202:205], v[102:105]
	v_mfma_f32_16x16x32_bf16 v[98:101], v[186:189], v[202:205], v[98:101]
	v_mfma_f32_16x16x32_bf16 v[86:89], v[178:181], v[232:235], v[86:89]
	v_mfma_f32_16x16x32_bf16 v[82:85], v[186:189], v[232:235], v[82:85]
	v_mfma_f32_16x16x32_bf16 v[70:73], v[178:181], v[240:243], v[70:73]
	v_mfma_f32_16x16x32_bf16 v[66:69], v[186:189], v[240:243], v[66:69]
	v_mfma_f32_16x16x32_bf16 v[122:125], v[182:185], v[198:201], v[122:125]
	v_mfma_f32_16x16x32_bf16 v[110:113], v[190:193], v[198:201], v[110:113]
	v_mfma_f32_16x16x32_bf16 v[102:105], v[182:185], v[228:231], v[102:105]
	v_mfma_f32_16x16x32_bf16 v[98:101], v[190:193], v[228:231], v[98:101]
	v_mfma_f32_16x16x32_bf16 v[86:89], v[182:185], v[236:239], v[86:89]
	v_mfma_f32_16x16x32_bf16 v[82:85], v[190:193], v[236:239], v[82:85]
	v_mfma_f32_16x16x32_bf16 v[70:73], v[182:185], v[244:247], v[70:73]
	v_mfma_f32_16x16x32_bf16 v[66:69], v[190:193], v[244:247], v[66:69]
	s_barrier
	s_setprio 0
	s_mov_b32 m0, s36
	s_or_b32 s27, s26, 0x80
	ds_read_b128 v[194:197], v141 offset:49152
	ds_read_b128 v[198:201], v141 offset:50176
	ds_read_b128 v[202:205], v141 offset:51200
	ds_read_b128 v[228:231], v141 offset:52224
	ds_read_b128 v[232:235], v141 offset:53248
	ds_read_b128 v[236:239], v141 offset:54272
	ds_read_b128 v[240:243], v141 offset:55296
	ds_read_b128 v[244:247], v141 offset:56320
	buffer_load_dwordx4 v137, s[44:47], s27 offen lds
	s_mov_b32 m0, s37
	s_add_i32 s26, s26, 0x160080
	buffer_load_dwordx4 v139, s[44:47], s27 offen lds
	s_mov_b32 m0, s66
	s_nop 0
	buffer_load_dwordx4 v137, s[44:47], s26 offen lds
	s_mov_b32 m0, s67
	s_nop 0
	buffer_load_dwordx4 v139, s[44:47], s26 offen lds
	s_mov_b32 m0, s48
	s_nop 0
	buffer_load_dwordx4 v136, s[60:63], s23 offen lds
	s_mov_b32 m0, s49
	s_nop 0
	buffer_load_dwordx4 v138, s[60:63], s23 offen lds
	s_waitcnt vmcnt(8)
	s_waitcnt lgkmcnt(0)
	s_setprio 1
	s_barrier
	v_mfma_f32_16x16x32_bf16 v[62:65], v[132:135], v[194:197], v[62:65]
	v_mfma_f32_16x16x32_bf16 v[58:61], v[170:173], v[194:197], v[58:61]
	v_mfma_f32_16x16x32_bf16 v[46:49], v[132:135], v[202:205], v[46:49]
	v_mfma_f32_16x16x32_bf16 v[42:45], v[170:173], v[202:205], v[42:45]
	v_mfma_f32_16x16x32_bf16 v[30:33], v[132:135], v[232:235], v[30:33]
	v_mfma_f32_16x16x32_bf16 v[26:29], v[170:173], v[232:235], v[26:29]
	v_mfma_f32_16x16x32_bf16 v[14:17], v[132:135], v[240:243], v[14:17]
	v_mfma_f32_16x16x32_bf16 v[10:13], v[170:173], v[240:243], v[10:13]
	v_mfma_f32_16x16x32_bf16 v[62:65], v[142:145], v[198:201], v[62:65]
	v_mfma_f32_16x16x32_bf16 v[58:61], v[174:177], v[198:201], v[58:61]
	v_mfma_f32_16x16x32_bf16 v[46:49], v[142:145], v[228:231], v[46:49]
	v_mfma_f32_16x16x32_bf16 v[42:45], v[174:177], v[228:231], v[42:45]
	v_mfma_f32_16x16x32_bf16 v[30:33], v[142:145], v[236:239], v[30:33]
	v_mfma_f32_16x16x32_bf16 v[26:29], v[174:177], v[236:239], v[26:29]
	v_mfma_f32_16x16x32_bf16 v[14:17], v[142:145], v[244:247], v[14:17]
	v_mfma_f32_16x16x32_bf16 v[10:13], v[174:177], v[244:247], v[10:13]
	v_mfma_f32_16x16x32_bf16 v[54:57], v[178:181], v[194:197], v[54:57]
	v_mfma_f32_16x16x32_bf16 v[50:53], v[186:189], v[194:197], v[50:53]
	v_mfma_f32_16x16x32_bf16 v[38:41], v[178:181], v[202:205], v[38:41]
	v_mfma_f32_16x16x32_bf16 v[34:37], v[186:189], v[202:205], v[34:37]
	v_mfma_f32_16x16x32_bf16 v[22:25], v[178:181], v[232:235], v[22:25]
	v_mfma_f32_16x16x32_bf16 v[18:21], v[186:189], v[232:235], v[18:21]
	v_mfma_f32_16x16x32_bf16 v[6:9], v[178:181], v[240:243], v[6:9]
	v_mfma_f32_16x16x32_bf16 v[2:5], v[186:189], v[240:243], v[2:5]
	v_mfma_f32_16x16x32_bf16 v[54:57], v[182:185], v[198:201], v[54:57]
	v_mfma_f32_16x16x32_bf16 v[50:53], v[190:193], v[198:201], v[50:53]
	v_mfma_f32_16x16x32_bf16 v[38:41], v[182:185], v[228:231], v[38:41]
	v_mfma_f32_16x16x32_bf16 v[34:37], v[190:193], v[228:231], v[34:37]
	v_mfma_f32_16x16x32_bf16 v[22:25], v[182:185], v[236:239], v[22:25]
	v_mfma_f32_16x16x32_bf16 v[18:21], v[190:193], v[236:239], v[18:21]
	v_mfma_f32_16x16x32_bf16 v[6:9], v[182:185], v[244:247], v[6:9]
	v_mfma_f32_16x16x32_bf16 v[2:5], v[190:193], v[244:247], v[2:5]
	s_barrier
	s_setprio 0
	s_addk_i32 s13, 0x100
	s_add_i32 s22, s22, 2
	s_add_i32 s21, s21, 0x10000
	s_cmpk_gt_u32 s22, 0x55

.LBB0_858:
	s_lshl_b32 s2, s21, 20
	s_and_b64 s[8:9], s[42:43], exec
	s_cselect_b32 s8, s2, s18
	s_lshl_b32 s82, s71, 20
	s_and_b64 s[26:27], s[42:43], exec
	s_cselect_b32 s9, s82, s19
	s_add_i32 s18, s18, 0x80080
	s_addk_i32 s19, 0x100
	s_mov_b32 s22, -2
	v_add_u32_e32 v146, 0x10000, v195
	ds_read_b128 v[130:133], v146
	ds_read_b128 v[138:141], v146 offset:1024
	ds_read_b128 v[142:145], v146 offset:2048
	ds_read_b128 v[154:157], v146 offset:3072
	v_add_u32_e32 v146, 0x14000, v195
	ds_read_b128 v[170:173], v146
	ds_read_b128 v[174:177], v146 offset:1024
	ds_read_b128 v[178:181], v146 offset:2048
	ds_read_b128 v[182:185], v146 offset:3072
	s_add_i32 s26, s18, 0xfff80080
	s_cmp_eq_u32 s22, 28
	s_cselect_b32 s52, s8, s26
	s_cselect_b32 s27, s9, s19
	s_or_b32 s26, s52, 0x80
	s_mov_b32 m0, s85
	ds_read_b128 v[186:189], v196
	ds_read_b128 v[198:201], v196 offset:1024
	ds_read_b128 v[202:205], v196 offset:2048
	ds_read_b128 v[228:231], v196 offset:3072
	ds_read_b128 v[232:235], v196 offset:4096
	ds_read_b128 v[236:239], v196 offset:5120
	ds_read_b128 v[240:243], v196 offset:6144
	ds_read_b128 v[244:247], v196 offset:7168
	buffer_load_dwordx4 v135, s[44:47], s18 offen lds
	s_mov_b32 m0, s15
	s_nop 0
	buffer_load_dwordx4 v193, s[44:47], s18 offen lds
	s_waitcnt vmcnt(8)
	s_waitcnt lgkmcnt(0)
	s_setprio 1
	s_barrier
	v_mfma_f32_16x16x32_bf16 v[126:129], v[130:133], v[186:189], 0
	v_mfma_f32_16x16x32_bf16 v[122:125], v[142:145], v[186:189], 0
	v_mfma_f32_16x16x32_bf16 v[110:113], v[130:133], v[202:205], 0
	v_mfma_f32_16x16x32_bf16 v[106:109], v[142:145], v[202:205], 0
	v_mfma_f32_16x16x32_bf16 v[94:97], v[130:133], v[232:235], 0
	v_mfma_f32_16x16x32_bf16 v[90:93], v[142:145], v[232:235], 0
	v_mfma_f32_16x16x32_bf16 v[78:81], v[130:133], v[240:243], 0
	v_mfma_f32_16x16x32_bf16 v[74:77], v[142:145], v[240:243], 0
	v_mfma_f32_16x16x32_bf16 v[126:129], v[138:141], v[198:201], v[126:129]
	v_mfma_f32_16x16x32_bf16 v[122:125], v[154:157], v[198:201], v[122:125]
	v_mfma_f32_16x16x32_bf16 v[110:113], v[138:141], v[228:231], v[110:113]
	v_mfma_f32_16x16x32_bf16 v[106:109], v[154:157], v[228:231], v[106:109]
	v_mfma_f32_16x16x32_bf16 v[94:97], v[138:141], v[236:239], v[94:97]
	v_mfma_f32_16x16x32_bf16 v[90:93], v[154:157], v[236:239], v[90:93]
	v_mfma_f32_16x16x32_bf16 v[78:81], v[138:141], v[244:247], v[78:81]
	v_mfma_f32_16x16x32_bf16 v[74:77], v[154:157], v[244:247], v[74:77]
	v_mfma_f32_16x16x32_bf16 v[118:121], v[170:173], v[186:189], 0
	v_mfma_f32_16x16x32_bf16 v[114:117], v[178:181], v[186:189], 0
	v_mfma_f32_16x16x32_bf16 v[102:105], v[170:173], v[202:205], 0
	v_mfma_f32_16x16x32_bf16 v[98:101], v[178:181], v[202:205], 0
	v_mfma_f32_16x16x32_bf16 v[86:89], v[170:173], v[232:235], 0
	v_mfma_f32_16x16x32_bf16 v[82:85], v[178:181], v[232:235], 0
	v_mfma_f32_16x16x32_bf16 v[70:73], v[170:173], v[240:243], 0
	v_mfma_f32_16x16x32_bf16 v[66:69], v[178:181], v[240:243], 0
	v_mfma_f32_16x16x32_bf16 v[118:121], v[174:177], v[198:201], v[118:121]
	v_mfma_f32_16x16x32_bf16 v[114:117], v[182:185], v[198:201], v[114:117]
	v_mfma_f32_16x16x32_bf16 v[102:105], v[174:177], v[228:231], v[102:105]
	v_mfma_f32_16x16x32_bf16 v[98:101], v[182:185], v[228:231], v[98:101]
	v_mfma_f32_16x16x32_bf16 v[86:89], v[174:177], v[236:239], v[86:89]
	v_mfma_f32_16x16x32_bf16 v[82:85], v[182:185], v[236:239], v[82:85]
	v_mfma_f32_16x16x32_bf16 v[70:73], v[174:177], v[244:247], v[70:73]
	v_mfma_f32_16x16x32_bf16 v[66:69], v[182:185], v[244:247], v[66:69]
	s_barrier
	s_setprio 0
	s_mov_b32 m0, s23
	s_mov_b32 s66, s46
	s_mov_b32 s67, s47
	ds_read_b128 v[186:189], v196 offset:16384
	ds_read_b128 v[198:201], v196 offset:17408
	ds_read_b128 v[202:205], v196 offset:18432
	ds_read_b128 v[228:231], v196 offset:19456
	ds_read_b128 v[232:235], v196 offset:20480
	ds_read_b128 v[236:239], v196 offset:21504
	ds_read_b128 v[240:243], v196 offset:22528
	ds_read_b128 v[244:247], v196 offset:23552
	buffer_load_dwordx4 v192, s[64:67], s27 offen lds
	s_mov_b32 m0, s24
	s_add_i32 s53, s27, 0x80000
	buffer_load_dwordx4 v194, s[64:67], s27 offen lds
	s_mov_b32 m0, s25
	s_nop 0
	buffer_load_dwordx4 v192, s[64:67], s53 offen lds
	s_mov_b32 m0, s33
	s_nop 0
	buffer_load_dwordx4 v194, s[64:67], s53 offen lds
	s_mov_b32 m0, s13
	s_nop 0
	buffer_load_dwordx4 v135, s[44:47], s52 offen lds
	s_mov_b32 m0, s34
	s_nop 0
	buffer_load_dwordx4 v193, s[44:47], s52 offen lds
	s_waitcnt vmcnt(8)
	s_waitcnt lgkmcnt(0)
	s_setprio 1
	s_barrier
	v_mfma_f32_16x16x32_bf16 v[62:65], v[130:133], v[186:189], 0
	v_mfma_f32_16x16x32_bf16 v[58:61], v[142:145], v[186:189], 0
	v_mfma_f32_16x16x32_bf16 v[46:49], v[130:133], v[202:205], 0
	v_mfma_f32_16x16x32_bf16 v[42:45], v[142:145], v[202:205], 0
	v_mfma_f32_16x16x32_bf16 v[30:33], v[130:133], v[232:235], 0
	v_mfma_f32_16x16x32_bf16 v[26:29], v[142:145], v[232:235], 0
	v_mfma_f32_16x16x32_bf16 v[14:17], v[130:133], v[240:243], 0
	v_mfma_f32_16x16x32_bf16 v[10:13], v[142:145], v[240:243], 0
	v_mfma_f32_16x16x32_bf16 v[62:65], v[138:141], v[198:201], v[62:65]
	v_mfma_f32_16x16x32_bf16 v[58:61], v[154:157], v[198:201], v[58:61]
	v_mfma_f32_16x16x32_bf16 v[46:49], v[138:141], v[228:231], v[46:49]
	v_mfma_f32_16x16x32_bf16 v[42:45], v[154:157], v[228:231], v[42:45]
	v_mfma_f32_16x16x32_bf16 v[30:33], v[138:141], v[236:239], v[30:33]
	v_mfma_f32_16x16x32_bf16 v[26:29], v[154:157], v[236:239], v[26:29]
	v_mfma_f32_16x16x32_bf16 v[14:17], v[138:141], v[244:247], v[14:17]
	v_mfma_f32_16x16x32_bf16 v[10:13], v[154:157], v[244:247], v[10:13]
	v_mfma_f32_16x16x32_bf16 v[54:57], v[170:173], v[186:189], 0
	v_mfma_f32_16x16x32_bf16 v[50:53], v[178:181], v[186:189], 0
	v_mfma_f32_16x16x32_bf16 v[38:41], v[170:173], v[202:205], 0
	v_mfma_f32_16x16x32_bf16 v[34:37], v[178:181], v[202:205], 0
	v_mfma_f32_16x16x32_bf16 v[22:25], v[170:173], v[232:235], 0
	v_mfma_f32_16x16x32_bf16 v[18:21], v[178:181], v[232:235], 0
	v_mfma_f32_16x16x32_bf16 v[6:9], v[170:173], v[240:243], 0
	v_mfma_f32_16x16x32_bf16 v[2:5], v[178:181], v[240:243], 0
	v_mfma_f32_16x16x32_bf16 v[54:57], v[174:177], v[198:201], v[54:57]
	v_mfma_f32_16x16x32_bf16 v[50:53], v[182:185], v[198:201], v[50:53]
	v_mfma_f32_16x16x32_bf16 v[38:41], v[174:177], v[228:231], v[38:41]
	v_mfma_f32_16x16x32_bf16 v[34:37], v[182:185], v[228:231], v[34:37]
	v_mfma_f32_16x16x32_bf16 v[22:25], v[174:177], v[236:239], v[22:25]
	v_mfma_f32_16x16x32_bf16 v[18:21], v[182:185], v[236:239], v[18:21]
	v_mfma_f32_16x16x32_bf16 v[6:9], v[174:177], v[244:247], v[6:9]
	v_mfma_f32_16x16x32_bf16 v[2:5], v[182:185], v[244:247], v[2:5]
	s_barrier
	s_setprio 0
	v_add_u32_e32 v146, 0x18000, v195
	ds_read_b128 v[130:133], v146
	ds_read_b128 v[138:141], v146 offset:1024
	ds_read_b128 v[142:145], v146 offset:2048
	ds_read_b128 v[154:157], v146 offset:3072
	v_add_u32_e32 v146, 0x1c000, v195
	ds_read_b128 v[170:173], v146
	ds_read_b128 v[174:177], v146 offset:1024
	ds_read_b128 v[178:181], v146 offset:2048
	ds_read_b128 v[182:185], v146 offset:3072
	s_add_i32 s52, s52, 0x80000
	s_mov_b32 m0, s35
	ds_read_b128 v[186:189], v196 offset:32768
	ds_read_b128 v[198:201], v196 offset:33792
	ds_read_b128 v[202:205], v196 offset:34816
	ds_read_b128 v[228:231], v196 offset:35840
	ds_read_b128 v[232:235], v196 offset:36864
	ds_read_b128 v[236:239], v196 offset:37888
	ds_read_b128 v[240:243], v196 offset:38912
	ds_read_b128 v[244:247], v196 offset:39936
	buffer_load_dwordx4 v135, s[44:47], s52 offen lds
	s_mov_b32 m0, s36
	s_nop 0
	buffer_load_dwordx4 v193, s[44:47], s52 offen lds
	s_waitcnt vmcnt(8)
	s_waitcnt lgkmcnt(0)
	s_setprio 1
	s_barrier
	v_mfma_f32_16x16x32_bf16 v[126:129], v[130:133], v[186:189], v[126:129]
	v_mfma_f32_16x16x32_bf16 v[122:125], v[142:145], v[186:189], v[122:125]
	v_mfma_f32_16x16x32_bf16 v[110:113], v[130:133], v[202:205], v[110:113]
	v_mfma_f32_16x16x32_bf16 v[106:109], v[142:145], v[202:205], v[106:109]
	v_mfma_f32_16x16x32_bf16 v[94:97], v[130:133], v[232:235], v[94:97]
	v_mfma_f32_16x16x32_bf16 v[90:93], v[142:145], v[232:235], v[90:93]
	v_mfma_f32_16x16x32_bf16 v[78:81], v[130:133], v[240:243], v[78:81]
	v_mfma_f32_16x16x32_bf16 v[74:77], v[142:145], v[240:243], v[74:77]
	v_mfma_f32_16x16x32_bf16 v[126:129], v[138:141], v[198:201], v[126:129]
	v_mfma_f32_16x16x32_bf16 v[122:125], v[154:157], v[198:201], v[122:125]
	v_mfma_f32_16x16x32_bf16 v[110:113], v[138:141], v[228:231], v[110:113]
	v_mfma_f32_16x16x32_bf16 v[106:109], v[154:157], v[228:231], v[106:109]
	v_mfma_f32_16x16x32_bf16 v[94:97], v[138:141], v[236:239], v[94:97]
	v_mfma_f32_16x16x32_bf16 v[90:93], v[154:157], v[236:239], v[90:93]
	v_mfma_f32_16x16x32_bf16 v[78:81], v[138:141], v[244:247], v[78:81]
	v_mfma_f32_16x16x32_bf16 v[74:77], v[154:157], v[244:247], v[74:77]
	v_mfma_f32_16x16x32_bf16 v[118:121], v[170:173], v[186:189], v[118:121]
	v_mfma_f32_16x16x32_bf16 v[114:117], v[178:181], v[186:189], v[114:117]
	v_mfma_f32_16x16x32_bf16 v[102:105], v[170:173], v[202:205], v[102:105]
	v_mfma_f32_16x16x32_bf16 v[98:101], v[178:181], v[202:205], v[98:101]
	v_mfma_f32_16x16x32_bf16 v[86:89], v[170:173], v[232:235], v[86:89]
	v_mfma_f32_16x16x32_bf16 v[82:85], v[178:181], v[232:235], v[82:85]
	v_mfma_f32_16x16x32_bf16 v[70:73], v[170:173], v[240:243], v[70:73]
	v_mfma_f32_16x16x32_bf16 v[66:69], v[178:181], v[240:243], v[66:69]
	v_mfma_f32_16x16x32_bf16 v[118:121], v[174:177], v[198:201], v[118:121]
	v_mfma_f32_16x16x32_bf16 v[114:117], v[182:185], v[198:201], v[114:117]
	v_mfma_f32_16x16x32_bf16 v[102:105], v[174:177], v[228:231], v[102:105]
	v_mfma_f32_16x16x32_bf16 v[98:101], v[182:185], v[228:231], v[98:101]
	v_mfma_f32_16x16x32_bf16 v[86:89], v[174:177], v[236:239], v[86:89]
	v_mfma_f32_16x16x32_bf16 v[82:85], v[182:185], v[236:239], v[82:85]
	v_mfma_f32_16x16x32_bf16 v[70:73], v[174:177], v[244:247], v[70:73]
	v_mfma_f32_16x16x32_bf16 v[66:69], v[182:185], v[244:247], v[66:69]
	s_barrier
	s_setprio 0
	s_mov_b32 m0, s41
	s_or_b32 s52, s27, 0x80
	ds_read_b128 v[186:189], v196 offset:49152
	ds_read_b128 v[198:201], v196 offset:50176
	ds_read_b128 v[202:205], v196 offset:51200
	ds_read_b128 v[228:231], v196 offset:52224
	ds_read_b128 v[232:235], v196 offset:53248
	ds_read_b128 v[236:239], v196 offset:54272
	ds_read_b128 v[240:243], v196 offset:55296
	ds_read_b128 v[244:247], v196 offset:56320
	buffer_load_dwordx4 v192, s[64:67], s52 offen lds
	s_mov_b32 m0, s48
	s_add_i32 s27, s27, 0x80080
	buffer_load_dwordx4 v194, s[64:67], s52 offen lds
	s_mov_b32 m0, s69
	s_nop 0
	buffer_load_dwordx4 v192, s[64:67], s27 offen lds
	s_mov_b32 m0, s72
	s_nop 0
	buffer_load_dwordx4 v194, s[64:67], s27 offen lds
	s_mov_b32 m0, s49
	s_nop 0
	buffer_load_dwordx4 v135, s[44:47], s26 offen lds
	s_mov_b32 m0, s68
	s_nop 0
	buffer_load_dwordx4 v193, s[44:47], s26 offen lds
	s_waitcnt vmcnt(8)
	s_waitcnt lgkmcnt(0)
	s_setprio 1
	s_barrier
	v_mfma_f32_16x16x32_bf16 v[62:65], v[130:133], v[186:189], v[62:65]
	v_mfma_f32_16x16x32_bf16 v[58:61], v[142:145], v[186:189], v[58:61]
	v_mfma_f32_16x16x32_bf16 v[46:49], v[130:133], v[202:205], v[46:49]
	v_mfma_f32_16x16x32_bf16 v[42:45], v[142:145], v[202:205], v[42:45]
	v_mfma_f32_16x16x32_bf16 v[30:33], v[130:133], v[232:235], v[30:33]
	v_mfma_f32_16x16x32_bf16 v[26:29], v[142:145], v[232:235], v[26:29]
	v_mfma_f32_16x16x32_bf16 v[14:17], v[130:133], v[240:243], v[14:17]
	v_mfma_f32_16x16x32_bf16 v[10:13], v[142:145], v[240:243], v[10:13]
	v_mfma_f32_16x16x32_bf16 v[62:65], v[138:141], v[198:201], v[62:65]
	v_mfma_f32_16x16x32_bf16 v[58:61], v[154:157], v[198:201], v[58:61]
	v_mfma_f32_16x16x32_bf16 v[46:49], v[138:141], v[228:231], v[46:49]
	v_mfma_f32_16x16x32_bf16 v[42:45], v[154:157], v[228:231], v[42:45]
	v_mfma_f32_16x16x32_bf16 v[30:33], v[138:141], v[236:239], v[30:33]
	v_mfma_f32_16x16x32_bf16 v[26:29], v[154:157], v[236:239], v[26:29]
	v_mfma_f32_16x16x32_bf16 v[14:17], v[138:141], v[244:247], v[14:17]
	v_mfma_f32_16x16x32_bf16 v[10:13], v[154:157], v[244:247], v[10:13]
	v_mfma_f32_16x16x32_bf16 v[54:57], v[170:173], v[186:189], v[54:57]
	v_mfma_f32_16x16x32_bf16 v[50:53], v[178:181], v[186:189], v[50:53]
	v_mfma_f32_16x16x32_bf16 v[38:41], v[170:173], v[202:205], v[38:41]
	v_mfma_f32_16x16x32_bf16 v[34:37], v[178:181], v[202:205], v[34:37]
	v_mfma_f32_16x16x32_bf16 v[22:25], v[170:173], v[232:235], v[22:25]
	v_mfma_f32_16x16x32_bf16 v[18:21], v[178:181], v[232:235], v[18:21]
	v_mfma_f32_16x16x32_bf16 v[6:9], v[170:173], v[240:243], v[6:9]
	v_mfma_f32_16x16x32_bf16 v[2:5], v[178:181], v[240:243], v[2:5]
	v_mfma_f32_16x16x32_bf16 v[54:57], v[174:177], v[198:201], v[54:57]
	v_mfma_f32_16x16x32_bf16 v[50:53], v[182:185], v[198:201], v[50:53]
	v_mfma_f32_16x16x32_bf16 v[38:41], v[174:177], v[228:231], v[38:41]
	v_mfma_f32_16x16x32_bf16 v[34:37], v[182:185], v[228:231], v[34:37]
	v_mfma_f32_16x16x32_bf16 v[22:25], v[174:177], v[236:239], v[22:25]
	v_mfma_f32_16x16x32_bf16 v[18:21], v[182:185], v[236:239], v[18:21]
	v_mfma_f32_16x16x32_bf16 v[6:9], v[174:177], v[244:247], v[6:9]
	v_mfma_f32_16x16x32_bf16 v[2:5], v[182:185], v[244:247], v[2:5]
	s_barrier
	s_setprio 0
	s_add_i32 s22, s22, 2
	s_addk_i32 s18, 0x100
	s_addk_i32 s19, 0x100
	s_cmp_gt_u32 s22, 29

.LBB0_880:
	s_lshl_b32 s14, s85, 20
	s_and_b64 s[8:9], s[42:43], exec
	s_cselect_b32 s8, s14, s12
	s_lshl_b32 s15, s66, 20
	s_and_b64 s[22:23], s[42:43], exec
	s_cselect_b32 s9, s15, s13
	s_add_i32 s12, s12, 0x80080
	s_addk_i32 s13, 0x100
	s_mov_b32 s16, -2
	v_add_u32_e32 v139, 0x10000, v234
	ds_read_b128 v[130:133], v139
	ds_read_b128 v[140:143], v139 offset:1024
	ds_read_b128 v[170:173], v139 offset:2048
	ds_read_b128 v[174:177], v139 offset:3072
	v_add_u32_e32 v139, 0x14000, v234
	ds_read_b128 v[178:181], v139
	ds_read_b128 v[182:185], v139 offset:1024
	ds_read_b128 v[186:189], v139 offset:2048
	ds_read_b128 v[190:193], v139 offset:3072
	s_add_i32 s21, s12, 0xfff80080
	s_cmp_eq_u32 s16, 28
	s_cselect_b32 s23, s8, s21
	s_cselect_b32 s22, s9, s13
	s_or_b32 s21, s23, 0x80
	s_mov_b32 m0, s72
	ds_read_b128 v[194:197], v235
	ds_read_b128 v[198:201], v235 offset:1024
	ds_read_b128 v[202:205], v235 offset:2048
	ds_read_b128 v[236:239], v235 offset:3072
	ds_read_b128 v[240:243], v235 offset:4096
	ds_read_b128 v[244:247], v235 offset:5120
	ds_read_b128 v[248:251], v235 offset:6144
	ds_read_b128 v[154:157], v235 offset:7168
	buffer_load_dwordx4 v228, s[60:63], s12 offen lds
	s_mov_b32 m0, s73
	s_nop 0
	buffer_load_dwordx4 v230, s[60:63], s12 offen lds
	s_waitcnt vmcnt(8)
	s_waitcnt lgkmcnt(0)
	s_setprio 1
	s_barrier
	v_mfma_f32_16x16x32_bf16 v[126:129], v[130:133], v[194:197], 0
	v_mfma_f32_16x16x32_bf16 v[122:125], v[170:173], v[194:197], 0
	v_mfma_f32_16x16x32_bf16 v[114:117], v[130:133], v[202:205], 0
	v_mfma_f32_16x16x32_bf16 v[106:109], v[170:173], v[202:205], 0
	v_mfma_f32_16x16x32_bf16 v[98:101], v[130:133], v[240:243], 0
	v_mfma_f32_16x16x32_bf16 v[90:93], v[170:173], v[240:243], 0
	v_mfma_f32_16x16x32_bf16 v[82:85], v[130:133], v[248:251], 0
	v_mfma_f32_16x16x32_bf16 v[74:77], v[170:173], v[248:251], 0
	v_mfma_f32_16x16x32_bf16 v[126:129], v[140:143], v[198:201], v[126:129]
	v_mfma_f32_16x16x32_bf16 v[122:125], v[174:177], v[198:201], v[122:125]
	v_mfma_f32_16x16x32_bf16 v[114:117], v[140:143], v[236:239], v[114:117]
	v_mfma_f32_16x16x32_bf16 v[106:109], v[174:177], v[236:239], v[106:109]
	v_mfma_f32_16x16x32_bf16 v[98:101], v[140:143], v[244:247], v[98:101]
	v_mfma_f32_16x16x32_bf16 v[90:93], v[174:177], v[244:247], v[90:93]
	v_mfma_f32_16x16x32_bf16 v[82:85], v[140:143], v[154:157], v[82:85]
	v_mfma_f32_16x16x32_bf16 v[74:77], v[174:177], v[154:157], v[74:77]
	v_mfma_f32_16x16x32_bf16 v[118:121], v[178:181], v[194:197], 0
	v_mfma_f32_16x16x32_bf16 v[110:113], v[186:189], v[194:197], 0
	v_mfma_f32_16x16x32_bf16 v[102:105], v[178:181], v[202:205], 0
	v_mfma_f32_16x16x32_bf16 v[94:97], v[186:189], v[202:205], 0
	v_mfma_f32_16x16x32_bf16 v[86:89], v[178:181], v[240:243], 0
	v_mfma_f32_16x16x32_bf16 v[78:81], v[186:189], v[240:243], 0
	v_mfma_f32_16x16x32_bf16 v[70:73], v[178:181], v[248:251], 0
	v_mfma_f32_16x16x32_bf16 v[66:69], v[186:189], v[248:251], 0
	v_mfma_f32_16x16x32_bf16 v[118:121], v[182:185], v[198:201], v[118:121]
	v_mfma_f32_16x16x32_bf16 v[110:113], v[190:193], v[198:201], v[110:113]
	v_mfma_f32_16x16x32_bf16 v[102:105], v[182:185], v[236:239], v[102:105]
	v_mfma_f32_16x16x32_bf16 v[94:97], v[190:193], v[236:239], v[94:97]
	v_mfma_f32_16x16x32_bf16 v[86:89], v[182:185], v[244:247], v[86:89]
	v_mfma_f32_16x16x32_bf16 v[78:81], v[190:193], v[244:247], v[78:81]
	v_mfma_f32_16x16x32_bf16 v[70:73], v[182:185], v[154:157], v[70:73]
	v_mfma_f32_16x16x32_bf16 v[66:69], v[190:193], v[154:157], v[66:69]
	s_barrier
	s_setprio 0
	s_mov_b32 m0, s26
	s_mov_b32 s46, s62
	s_mov_b32 s47, s63
	ds_read_b128 v[154:157], v235 offset:16384
	ds_read_b128 v[194:197], v235 offset:17408
	ds_read_b128 v[198:201], v235 offset:18432
	ds_read_b128 v[202:205], v235 offset:19456
	ds_read_b128 v[236:239], v235 offset:20480
	ds_read_b128 v[240:243], v235 offset:21504
	ds_read_b128 v[244:247], v235 offset:22528
	ds_read_b128 v[248:251], v235 offset:23552
	buffer_load_dwordx4 v229, s[44:47], s22 offen lds
	s_mov_b32 m0, s27
	s_add_i32 s38, s22, 0x80000
	buffer_load_dwordx4 v231, s[44:47], s22 offen lds
	s_mov_b32 m0, s34
	s_nop 0
	buffer_load_dwordx4 v229, s[44:47], s38 offen lds
	s_mov_b32 m0, s35
	s_nop 0
	buffer_load_dwordx4 v231, s[44:47], s38 offen lds
	s_mov_b32 m0, s19
	s_nop 0
	buffer_load_dwordx4 v228, s[60:63], s23 offen lds
	s_mov_b32 m0, s36
	s_nop 0
	buffer_load_dwordx4 v230, s[60:63], s23 offen lds
	s_waitcnt vmcnt(8)
	s_waitcnt lgkmcnt(0)
	s_setprio 1
	s_barrier
	v_mfma_f32_16x16x32_bf16 v[62:65], v[130:133], v[154:157], 0
	v_mfma_f32_16x16x32_bf16 v[58:61], v[170:173], v[154:157], 0
	v_mfma_f32_16x16x32_bf16 v[50:53], v[130:133], v[198:201], 0
	v_mfma_f32_16x16x32_bf16 v[42:45], v[170:173], v[198:201], 0
	v_mfma_f32_16x16x32_bf16 v[34:37], v[130:133], v[236:239], 0
	v_mfma_f32_16x16x32_bf16 v[26:29], v[170:173], v[236:239], 0
	v_mfma_f32_16x16x32_bf16 v[18:21], v[130:133], v[244:247], 0
	v_mfma_f32_16x16x32_bf16 v[10:13], v[170:173], v[244:247], 0
	v_mfma_f32_16x16x32_bf16 v[62:65], v[140:143], v[194:197], v[62:65]
	v_mfma_f32_16x16x32_bf16 v[58:61], v[174:177], v[194:197], v[58:61]
	v_mfma_f32_16x16x32_bf16 v[50:53], v[140:143], v[202:205], v[50:53]
	v_mfma_f32_16x16x32_bf16 v[42:45], v[174:177], v[202:205], v[42:45]
	v_mfma_f32_16x16x32_bf16 v[34:37], v[140:143], v[240:243], v[34:37]
	v_mfma_f32_16x16x32_bf16 v[26:29], v[174:177], v[240:243], v[26:29]
	v_mfma_f32_16x16x32_bf16 v[18:21], v[140:143], v[248:251], v[18:21]
	v_mfma_f32_16x16x32_bf16 v[10:13], v[174:177], v[248:251], v[10:13]
	v_mfma_f32_16x16x32_bf16 v[54:57], v[178:181], v[154:157], 0
	v_mfma_f32_16x16x32_bf16 v[46:49], v[186:189], v[154:157], 0
	v_mfma_f32_16x16x32_bf16 v[38:41], v[178:181], v[198:201], 0
	v_mfma_f32_16x16x32_bf16 v[30:33], v[186:189], v[198:201], 0
	v_mfma_f32_16x16x32_bf16 v[22:25], v[178:181], v[236:239], 0
	v_mfma_f32_16x16x32_bf16 v[14:17], v[186:189], v[236:239], 0
	v_mfma_f32_16x16x32_bf16 v[6:9], v[178:181], v[244:247], 0
	v_mfma_f32_16x16x32_bf16 v[2:5], v[186:189], v[244:247], 0
	v_mfma_f32_16x16x32_bf16 v[54:57], v[182:185], v[194:197], v[54:57]
	v_mfma_f32_16x16x32_bf16 v[46:49], v[190:193], v[194:197], v[46:49]
	v_mfma_f32_16x16x32_bf16 v[38:41], v[182:185], v[202:205], v[38:41]
	v_mfma_f32_16x16x32_bf16 v[30:33], v[190:193], v[202:205], v[30:33]
	v_mfma_f32_16x16x32_bf16 v[22:25], v[182:185], v[240:243], v[22:25]
	v_mfma_f32_16x16x32_bf16 v[14:17], v[190:193], v[240:243], v[14:17]
	v_mfma_f32_16x16x32_bf16 v[6:9], v[182:185], v[248:251], v[6:9]
	v_mfma_f32_16x16x32_bf16 v[2:5], v[190:193], v[248:251], v[2:5]
	s_barrier
	s_setprio 0
	v_add_u32_e32 v139, 0x18000, v234
	ds_read_b128 v[130:133], v139
	ds_read_b128 v[140:143], v139 offset:1024
	ds_read_b128 v[154:157], v139 offset:2048
	ds_read_b128 v[170:173], v139 offset:3072
	v_add_u32_e32 v139, 0x1c000, v234
	ds_read_b128 v[174:177], v139
	ds_read_b128 v[178:181], v139 offset:1024
	ds_read_b128 v[182:185], v139 offset:2048
	ds_read_b128 v[186:189], v139 offset:3072
	s_add_i32 s23, s23, 0x80000
	s_mov_b32 m0, s37
	ds_read_b128 v[190:193], v235 offset:32768
	ds_read_b128 v[194:197], v235 offset:33792
	ds_read_b128 v[198:201], v235 offset:34816
	ds_read_b128 v[202:205], v235 offset:35840
	ds_read_b128 v[236:239], v235 offset:36864
	ds_read_b128 v[240:243], v235 offset:37888
	ds_read_b128 v[244:247], v235 offset:38912
	ds_read_b128 v[248:251], v235 offset:39936
	buffer_load_dwordx4 v228, s[60:63], s23 offen lds
	s_mov_b32 m0, s18
	s_nop 0
	buffer_load_dwordx4 v230, s[60:63], s23 offen lds
	s_waitcnt vmcnt(8)
	s_waitcnt lgkmcnt(0)
	s_setprio 1
	s_barrier
	v_mfma_f32_16x16x32_bf16 v[126:129], v[130:133], v[190:193], v[126:129]
	v_mfma_f32_16x16x32_bf16 v[122:125], v[154:157], v[190:193], v[122:125]
	v_mfma_f32_16x16x32_bf16 v[114:117], v[130:133], v[198:201], v[114:117]
	v_mfma_f32_16x16x32_bf16 v[106:109], v[154:157], v[198:201], v[106:109]
	v_mfma_f32_16x16x32_bf16 v[98:101], v[130:133], v[236:239], v[98:101]
	v_mfma_f32_16x16x32_bf16 v[90:93], v[154:157], v[236:239], v[90:93]
	v_mfma_f32_16x16x32_bf16 v[82:85], v[130:133], v[244:247], v[82:85]
	v_mfma_f32_16x16x32_bf16 v[74:77], v[154:157], v[244:247], v[74:77]
	v_mfma_f32_16x16x32_bf16 v[126:129], v[140:143], v[194:197], v[126:129]
	v_mfma_f32_16x16x32_bf16 v[122:125], v[170:173], v[194:197], v[122:125]
	v_mfma_f32_16x16x32_bf16 v[114:117], v[140:143], v[202:205], v[114:117]
	v_mfma_f32_16x16x32_bf16 v[106:109], v[170:173], v[202:205], v[106:109]
	v_mfma_f32_16x16x32_bf16 v[98:101], v[140:143], v[240:243], v[98:101]
	v_mfma_f32_16x16x32_bf16 v[90:93], v[170:173], v[240:243], v[90:93]
	v_mfma_f32_16x16x32_bf16 v[82:85], v[140:143], v[248:251], v[82:85]
	v_mfma_f32_16x16x32_bf16 v[74:77], v[170:173], v[248:251], v[74:77]
	v_mfma_f32_16x16x32_bf16 v[118:121], v[174:177], v[190:193], v[118:121]
	v_mfma_f32_16x16x32_bf16 v[110:113], v[182:185], v[190:193], v[110:113]
	v_mfma_f32_16x16x32_bf16 v[102:105], v[174:177], v[198:201], v[102:105]
	v_mfma_f32_16x16x32_bf16 v[94:97], v[182:185], v[198:201], v[94:97]
	v_mfma_f32_16x16x32_bf16 v[86:89], v[174:177], v[236:239], v[86:89]
	v_mfma_f32_16x16x32_bf16 v[78:81], v[182:185], v[236:239], v[78:81]
	v_mfma_f32_16x16x32_bf16 v[70:73], v[174:177], v[244:247], v[70:73]
	v_mfma_f32_16x16x32_bf16 v[66:69], v[182:185], v[244:247], v[66:69]
	v_mfma_f32_16x16x32_bf16 v[118:121], v[178:181], v[194:197], v[118:121]
	v_mfma_f32_16x16x32_bf16 v[110:113], v[186:189], v[194:197], v[110:113]
	v_mfma_f32_16x16x32_bf16 v[102:105], v[178:181], v[202:205], v[102:105]
	v_mfma_f32_16x16x32_bf16 v[94:97], v[186:189], v[202:205], v[94:97]
	v_mfma_f32_16x16x32_bf16 v[86:89], v[178:181], v[240:243], v[86:89]
	v_mfma_f32_16x16x32_bf16 v[78:81], v[186:189], v[240:243], v[78:81]
	v_mfma_f32_16x16x32_bf16 v[70:73], v[178:181], v[248:251], v[70:73]
	v_mfma_f32_16x16x32_bf16 v[66:69], v[186:189], v[248:251], v[66:69]
	s_barrier
	s_setprio 0
	s_mov_b32 m0, s24
	s_or_b32 s23, s22, 0x80
	ds_read_b128 v[190:193], v235 offset:49152
	ds_read_b128 v[194:197], v235 offset:50176
	ds_read_b128 v[198:201], v235 offset:51200
	ds_read_b128 v[202:205], v235 offset:52224
	ds_read_b128 v[236:239], v235 offset:53248
	ds_read_b128 v[240:243], v235 offset:54272
	ds_read_b128 v[244:247], v235 offset:55296
	ds_read_b128 v[248:251], v235 offset:56320
	buffer_load_dwordx4 v229, s[44:47], s23 offen lds
	s_mov_b32 m0, s25
	s_add_i32 s22, s22, 0x80080
	buffer_load_dwordx4 v231, s[44:47], s23 offen lds
	s_mov_b32 m0, s64
	s_nop 0
	buffer_load_dwordx4 v229, s[44:47], s22 offen lds
	s_mov_b32 m0, s65
	s_nop 0
	buffer_load_dwordx4 v231, s[44:47], s22 offen lds
	s_mov_b32 m0, s48
	s_nop 0
	buffer_load_dwordx4 v228, s[60:63], s21 offen lds
	s_mov_b32 m0, s49
	s_nop 0
	buffer_load_dwordx4 v230, s[60:63], s21 offen lds
	s_waitcnt vmcnt(8)
	s_waitcnt lgkmcnt(0)
	s_setprio 1
	s_barrier
	v_mfma_f32_16x16x32_bf16 v[62:65], v[130:133], v[190:193], v[62:65]
	v_mfma_f32_16x16x32_bf16 v[58:61], v[154:157], v[190:193], v[58:61]
	v_mfma_f32_16x16x32_bf16 v[50:53], v[130:133], v[198:201], v[50:53]
	v_mfma_f32_16x16x32_bf16 v[42:45], v[154:157], v[198:201], v[42:45]
	v_mfma_f32_16x16x32_bf16 v[34:37], v[130:133], v[236:239], v[34:37]
	v_mfma_f32_16x16x32_bf16 v[26:29], v[154:157], v[236:239], v[26:29]
	v_mfma_f32_16x16x32_bf16 v[18:21], v[130:133], v[244:247], v[18:21]
	v_mfma_f32_16x16x32_bf16 v[10:13], v[154:157], v[244:247], v[10:13]
	v_mfma_f32_16x16x32_bf16 v[62:65], v[140:143], v[194:197], v[62:65]
	v_mfma_f32_16x16x32_bf16 v[58:61], v[170:173], v[194:197], v[58:61]
	v_mfma_f32_16x16x32_bf16 v[50:53], v[140:143], v[202:205], v[50:53]
	v_mfma_f32_16x16x32_bf16 v[42:45], v[170:173], v[202:205], v[42:45]
	v_mfma_f32_16x16x32_bf16 v[34:37], v[140:143], v[240:243], v[34:37]
	v_mfma_f32_16x16x32_bf16 v[26:29], v[170:173], v[240:243], v[26:29]
	v_mfma_f32_16x16x32_bf16 v[18:21], v[140:143], v[248:251], v[18:21]
	v_mfma_f32_16x16x32_bf16 v[10:13], v[170:173], v[248:251], v[10:13]
	v_mfma_f32_16x16x32_bf16 v[54:57], v[174:177], v[190:193], v[54:57]
	v_mfma_f32_16x16x32_bf16 v[46:49], v[182:185], v[190:193], v[46:49]
	v_mfma_f32_16x16x32_bf16 v[38:41], v[174:177], v[198:201], v[38:41]
	v_mfma_f32_16x16x32_bf16 v[30:33], v[182:185], v[198:201], v[30:33]
	v_mfma_f32_16x16x32_bf16 v[22:25], v[174:177], v[236:239], v[22:25]
	v_mfma_f32_16x16x32_bf16 v[14:17], v[182:185], v[236:239], v[14:17]
	v_mfma_f32_16x16x32_bf16 v[6:9], v[174:177], v[244:247], v[6:9]
	v_mfma_f32_16x16x32_bf16 v[2:5], v[182:185], v[244:247], v[2:5]
	v_mfma_f32_16x16x32_bf16 v[54:57], v[178:181], v[194:197], v[54:57]
	v_mfma_f32_16x16x32_bf16 v[46:49], v[186:189], v[194:197], v[46:49]
	v_mfma_f32_16x16x32_bf16 v[38:41], v[178:181], v[202:205], v[38:41]
	v_mfma_f32_16x16x32_bf16 v[30:33], v[186:189], v[202:205], v[30:33]
	v_mfma_f32_16x16x32_bf16 v[22:25], v[178:181], v[240:243], v[22:25]
	v_mfma_f32_16x16x32_bf16 v[14:17], v[186:189], v[240:243], v[14:17]
	v_mfma_f32_16x16x32_bf16 v[6:9], v[178:181], v[248:251], v[6:9]
	v_mfma_f32_16x16x32_bf16 v[2:5], v[186:189], v[248:251], v[2:5]
	s_barrier
	s_setprio 0
	s_add_i32 s16, s16, 2
	s_addk_i32 s12, 0x100
	s_addk_i32 s13, 0x100
	s_cmp_gt_u32 s16, 29

.LBB0_904:
	s_lshl_b32 s73, s72, 20
	s_and_b64 s[8:9], s[42:43], exec
	s_cselect_b32 s8, s73, s13
	s_lshl_b32 s84, s71, 20
	s_and_b64 s[22:23], s[42:43], exec
	s_cselect_b32 s9, s84, s21
	s_add_i32 s13, s13, 0x80080
	s_addk_i32 s21, 0x100
	s_mov_b32 s22, -2
	v_add_u32_e32 v133, 0x10000, v178
	ds_read_b128 v[134:137], v133
	ds_read_b128 v[138:141], v133 offset:1024
	ds_read_b128 v[142:145], v133 offset:2048
	ds_read_b128 v[154:157], v133 offset:3072
	v_add_u32_e32 v133, 0x14000, v178
	ds_read_b128 v[170:173], v133
	ds_read_b128 v[180:183], v133 offset:1024
	ds_read_b128 v[184:187], v133 offset:2048
	ds_read_b128 v[188:191], v133 offset:3072
	s_add_i32 s23, s13, 0xfff80080
	s_cmp_eq_u32 s22, 28
	s_cselect_b32 s27, s8, s23
	s_cselect_b32 s26, s9, s21
	s_or_b32 s23, s27, 0x80
	s_mov_b32 s46, s62
	s_mov_b32 s47, s63
	s_mov_b32 m0, s68
	ds_read_b128 v[192:195], v179
	ds_read_b128 v[196:199], v179 offset:1024
	ds_read_b128 v[200:203], v179 offset:2048
	ds_read_b128 v[204:207], v179 offset:3072
	ds_read_b128 v[228:231], v179 offset:4096
	ds_read_b128 v[232:235], v179 offset:5120
	ds_read_b128 v[236:239], v179 offset:6144
	ds_read_b128 v[240:243], v179 offset:7168
	buffer_load_dwordx4 v174, s[44:47], s13 offen lds
	s_mov_b32 m0, s69
	s_nop 0
	buffer_load_dwordx4 v176, s[44:47], s13 offen lds
	s_waitcnt vmcnt(8)
	s_waitcnt lgkmcnt(0)
	s_setprio 1
	s_barrier
	v_mfma_f32_16x16x32_bf16 v[126:129], v[134:137], v[192:195], 0
	v_mfma_f32_16x16x32_bf16 v[122:125], v[142:145], v[192:195], 0
	v_mfma_f32_16x16x32_bf16 v[110:113], v[134:137], v[200:203], 0
	v_mfma_f32_16x16x32_bf16 v[106:109], v[142:145], v[200:203], 0
	v_mfma_f32_16x16x32_bf16 v[94:97], v[134:137], v[228:231], 0
	v_mfma_f32_16x16x32_bf16 v[90:93], v[142:145], v[228:231], 0
	v_mfma_f32_16x16x32_bf16 v[78:81], v[134:137], v[236:239], 0
	v_mfma_f32_16x16x32_bf16 v[74:77], v[142:145], v[236:239], 0
	v_mfma_f32_16x16x32_bf16 v[126:129], v[138:141], v[196:199], v[126:129]
	v_mfma_f32_16x16x32_bf16 v[122:125], v[154:157], v[196:199], v[122:125]
	v_mfma_f32_16x16x32_bf16 v[110:113], v[138:141], v[204:207], v[110:113]
	v_mfma_f32_16x16x32_bf16 v[106:109], v[154:157], v[204:207], v[106:109]
	v_mfma_f32_16x16x32_bf16 v[94:97], v[138:141], v[232:235], v[94:97]
	v_mfma_f32_16x16x32_bf16 v[90:93], v[154:157], v[232:235], v[90:93]
	v_mfma_f32_16x16x32_bf16 v[78:81], v[138:141], v[240:243], v[78:81]
	v_mfma_f32_16x16x32_bf16 v[74:77], v[154:157], v[240:243], v[74:77]
	v_mfma_f32_16x16x32_bf16 v[118:121], v[170:173], v[192:195], 0
	v_mfma_f32_16x16x32_bf16 v[114:117], v[184:187], v[192:195], 0
	v_mfma_f32_16x16x32_bf16 v[102:105], v[170:173], v[200:203], 0
	v_mfma_f32_16x16x32_bf16 v[98:101], v[184:187], v[200:203], 0
	v_mfma_f32_16x16x32_bf16 v[86:89], v[170:173], v[228:231], 0
	v_mfma_f32_16x16x32_bf16 v[82:85], v[184:187], v[228:231], 0
	v_mfma_f32_16x16x32_bf16 v[70:73], v[170:173], v[236:239], 0
	v_mfma_f32_16x16x32_bf16 v[66:69], v[184:187], v[236:239], 0
	v_mfma_f32_16x16x32_bf16 v[118:121], v[180:183], v[196:199], v[118:121]
	v_mfma_f32_16x16x32_bf16 v[114:117], v[188:191], v[196:199], v[114:117]
	v_mfma_f32_16x16x32_bf16 v[102:105], v[180:183], v[204:207], v[102:105]
	v_mfma_f32_16x16x32_bf16 v[98:101], v[188:191], v[204:207], v[98:101]
	v_mfma_f32_16x16x32_bf16 v[86:89], v[180:183], v[232:235], v[86:89]
	v_mfma_f32_16x16x32_bf16 v[82:85], v[188:191], v[232:235], v[82:85]
	v_mfma_f32_16x16x32_bf16 v[70:73], v[180:183], v[240:243], v[70:73]
	v_mfma_f32_16x16x32_bf16 v[66:69], v[188:191], v[240:243], v[66:69]
	s_barrier
	s_setprio 0
	s_mov_b32 m0, s15
	ds_read_b128 v[192:195], v179 offset:16384
	ds_read_b128 v[196:199], v179 offset:17408
	ds_read_b128 v[200:203], v179 offset:18432
	ds_read_b128 v[204:207], v179 offset:19456
	ds_read_b128 v[228:231], v179 offset:20480
	ds_read_b128 v[232:235], v179 offset:21504
	ds_read_b128 v[236:239], v179 offset:22528
	ds_read_b128 v[240:243], v179 offset:23552
	buffer_load_dwordx4 v175, s[60:63], s26 offen lds
	s_mov_b32 m0, s16
	s_add_i32 s34, s26, 0x80000
	buffer_load_dwordx4 v177, s[60:63], s26 offen lds
	s_mov_b32 m0, s18
	s_nop 0
	buffer_load_dwordx4 v175, s[60:63], s34 offen lds
	s_mov_b32 m0, s19
	s_nop 0
	buffer_load_dwordx4 v177, s[60:63], s34 offen lds
	s_mov_b32 m0, s14
	s_nop 0
	buffer_load_dwordx4 v174, s[44:47], s27 offen lds
	s_mov_b32 m0, s24
	s_nop 0
	buffer_load_dwordx4 v176, s[44:47], s27 offen lds
	s_waitcnt vmcnt(8)
	s_waitcnt lgkmcnt(0)
	s_setprio 1
	s_barrier
	v_mfma_f32_16x16x32_bf16 v[62:65], v[134:137], v[192:195], 0
	v_mfma_f32_16x16x32_bf16 v[58:61], v[142:145], v[192:195], 0
	v_mfma_f32_16x16x32_bf16 v[46:49], v[134:137], v[200:203], 0
	v_mfma_f32_16x16x32_bf16 v[42:45], v[142:145], v[200:203], 0
	v_mfma_f32_16x16x32_bf16 v[30:33], v[134:137], v[228:231], 0
	v_mfma_f32_16x16x32_bf16 v[26:29], v[142:145], v[228:231], 0
	v_mfma_f32_16x16x32_bf16 v[14:17], v[134:137], v[236:239], 0
	v_mfma_f32_16x16x32_bf16 v[10:13], v[142:145], v[236:239], 0
	v_mfma_f32_16x16x32_bf16 v[62:65], v[138:141], v[196:199], v[62:65]
	v_mfma_f32_16x16x32_bf16 v[58:61], v[154:157], v[196:199], v[58:61]
	v_mfma_f32_16x16x32_bf16 v[46:49], v[138:141], v[204:207], v[46:49]
	v_mfma_f32_16x16x32_bf16 v[42:45], v[154:157], v[204:207], v[42:45]
	v_mfma_f32_16x16x32_bf16 v[30:33], v[138:141], v[232:235], v[30:33]
	v_mfma_f32_16x16x32_bf16 v[26:29], v[154:157], v[232:235], v[26:29]
	v_mfma_f32_16x16x32_bf16 v[14:17], v[138:141], v[240:243], v[14:17]
	v_mfma_f32_16x16x32_bf16 v[10:13], v[154:157], v[240:243], v[10:13]
	v_mfma_f32_16x16x32_bf16 v[54:57], v[170:173], v[192:195], 0
	v_mfma_f32_16x16x32_bf16 v[50:53], v[184:187], v[192:195], 0
	v_mfma_f32_16x16x32_bf16 v[38:41], v[170:173], v[200:203], 0
	v_mfma_f32_16x16x32_bf16 v[34:37], v[184:187], v[200:203], 0
	v_mfma_f32_16x16x32_bf16 v[22:25], v[170:173], v[228:231], 0
	v_mfma_f32_16x16x32_bf16 v[18:21], v[184:187], v[228:231], 0
	v_mfma_f32_16x16x32_bf16 v[6:9], v[170:173], v[236:239], 0
	v_mfma_f32_16x16x32_bf16 v[2:5], v[184:187], v[236:239], 0
	v_mfma_f32_16x16x32_bf16 v[54:57], v[180:183], v[196:199], v[54:57]
	v_mfma_f32_16x16x32_bf16 v[50:53], v[188:191], v[196:199], v[50:53]
	v_mfma_f32_16x16x32_bf16 v[38:41], v[180:183], v[204:207], v[38:41]
	v_mfma_f32_16x16x32_bf16 v[34:37], v[188:191], v[204:207], v[34:37]
	v_mfma_f32_16x16x32_bf16 v[22:25], v[180:183], v[232:235], v[22:25]
	v_mfma_f32_16x16x32_bf16 v[18:21], v[188:191], v[232:235], v[18:21]
	v_mfma_f32_16x16x32_bf16 v[6:9], v[180:183], v[240:243], v[6:9]
	v_mfma_f32_16x16x32_bf16 v[2:5], v[188:191], v[240:243], v[2:5]
	s_barrier
	s_setprio 0
	v_add_u32_e32 v133, 0x18000, v178
	ds_read_b128 v[134:137], v133
	ds_read_b128 v[138:141], v133 offset:1024
	ds_read_b128 v[142:145], v133 offset:2048
	ds_read_b128 v[154:157], v133 offset:3072
	v_add_u32_e32 v133, 0x1c000, v178
	ds_read_b128 v[170:173], v133
	ds_read_b128 v[180:183], v133 offset:1024
	ds_read_b128 v[184:187], v133 offset:2048
	ds_read_b128 v[188:191], v133 offset:3072
	s_add_i32 s27, s27, 0x80000
	s_mov_b32 m0, s25
	ds_read_b128 v[192:195], v179 offset:32768
	ds_read_b128 v[196:199], v179 offset:33792
	ds_read_b128 v[200:203], v179 offset:34816
	ds_read_b128 v[204:207], v179 offset:35840
	ds_read_b128 v[228:231], v179 offset:36864
	ds_read_b128 v[232:235], v179 offset:37888
	ds_read_b128 v[236:239], v179 offset:38912
	ds_read_b128 v[240:243], v179 offset:39936
	buffer_load_dwordx4 v174, s[44:47], s27 offen lds
	s_mov_b32 m0, s30
	s_nop 0
	buffer_load_dwordx4 v176, s[44:47], s27 offen lds
	s_waitcnt vmcnt(8)
	s_waitcnt lgkmcnt(0)
	s_setprio 1
	s_barrier
	v_mfma_f32_16x16x32_bf16 v[126:129], v[134:137], v[192:195], v[126:129]
	v_mfma_f32_16x16x32_bf16 v[122:125], v[142:145], v[192:195], v[122:125]
	v_mfma_f32_16x16x32_bf16 v[110:113], v[134:137], v[200:203], v[110:113]
	v_mfma_f32_16x16x32_bf16 v[106:109], v[142:145], v[200:203], v[106:109]
	v_mfma_f32_16x16x32_bf16 v[94:97], v[134:137], v[228:231], v[94:97]
	v_mfma_f32_16x16x32_bf16 v[90:93], v[142:145], v[228:231], v[90:93]
	v_mfma_f32_16x16x32_bf16 v[78:81], v[134:137], v[236:239], v[78:81]
	v_mfma_f32_16x16x32_bf16 v[74:77], v[142:145], v[236:239], v[74:77]
	v_mfma_f32_16x16x32_bf16 v[126:129], v[138:141], v[196:199], v[126:129]
	v_mfma_f32_16x16x32_bf16 v[122:125], v[154:157], v[196:199], v[122:125]
	v_mfma_f32_16x16x32_bf16 v[110:113], v[138:141], v[204:207], v[110:113]
	v_mfma_f32_16x16x32_bf16 v[106:109], v[154:157], v[204:207], v[106:109]
	v_mfma_f32_16x16x32_bf16 v[94:97], v[138:141], v[232:235], v[94:97]
	v_mfma_f32_16x16x32_bf16 v[90:93], v[154:157], v[232:235], v[90:93]
	v_mfma_f32_16x16x32_bf16 v[78:81], v[138:141], v[240:243], v[78:81]
	v_mfma_f32_16x16x32_bf16 v[74:77], v[154:157], v[240:243], v[74:77]
	v_mfma_f32_16x16x32_bf16 v[118:121], v[170:173], v[192:195], v[118:121]
	v_mfma_f32_16x16x32_bf16 v[114:117], v[184:187], v[192:195], v[114:117]
	v_mfma_f32_16x16x32_bf16 v[102:105], v[170:173], v[200:203], v[102:105]
	v_mfma_f32_16x16x32_bf16 v[98:101], v[184:187], v[200:203], v[98:101]
	v_mfma_f32_16x16x32_bf16 v[86:89], v[170:173], v[228:231], v[86:89]
	v_mfma_f32_16x16x32_bf16 v[82:85], v[184:187], v[228:231], v[82:85]
	v_mfma_f32_16x16x32_bf16 v[70:73], v[170:173], v[236:239], v[70:73]
	v_mfma_f32_16x16x32_bf16 v[66:69], v[184:187], v[236:239], v[66:69]
	v_mfma_f32_16x16x32_bf16 v[118:121], v[180:183], v[196:199], v[118:121]
	v_mfma_f32_16x16x32_bf16 v[114:117], v[188:191], v[196:199], v[114:117]
	v_mfma_f32_16x16x32_bf16 v[102:105], v[180:183], v[204:207], v[102:105]
	v_mfma_f32_16x16x32_bf16 v[98:101], v[188:191], v[204:207], v[98:101]
	v_mfma_f32_16x16x32_bf16 v[86:89], v[180:183], v[232:235], v[86:89]
	v_mfma_f32_16x16x32_bf16 v[82:85], v[188:191], v[232:235], v[82:85]
	v_mfma_f32_16x16x32_bf16 v[70:73], v[180:183], v[240:243], v[70:73]
	v_mfma_f32_16x16x32_bf16 v[66:69], v[188:191], v[240:243], v[66:69]
	s_barrier
	s_setprio 0
	s_mov_b32 m0, s36
	s_or_b32 s27, s26, 0x80
	ds_read_b128 v[192:195], v179 offset:49152
	ds_read_b128 v[196:199], v179 offset:50176
	ds_read_b128 v[200:203], v179 offset:51200
	ds_read_b128 v[204:207], v179 offset:52224
	ds_read_b128 v[228:231], v179 offset:53248
	ds_read_b128 v[232:235], v179 offset:54272
	ds_read_b128 v[236:239], v179 offset:55296
	ds_read_b128 v[240:243], v179 offset:56320
	buffer_load_dwordx4 v175, s[60:63], s27 offen lds
	s_mov_b32 m0, s37
	s_add_i32 s26, s26, 0x80080
	buffer_load_dwordx4 v177, s[60:63], s27 offen lds
	s_mov_b32 m0, s48
	s_nop 0
	buffer_load_dwordx4 v175, s[60:63], s26 offen lds
	s_mov_b32 m0, s49
	s_nop 0
	buffer_load_dwordx4 v177, s[60:63], s26 offen lds
	s_mov_b32 m0, s40
	s_nop 0
	buffer_load_dwordx4 v174, s[44:47], s23 offen lds
	s_mov_b32 m0, s41
	s_nop 0
	buffer_load_dwordx4 v176, s[44:47], s23 offen lds
	s_waitcnt vmcnt(8)
	s_waitcnt lgkmcnt(0)
	s_setprio 1
	s_barrier
	v_mfma_f32_16x16x32_bf16 v[62:65], v[134:137], v[192:195], v[62:65]
	v_mfma_f32_16x16x32_bf16 v[58:61], v[142:145], v[192:195], v[58:61]
	v_mfma_f32_16x16x32_bf16 v[46:49], v[134:137], v[200:203], v[46:49]
	v_mfma_f32_16x16x32_bf16 v[42:45], v[142:145], v[200:203], v[42:45]
	v_mfma_f32_16x16x32_bf16 v[30:33], v[134:137], v[228:231], v[30:33]
	v_mfma_f32_16x16x32_bf16 v[26:29], v[142:145], v[228:231], v[26:29]
	v_mfma_f32_16x16x32_bf16 v[14:17], v[134:137], v[236:239], v[14:17]
	v_mfma_f32_16x16x32_bf16 v[10:13], v[142:145], v[236:239], v[10:13]
	v_mfma_f32_16x16x32_bf16 v[62:65], v[138:141], v[196:199], v[62:65]
	v_mfma_f32_16x16x32_bf16 v[58:61], v[154:157], v[196:199], v[58:61]
	v_mfma_f32_16x16x32_bf16 v[46:49], v[138:141], v[204:207], v[46:49]
	v_mfma_f32_16x16x32_bf16 v[42:45], v[154:157], v[204:207], v[42:45]
	v_mfma_f32_16x16x32_bf16 v[30:33], v[138:141], v[232:235], v[30:33]
	v_mfma_f32_16x16x32_bf16 v[26:29], v[154:157], v[232:235], v[26:29]
	v_mfma_f32_16x16x32_bf16 v[14:17], v[138:141], v[240:243], v[14:17]
	v_mfma_f32_16x16x32_bf16 v[10:13], v[154:157], v[240:243], v[10:13]
	v_mfma_f32_16x16x32_bf16 v[54:57], v[170:173], v[192:195], v[54:57]
	v_mfma_f32_16x16x32_bf16 v[50:53], v[184:187], v[192:195], v[50:53]
	v_mfma_f32_16x16x32_bf16 v[38:41], v[170:173], v[200:203], v[38:41]
	v_mfma_f32_16x16x32_bf16 v[34:37], v[184:187], v[200:203], v[34:37]
	v_mfma_f32_16x16x32_bf16 v[22:25], v[170:173], v[228:231], v[22:25]
	v_mfma_f32_16x16x32_bf16 v[18:21], v[184:187], v[228:231], v[18:21]
	v_mfma_f32_16x16x32_bf16 v[6:9], v[170:173], v[236:239], v[6:9]
	v_mfma_f32_16x16x32_bf16 v[2:5], v[184:187], v[236:239], v[2:5]
	v_mfma_f32_16x16x32_bf16 v[54:57], v[180:183], v[196:199], v[54:57]
	v_mfma_f32_16x16x32_bf16 v[50:53], v[188:191], v[196:199], v[50:53]
	v_mfma_f32_16x16x32_bf16 v[38:41], v[180:183], v[204:207], v[38:41]
	v_mfma_f32_16x16x32_bf16 v[34:37], v[188:191], v[204:207], v[34:37]
	v_mfma_f32_16x16x32_bf16 v[22:25], v[180:183], v[232:235], v[22:25]
	v_mfma_f32_16x16x32_bf16 v[18:21], v[188:191], v[232:235], v[18:21]
	v_mfma_f32_16x16x32_bf16 v[6:9], v[180:183], v[240:243], v[6:9]
	v_mfma_f32_16x16x32_bf16 v[2:5], v[188:191], v[240:243], v[2:5]
	s_barrier
	s_setprio 0
	s_add_i32 s22, s22, 2
	s_addk_i32 s13, 0x100
	s_addk_i32 s21, 0x100
	s_cmp_gt_u32 s22, 29

.LBB0_1192:
	s_lshl_b32 s12, s70, 22
	s_and_b64 s[8:9], s[26:27], exec
	s_cselect_b32 s8, s12, s30
	s_lshl_b32 s22, s71, 22
	s_and_b64 s[66:67], s[26:27], exec
	s_cselect_b32 s9, s22, s31
	s_add_i32 s30, s30, 0x200080
	s_addk_i32 s31, 0x100
	s_mov_b32 s72, -2
	v_add_u32_e32 v141, 0x10000, v139
	ds_read_b128 v[142:145], v141
	ds_read_b128 v[154:157], v141 offset:1024
	ds_read_b128 v[170:173], v141 offset:2048
	ds_read_b128 v[174:177], v141 offset:3072
	v_add_u32_e32 v141, 0x14000, v139
	ds_read_b128 v[178:181], v141
	ds_read_b128 v[182:185], v141 offset:1024
	ds_read_b128 v[186:189], v141 offset:2048
	ds_read_b128 v[190:193], v141 offset:3072
	s_add_i32 s52, s30, 0xffe00080
	s_cmpk_eq_i32 s72, 0x7c
	s_cselect_b32 s52, s8, s52
	s_cselect_b32 s82, s9, s31
	s_or_b32 s73, s52, 0x80
	s_mov_b32 m0, s69
	ds_read_b128 v[194:197], v140
	ds_read_b128 v[198:201], v140 offset:1024
	ds_read_b128 v[202:205], v140 offset:2048
	ds_read_b128 v[228:231], v140 offset:3072
	ds_read_b128 v[232:235], v140 offset:4096
	ds_read_b128 v[236:239], v140 offset:5120
	ds_read_b128 v[240:243], v140 offset:6144
	ds_read_b128 v[244:247], v140 offset:7168
	buffer_load_dwordx4 v131, s[60:63], s30 offen lds
	s_mov_b32 m0, s46
	s_nop 0
	buffer_load_dwordx4 v135, s[60:63], s30 offen lds
	s_waitcnt vmcnt(8)
	s_waitcnt lgkmcnt(0)
	s_setprio 1
	s_barrier
	v_mfma_f32_16x16x32_bf16 v[126:129], v[142:145], v[194:197], 0
	v_mfma_f32_16x16x32_bf16 v[122:125], v[170:173], v[194:197], 0
	v_mfma_f32_16x16x32_bf16 v[118:121], v[142:145], v[202:205], 0
	v_mfma_f32_16x16x32_bf16 v[114:117], v[170:173], v[202:205], 0
	v_mfma_f32_16x16x32_bf16 v[110:113], v[142:145], v[232:235], 0
	v_mfma_f32_16x16x32_bf16 v[106:109], v[170:173], v[232:235], 0
	v_mfma_f32_16x16x32_bf16 v[102:105], v[142:145], v[240:243], 0
	v_mfma_f32_16x16x32_bf16 v[98:101], v[170:173], v[240:243], 0
	v_mfma_f32_16x16x32_bf16 v[126:129], v[154:157], v[198:201], v[126:129]
	v_mfma_f32_16x16x32_bf16 v[122:125], v[174:177], v[198:201], v[122:125]
	v_mfma_f32_16x16x32_bf16 v[118:121], v[154:157], v[228:231], v[118:121]
	v_mfma_f32_16x16x32_bf16 v[114:117], v[174:177], v[228:231], v[114:117]
	v_mfma_f32_16x16x32_bf16 v[110:113], v[154:157], v[236:239], v[110:113]
	v_mfma_f32_16x16x32_bf16 v[106:109], v[174:177], v[236:239], v[106:109]
	v_mfma_f32_16x16x32_bf16 v[102:105], v[154:157], v[244:247], v[102:105]
	v_mfma_f32_16x16x32_bf16 v[98:101], v[174:177], v[244:247], v[98:101]
	v_mfma_f32_16x16x32_bf16 v[62:65], v[178:181], v[194:197], 0
	v_mfma_f32_16x16x32_bf16 v[58:61], v[186:189], v[194:197], 0
	v_mfma_f32_16x16x32_bf16 v[54:57], v[178:181], v[202:205], 0
	v_mfma_f32_16x16x32_bf16 v[50:53], v[186:189], v[202:205], 0
	v_mfma_f32_16x16x32_bf16 v[46:49], v[178:181], v[232:235], 0
	v_mfma_f32_16x16x32_bf16 v[42:45], v[186:189], v[232:235], 0
	v_mfma_f32_16x16x32_bf16 v[38:41], v[178:181], v[240:243], 0
	v_mfma_f32_16x16x32_bf16 v[34:37], v[186:189], v[240:243], 0
	v_mfma_f32_16x16x32_bf16 v[62:65], v[182:185], v[198:201], v[62:65]
	v_mfma_f32_16x16x32_bf16 v[58:61], v[190:193], v[198:201], v[58:61]
	v_mfma_f32_16x16x32_bf16 v[54:57], v[182:185], v[228:231], v[54:57]
	v_mfma_f32_16x16x32_bf16 v[50:53], v[190:193], v[228:231], v[50:53]
	v_mfma_f32_16x16x32_bf16 v[46:49], v[182:185], v[236:239], v[46:49]
	v_mfma_f32_16x16x32_bf16 v[42:45], v[190:193], v[236:239], v[42:45]
	v_mfma_f32_16x16x32_bf16 v[38:41], v[182:185], v[244:247], v[38:41]
	v_mfma_f32_16x16x32_bf16 v[34:37], v[190:193], v[244:247], v[34:37]
	s_barrier
	s_setprio 0
	s_mov_b32 m0, s15
	s_mov_b32 s66, s62
	s_mov_b32 s67, s63
	ds_read_b128 v[194:197], v140 offset:16384
	ds_read_b128 v[198:201], v140 offset:17408
	ds_read_b128 v[202:205], v140 offset:18432
	ds_read_b128 v[228:231], v140 offset:19456
	ds_read_b128 v[232:235], v140 offset:20480
	ds_read_b128 v[236:239], v140 offset:21504
	ds_read_b128 v[240:243], v140 offset:22528
	ds_read_b128 v[244:247], v140 offset:23552
	buffer_load_dwordx4 v134, s[64:67], s82 offen lds
	s_mov_b32 m0, s16
	s_add_i32 s53, s82, 0x200000
	buffer_load_dwordx4 v136, s[64:67], s82 offen lds
	s_mov_b32 m0, s21
	s_nop 0
	buffer_load_dwordx4 v134, s[64:67], s53 offen lds
	s_mov_b32 m0, s23
	s_nop 0
	buffer_load_dwordx4 v136, s[64:67], s53 offen lds
	s_mov_b32 m0, s2
	s_nop 0
	buffer_load_dwordx4 v131, s[60:63], s52 offen lds
	s_mov_b32 m0, s24
	s_nop 0
	buffer_load_dwordx4 v135, s[60:63], s52 offen lds
	s_waitcnt vmcnt(8)
	s_waitcnt lgkmcnt(0)
	s_setprio 1
	s_barrier
	v_mfma_f32_16x16x32_bf16 v[94:97], v[142:145], v[194:197], 0
	v_mfma_f32_16x16x32_bf16 v[90:93], v[170:173], v[194:197], 0
	v_mfma_f32_16x16x32_bf16 v[86:89], v[142:145], v[202:205], 0
	v_mfma_f32_16x16x32_bf16 v[82:85], v[170:173], v[202:205], 0
	v_mfma_f32_16x16x32_bf16 v[78:81], v[142:145], v[232:235], 0
	v_mfma_f32_16x16x32_bf16 v[74:77], v[170:173], v[232:235], 0
	v_mfma_f32_16x16x32_bf16 v[70:73], v[142:145], v[240:243], 0
	v_mfma_f32_16x16x32_bf16 v[66:69], v[170:173], v[240:243], 0
	v_mfma_f32_16x16x32_bf16 v[94:97], v[154:157], v[198:201], v[94:97]
	v_mfma_f32_16x16x32_bf16 v[90:93], v[174:177], v[198:201], v[90:93]
	v_mfma_f32_16x16x32_bf16 v[86:89], v[154:157], v[228:231], v[86:89]
	v_mfma_f32_16x16x32_bf16 v[82:85], v[174:177], v[228:231], v[82:85]
	v_mfma_f32_16x16x32_bf16 v[78:81], v[154:157], v[236:239], v[78:81]
	v_mfma_f32_16x16x32_bf16 v[74:77], v[174:177], v[236:239], v[74:77]
	v_mfma_f32_16x16x32_bf16 v[70:73], v[154:157], v[244:247], v[70:73]
	v_mfma_f32_16x16x32_bf16 v[66:69], v[174:177], v[244:247], v[66:69]
	v_mfma_f32_16x16x32_bf16 v[30:33], v[178:181], v[194:197], 0
	v_mfma_f32_16x16x32_bf16 v[26:29], v[186:189], v[194:197], 0
	v_mfma_f32_16x16x32_bf16 v[22:25], v[178:181], v[202:205], 0
	v_mfma_f32_16x16x32_bf16 v[18:21], v[186:189], v[202:205], 0
	v_mfma_f32_16x16x32_bf16 v[14:17], v[178:181], v[232:235], 0
	v_mfma_f32_16x16x32_bf16 v[10:13], v[186:189], v[232:235], 0
	v_mfma_f32_16x16x32_bf16 v[6:9], v[178:181], v[240:243], 0
	v_mfma_f32_16x16x32_bf16 v[2:5], v[186:189], v[240:243], 0
	v_mfma_f32_16x16x32_bf16 v[30:33], v[182:185], v[198:201], v[30:33]
	v_mfma_f32_16x16x32_bf16 v[26:29], v[190:193], v[198:201], v[26:29]
	v_mfma_f32_16x16x32_bf16 v[22:25], v[182:185], v[228:231], v[22:25]
	v_mfma_f32_16x16x32_bf16 v[18:21], v[190:193], v[228:231], v[18:21]
	v_mfma_f32_16x16x32_bf16 v[14:17], v[182:185], v[236:239], v[14:17]
	v_mfma_f32_16x16x32_bf16 v[10:13], v[190:193], v[236:239], v[10:13]
	v_mfma_f32_16x16x32_bf16 v[6:9], v[182:185], v[244:247], v[6:9]
	v_mfma_f32_16x16x32_bf16 v[2:5], v[190:193], v[244:247], v[2:5]
	s_barrier
	s_setprio 0
	v_add_u32_e32 v141, 0x18000, v139
	ds_read_b128 v[142:145], v141
	ds_read_b128 v[154:157], v141 offset:1024
	ds_read_b128 v[170:173], v141 offset:2048
	ds_read_b128 v[174:177], v141 offset:3072
	v_add_u32_e32 v141, 0x1c000, v139
	ds_read_b128 v[178:181], v141
	ds_read_b128 v[182:185], v141 offset:1024
	ds_read_b128 v[186:189], v141 offset:2048
	ds_read_b128 v[190:193], v141 offset:3072
	s_add_i32 s52, s52, 0x200000
	s_mov_b32 m0, s25
	ds_read_b128 v[194:197], v140 offset:32768
	ds_read_b128 v[198:201], v140 offset:33792
	ds_read_b128 v[202:205], v140 offset:34816
	ds_read_b128 v[228:231], v140 offset:35840
	ds_read_b128 v[232:235], v140 offset:36864
	ds_read_b128 v[236:239], v140 offset:37888
	ds_read_b128 v[240:243], v140 offset:38912
	ds_read_b128 v[244:247], v140 offset:39936
	buffer_load_dwordx4 v131, s[60:63], s52 offen lds
	s_mov_b32 m0, s33
	s_nop 0
	buffer_load_dwordx4 v135, s[60:63], s52 offen lds
	s_waitcnt vmcnt(8)
	s_waitcnt lgkmcnt(0)
	s_setprio 1
	s_barrier
	v_mfma_f32_16x16x32_bf16 v[126:129], v[142:145], v[194:197], v[126:129]
	v_mfma_f32_16x16x32_bf16 v[122:125], v[170:173], v[194:197], v[122:125]
	v_mfma_f32_16x16x32_bf16 v[118:121], v[142:145], v[202:205], v[118:121]
	v_mfma_f32_16x16x32_bf16 v[114:117], v[170:173], v[202:205], v[114:117]
	v_mfma_f32_16x16x32_bf16 v[110:113], v[142:145], v[232:235], v[110:113]
	v_mfma_f32_16x16x32_bf16 v[106:109], v[170:173], v[232:235], v[106:109]
	v_mfma_f32_16x16x32_bf16 v[102:105], v[142:145], v[240:243], v[102:105]
	v_mfma_f32_16x16x32_bf16 v[98:101], v[170:173], v[240:243], v[98:101]
	v_mfma_f32_16x16x32_bf16 v[126:129], v[154:157], v[198:201], v[126:129]
	v_mfma_f32_16x16x32_bf16 v[122:125], v[174:177], v[198:201], v[122:125]
	v_mfma_f32_16x16x32_bf16 v[118:121], v[154:157], v[228:231], v[118:121]
	v_mfma_f32_16x16x32_bf16 v[114:117], v[174:177], v[228:231], v[114:117]
	v_mfma_f32_16x16x32_bf16 v[110:113], v[154:157], v[236:239], v[110:113]
	v_mfma_f32_16x16x32_bf16 v[106:109], v[174:177], v[236:239], v[106:109]
	v_mfma_f32_16x16x32_bf16 v[102:105], v[154:157], v[244:247], v[102:105]
	v_mfma_f32_16x16x32_bf16 v[98:101], v[174:177], v[244:247], v[98:101]
	v_mfma_f32_16x16x32_bf16 v[62:65], v[178:181], v[194:197], v[62:65]
	v_mfma_f32_16x16x32_bf16 v[58:61], v[186:189], v[194:197], v[58:61]
	v_mfma_f32_16x16x32_bf16 v[54:57], v[178:181], v[202:205], v[54:57]
	v_mfma_f32_16x16x32_bf16 v[50:53], v[186:189], v[202:205], v[50:53]
	v_mfma_f32_16x16x32_bf16 v[46:49], v[178:181], v[232:235], v[46:49]
	v_mfma_f32_16x16x32_bf16 v[42:45], v[186:189], v[232:235], v[42:45]
	v_mfma_f32_16x16x32_bf16 v[38:41], v[178:181], v[240:243], v[38:41]
	v_mfma_f32_16x16x32_bf16 v[34:37], v[186:189], v[240:243], v[34:37]
	v_mfma_f32_16x16x32_bf16 v[62:65], v[182:185], v[198:201], v[62:65]
	v_mfma_f32_16x16x32_bf16 v[58:61], v[190:193], v[198:201], v[58:61]
	v_mfma_f32_16x16x32_bf16 v[54:57], v[182:185], v[228:231], v[54:57]
	v_mfma_f32_16x16x32_bf16 v[50:53], v[190:193], v[228:231], v[50:53]
	v_mfma_f32_16x16x32_bf16 v[46:49], v[182:185], v[236:239], v[46:49]
	v_mfma_f32_16x16x32_bf16 v[42:45], v[190:193], v[236:239], v[42:45]
	v_mfma_f32_16x16x32_bf16 v[38:41], v[182:185], v[244:247], v[38:41]
	v_mfma_f32_16x16x32_bf16 v[34:37], v[190:193], v[244:247], v[34:37]
	s_barrier
	s_setprio 0
	s_mov_b32 m0, s34
	s_or_b32 s52, s82, 0x80
	ds_read_b128 v[194:197], v140 offset:49152
	ds_read_b128 v[198:201], v140 offset:50176
	ds_read_b128 v[202:205], v140 offset:51200
	ds_read_b128 v[228:231], v140 offset:52224
	ds_read_b128 v[232:235], v140 offset:53248
	ds_read_b128 v[236:239], v140 offset:54272
	ds_read_b128 v[240:243], v140 offset:55296
	ds_read_b128 v[244:247], v140 offset:56320
	buffer_load_dwordx4 v134, s[64:67], s52 offen lds
	s_mov_b32 m0, s35
	s_add_i32 s82, s82, 0x200080
	buffer_load_dwordx4 v136, s[64:67], s52 offen lds
	s_mov_b32 m0, s37
	s_nop 0
	buffer_load_dwordx4 v134, s[64:67], s82 offen lds
	s_mov_b32 m0, s44
	s_nop 0
	buffer_load_dwordx4 v136, s[64:67], s82 offen lds
	s_mov_b32 m0, s14
	s_nop 0
	buffer_load_dwordx4 v131, s[60:63], s73 offen lds
	s_mov_b32 m0, s36
	s_nop 0
	buffer_load_dwordx4 v135, s[60:63], s73 offen lds
	s_waitcnt vmcnt(8)
	s_waitcnt lgkmcnt(0)
	s_setprio 1
	s_barrier
	v_mfma_f32_16x16x32_bf16 v[94:97], v[142:145], v[194:197], v[94:97]
	v_mfma_f32_16x16x32_bf16 v[90:93], v[170:173], v[194:197], v[90:93]
	v_mfma_f32_16x16x32_bf16 v[86:89], v[142:145], v[202:205], v[86:89]
	v_mfma_f32_16x16x32_bf16 v[82:85], v[170:173], v[202:205], v[82:85]
	v_mfma_f32_16x16x32_bf16 v[78:81], v[142:145], v[232:235], v[78:81]
	v_mfma_f32_16x16x32_bf16 v[74:77], v[170:173], v[232:235], v[74:77]
	v_mfma_f32_16x16x32_bf16 v[70:73], v[142:145], v[240:243], v[70:73]
	v_mfma_f32_16x16x32_bf16 v[66:69], v[170:173], v[240:243], v[66:69]
	v_mfma_f32_16x16x32_bf16 v[94:97], v[154:157], v[198:201], v[94:97]
	v_mfma_f32_16x16x32_bf16 v[90:93], v[174:177], v[198:201], v[90:93]
	v_mfma_f32_16x16x32_bf16 v[86:89], v[154:157], v[228:231], v[86:89]
	v_mfma_f32_16x16x32_bf16 v[82:85], v[174:177], v[228:231], v[82:85]
	v_mfma_f32_16x16x32_bf16 v[78:81], v[154:157], v[236:239], v[78:81]
	v_mfma_f32_16x16x32_bf16 v[74:77], v[174:177], v[236:239], v[74:77]
	v_mfma_f32_16x16x32_bf16 v[70:73], v[154:157], v[244:247], v[70:73]
	v_mfma_f32_16x16x32_bf16 v[66:69], v[174:177], v[244:247], v[66:69]
	v_mfma_f32_16x16x32_bf16 v[30:33], v[178:181], v[194:197], v[30:33]
	v_mfma_f32_16x16x32_bf16 v[26:29], v[186:189], v[194:197], v[26:29]
	v_mfma_f32_16x16x32_bf16 v[22:25], v[178:181], v[202:205], v[22:25]
	v_mfma_f32_16x16x32_bf16 v[18:21], v[186:189], v[202:205], v[18:21]
	v_mfma_f32_16x16x32_bf16 v[14:17], v[178:181], v[232:235], v[14:17]
	v_mfma_f32_16x16x32_bf16 v[10:13], v[186:189], v[232:235], v[10:13]
	v_mfma_f32_16x16x32_bf16 v[6:9], v[178:181], v[240:243], v[6:9]
	v_mfma_f32_16x16x32_bf16 v[2:5], v[186:189], v[240:243], v[2:5]
	v_mfma_f32_16x16x32_bf16 v[30:33], v[182:185], v[198:201], v[30:33]
	v_mfma_f32_16x16x32_bf16 v[26:29], v[190:193], v[198:201], v[26:29]
	v_mfma_f32_16x16x32_bf16 v[22:25], v[182:185], v[228:231], v[22:25]
	v_mfma_f32_16x16x32_bf16 v[18:21], v[190:193], v[228:231], v[18:21]
	v_mfma_f32_16x16x32_bf16 v[14:17], v[182:185], v[236:239], v[14:17]
	v_mfma_f32_16x16x32_bf16 v[10:13], v[190:193], v[236:239], v[10:13]
	v_mfma_f32_16x16x32_bf16 v[6:9], v[182:185], v[244:247], v[6:9]
	v_mfma_f32_16x16x32_bf16 v[2:5], v[190:193], v[244:247], v[2:5]
	s_barrier
	s_setprio 0
	s_add_i32 s72, s72, 2
	s_addk_i32 s30, 0x100
	s_addk_i32 s31, 0x100
	s_cmpk_gt_u32 s72, 0x7d

.LBB0_1222:
	s_lshl_b32 s14, s82, 22
	s_and_b64 s[8:9], s[44:45], exec
	s_cselect_b32 s8, s14, s19
	s_lshl_b32 s46, s84, 22
	s_and_b64 s[26:27], s[44:45], exec
	s_cselect_b32 s9, s46, s22
	s_add_i32 s19, s19, 0x200080
	s_addk_i32 s22, 0x100
	s_mov_b32 s26, -2
	v_add_u32_e32 v141, 0x10000, v139
	ds_read_b128 v[142:145], v141
	ds_read_b128 v[154:157], v141 offset:1024
	ds_read_b128 v[170:173], v141 offset:2048
	ds_read_b128 v[174:177], v141 offset:3072
	v_add_u32_e32 v141, 0x14000, v139
	ds_read_b128 v[178:181], v141
	ds_read_b128 v[182:185], v141 offset:1024
	ds_read_b128 v[186:189], v141 offset:2048
	ds_read_b128 v[190:193], v141 offset:3072
	s_add_i32 s27, s19, 0xffe00080
	s_cmpk_eq_i32 s26, 0x7c
	s_cselect_b32 s52, s8, s27
	s_cselect_b32 s47, s9, s22
	s_or_b32 s27, s52, 0x80
	s_mov_b32 m0, s71
	ds_read_b128 v[194:197], v140
	ds_read_b128 v[198:201], v140 offset:1024
	ds_read_b128 v[202:205], v140 offset:2048
	ds_read_b128 v[228:231], v140 offset:3072
	ds_read_b128 v[232:235], v140 offset:4096
	ds_read_b128 v[236:239], v140 offset:5120
	ds_read_b128 v[240:243], v140 offset:6144
	ds_read_b128 v[244:247], v140 offset:7168
	buffer_load_dwordx4 v131, s[60:63], s19 offen lds
	s_mov_b32 m0, s72
	s_nop 0
	buffer_load_dwordx4 v135, s[60:63], s19 offen lds
	s_waitcnt vmcnt(8)
	s_waitcnt lgkmcnt(0)
	s_setprio 1
	s_barrier
	v_mfma_f32_16x16x32_bf16 v[126:129], v[142:145], v[194:197], 0
	v_mfma_f32_16x16x32_bf16 v[122:125], v[170:173], v[194:197], 0
	v_mfma_f32_16x16x32_bf16 v[118:121], v[142:145], v[202:205], 0
	v_mfma_f32_16x16x32_bf16 v[114:117], v[170:173], v[202:205], 0
	v_mfma_f32_16x16x32_bf16 v[110:113], v[142:145], v[232:235], 0
	v_mfma_f32_16x16x32_bf16 v[106:109], v[170:173], v[232:235], 0
	v_mfma_f32_16x16x32_bf16 v[102:105], v[142:145], v[240:243], 0
	v_mfma_f32_16x16x32_bf16 v[98:101], v[170:173], v[240:243], 0
	v_mfma_f32_16x16x32_bf16 v[126:129], v[154:157], v[198:201], v[126:129]
	v_mfma_f32_16x16x32_bf16 v[122:125], v[174:177], v[198:201], v[122:125]
	v_mfma_f32_16x16x32_bf16 v[118:121], v[154:157], v[228:231], v[118:121]
	v_mfma_f32_16x16x32_bf16 v[114:117], v[174:177], v[228:231], v[114:117]
	v_mfma_f32_16x16x32_bf16 v[110:113], v[154:157], v[236:239], v[110:113]
	v_mfma_f32_16x16x32_bf16 v[106:109], v[174:177], v[236:239], v[106:109]
	v_mfma_f32_16x16x32_bf16 v[102:105], v[154:157], v[244:247], v[102:105]
	v_mfma_f32_16x16x32_bf16 v[98:101], v[174:177], v[244:247], v[98:101]
	v_mfma_f32_16x16x32_bf16 v[62:65], v[178:181], v[194:197], 0
	v_mfma_f32_16x16x32_bf16 v[58:61], v[186:189], v[194:197], 0
	v_mfma_f32_16x16x32_bf16 v[54:57], v[178:181], v[202:205], 0
	v_mfma_f32_16x16x32_bf16 v[50:53], v[186:189], v[202:205], 0
	v_mfma_f32_16x16x32_bf16 v[46:49], v[178:181], v[232:235], 0
	v_mfma_f32_16x16x32_bf16 v[42:45], v[186:189], v[232:235], 0
	v_mfma_f32_16x16x32_bf16 v[38:41], v[178:181], v[240:243], 0
	v_mfma_f32_16x16x32_bf16 v[34:37], v[186:189], v[240:243], 0
	v_mfma_f32_16x16x32_bf16 v[62:65], v[182:185], v[198:201], v[62:65]
	v_mfma_f32_16x16x32_bf16 v[58:61], v[190:193], v[198:201], v[58:61]
	v_mfma_f32_16x16x32_bf16 v[54:57], v[182:185], v[228:231], v[54:57]
	v_mfma_f32_16x16x32_bf16 v[50:53], v[190:193], v[228:231], v[50:53]
	v_mfma_f32_16x16x32_bf16 v[46:49], v[182:185], v[236:239], v[46:49]
	v_mfma_f32_16x16x32_bf16 v[42:45], v[190:193], v[236:239], v[42:45]
	v_mfma_f32_16x16x32_bf16 v[38:41], v[182:185], v[244:247], v[38:41]
	v_mfma_f32_16x16x32_bf16 v[34:37], v[190:193], v[244:247], v[34:37]
	s_barrier
	s_setprio 0
	s_mov_b32 m0, s2
	s_mov_b32 s66, s62
	s_mov_b32 s67, s63
	ds_read_b128 v[194:197], v140 offset:16384
	ds_read_b128 v[198:201], v140 offset:17408
	ds_read_b128 v[202:205], v140 offset:18432
	ds_read_b128 v[228:231], v140 offset:19456
	ds_read_b128 v[232:235], v140 offset:20480
	ds_read_b128 v[236:239], v140 offset:21504
	ds_read_b128 v[240:243], v140 offset:22528
	ds_read_b128 v[244:247], v140 offset:23552
	buffer_load_dwordx4 v134, s[64:67], s47 offen lds
	s_mov_b32 m0, s21
	s_add_i32 s53, s47, 0x200000
	buffer_load_dwordx4 v136, s[64:67], s47 offen lds
	s_mov_b32 m0, s23
	s_nop 0
	buffer_load_dwordx4 v134, s[64:67], s53 offen lds
	s_mov_b32 m0, s24
	s_nop 0
	buffer_load_dwordx4 v136, s[64:67], s53 offen lds
	s_mov_b32 m0, s16
	s_nop 0
	buffer_load_dwordx4 v131, s[60:63], s52 offen lds
	s_mov_b32 m0, s25
	s_nop 0
	buffer_load_dwordx4 v135, s[60:63], s52 offen lds
	s_waitcnt vmcnt(8)
	s_waitcnt lgkmcnt(0)
	s_setprio 1
	s_barrier
	v_mfma_f32_16x16x32_bf16 v[94:97], v[142:145], v[194:197], 0
	v_mfma_f32_16x16x32_bf16 v[90:93], v[170:173], v[194:197], 0
	v_mfma_f32_16x16x32_bf16 v[86:89], v[142:145], v[202:205], 0
	v_mfma_f32_16x16x32_bf16 v[82:85], v[170:173], v[202:205], 0
	v_mfma_f32_16x16x32_bf16 v[78:81], v[142:145], v[232:235], 0
	v_mfma_f32_16x16x32_bf16 v[74:77], v[170:173], v[232:235], 0
	v_mfma_f32_16x16x32_bf16 v[70:73], v[142:145], v[240:243], 0
	v_mfma_f32_16x16x32_bf16 v[66:69], v[170:173], v[240:243], 0
	v_mfma_f32_16x16x32_bf16 v[94:97], v[154:157], v[198:201], v[94:97]
	v_mfma_f32_16x16x32_bf16 v[90:93], v[174:177], v[198:201], v[90:93]
	v_mfma_f32_16x16x32_bf16 v[86:89], v[154:157], v[228:231], v[86:89]
	v_mfma_f32_16x16x32_bf16 v[82:85], v[174:177], v[228:231], v[82:85]
	v_mfma_f32_16x16x32_bf16 v[78:81], v[154:157], v[236:239], v[78:81]
	v_mfma_f32_16x16x32_bf16 v[74:77], v[174:177], v[236:239], v[74:77]
	v_mfma_f32_16x16x32_bf16 v[70:73], v[154:157], v[244:247], v[70:73]
	v_mfma_f32_16x16x32_bf16 v[66:69], v[174:177], v[244:247], v[66:69]
	v_mfma_f32_16x16x32_bf16 v[30:33], v[178:181], v[194:197], 0
	v_mfma_f32_16x16x32_bf16 v[26:29], v[186:189], v[194:197], 0
	v_mfma_f32_16x16x32_bf16 v[22:25], v[178:181], v[202:205], 0
	v_mfma_f32_16x16x32_bf16 v[18:21], v[186:189], v[202:205], 0
	v_mfma_f32_16x16x32_bf16 v[14:17], v[178:181], v[232:235], 0
	v_mfma_f32_16x16x32_bf16 v[10:13], v[186:189], v[232:235], 0
	v_mfma_f32_16x16x32_bf16 v[6:9], v[178:181], v[240:243], 0
	v_mfma_f32_16x16x32_bf16 v[2:5], v[186:189], v[240:243], 0
	v_mfma_f32_16x16x32_bf16 v[30:33], v[182:185], v[198:201], v[30:33]
	v_mfma_f32_16x16x32_bf16 v[26:29], v[190:193], v[198:201], v[26:29]
	v_mfma_f32_16x16x32_bf16 v[22:25], v[182:185], v[228:231], v[22:25]
	v_mfma_f32_16x16x32_bf16 v[18:21], v[190:193], v[228:231], v[18:21]
	v_mfma_f32_16x16x32_bf16 v[14:17], v[182:185], v[236:239], v[14:17]
	v_mfma_f32_16x16x32_bf16 v[10:13], v[190:193], v[236:239], v[10:13]
	v_mfma_f32_16x16x32_bf16 v[6:9], v[182:185], v[244:247], v[6:9]
	v_mfma_f32_16x16x32_bf16 v[2:5], v[190:193], v[244:247], v[2:5]
	s_barrier
	s_setprio 0
	v_add_u32_e32 v141, 0x18000, v139
	ds_read_b128 v[142:145], v141
	ds_read_b128 v[154:157], v141 offset:1024
	ds_read_b128 v[170:173], v141 offset:2048
	ds_read_b128 v[174:177], v141 offset:3072
	v_add_u32_e32 v141, 0x1c000, v139
	ds_read_b128 v[178:181], v141
	ds_read_b128 v[182:185], v141 offset:1024
	ds_read_b128 v[186:189], v141 offset:2048
	ds_read_b128 v[190:193], v141 offset:3072
	s_add_i32 s52, s52, 0x200000
	s_mov_b32 m0, s30
	ds_read_b128 v[194:197], v140 offset:32768
	ds_read_b128 v[198:201], v140 offset:33792
	ds_read_b128 v[202:205], v140 offset:34816
	ds_read_b128 v[228:231], v140 offset:35840
	ds_read_b128 v[232:235], v140 offset:36864
	ds_read_b128 v[236:239], v140 offset:37888
	ds_read_b128 v[240:243], v140 offset:38912
	ds_read_b128 v[244:247], v140 offset:39936
	buffer_load_dwordx4 v131, s[60:63], s52 offen lds
	s_mov_b32 m0, s31
	s_nop 0
	buffer_load_dwordx4 v135, s[60:63], s52 offen lds
	s_waitcnt vmcnt(8)
	s_waitcnt lgkmcnt(0)
	s_setprio 1
	s_barrier
	v_mfma_f32_16x16x32_bf16 v[126:129], v[142:145], v[194:197], v[126:129]
	v_mfma_f32_16x16x32_bf16 v[122:125], v[170:173], v[194:197], v[122:125]
	v_mfma_f32_16x16x32_bf16 v[118:121], v[142:145], v[202:205], v[118:121]
	v_mfma_f32_16x16x32_bf16 v[114:117], v[170:173], v[202:205], v[114:117]
	v_mfma_f32_16x16x32_bf16 v[110:113], v[142:145], v[232:235], v[110:113]
	v_mfma_f32_16x16x32_bf16 v[106:109], v[170:173], v[232:235], v[106:109]
	v_mfma_f32_16x16x32_bf16 v[102:105], v[142:145], v[240:243], v[102:105]
	v_mfma_f32_16x16x32_bf16 v[98:101], v[170:173], v[240:243], v[98:101]
	v_mfma_f32_16x16x32_bf16 v[126:129], v[154:157], v[198:201], v[126:129]
	v_mfma_f32_16x16x32_bf16 v[122:125], v[174:177], v[198:201], v[122:125]
	v_mfma_f32_16x16x32_bf16 v[118:121], v[154:157], v[228:231], v[118:121]
	v_mfma_f32_16x16x32_bf16 v[114:117], v[174:177], v[228:231], v[114:117]
	v_mfma_f32_16x16x32_bf16 v[110:113], v[154:157], v[236:239], v[110:113]
	v_mfma_f32_16x16x32_bf16 v[106:109], v[174:177], v[236:239], v[106:109]
	v_mfma_f32_16x16x32_bf16 v[102:105], v[154:157], v[244:247], v[102:105]
	v_mfma_f32_16x16x32_bf16 v[98:101], v[174:177], v[244:247], v[98:101]
	v_mfma_f32_16x16x32_bf16 v[62:65], v[178:181], v[194:197], v[62:65]
	v_mfma_f32_16x16x32_bf16 v[58:61], v[186:189], v[194:197], v[58:61]
	v_mfma_f32_16x16x32_bf16 v[54:57], v[178:181], v[202:205], v[54:57]
	v_mfma_f32_16x16x32_bf16 v[50:53], v[186:189], v[202:205], v[50:53]
	v_mfma_f32_16x16x32_bf16 v[46:49], v[178:181], v[232:235], v[46:49]
	v_mfma_f32_16x16x32_bf16 v[42:45], v[186:189], v[232:235], v[42:45]
	v_mfma_f32_16x16x32_bf16 v[38:41], v[178:181], v[240:243], v[38:41]
	v_mfma_f32_16x16x32_bf16 v[34:37], v[186:189], v[240:243], v[34:37]
	v_mfma_f32_16x16x32_bf16 v[62:65], v[182:185], v[198:201], v[62:65]
	v_mfma_f32_16x16x32_bf16 v[58:61], v[190:193], v[198:201], v[58:61]
	v_mfma_f32_16x16x32_bf16 v[54:57], v[182:185], v[228:231], v[54:57]
	v_mfma_f32_16x16x32_bf16 v[50:53], v[190:193], v[228:231], v[50:53]
	v_mfma_f32_16x16x32_bf16 v[46:49], v[182:185], v[236:239], v[46:49]
	v_mfma_f32_16x16x32_bf16 v[42:45], v[190:193], v[236:239], v[42:45]
	v_mfma_f32_16x16x32_bf16 v[38:41], v[182:185], v[244:247], v[38:41]
	v_mfma_f32_16x16x32_bf16 v[34:37], v[190:193], v[244:247], v[34:37]
	s_barrier
	s_setprio 0
	s_mov_b32 m0, s33
	s_or_b32 s52, s47, 0x80
	ds_read_b128 v[194:197], v140 offset:49152
	ds_read_b128 v[198:201], v140 offset:50176
	ds_read_b128 v[202:205], v140 offset:51200
	ds_read_b128 v[228:231], v140 offset:52224
	ds_read_b128 v[232:235], v140 offset:53248
	ds_read_b128 v[236:239], v140 offset:54272
	ds_read_b128 v[240:243], v140 offset:55296
	ds_read_b128 v[244:247], v140 offset:56320
	buffer_load_dwordx4 v134, s[64:67], s52 offen lds
	s_mov_b32 m0, s34
	s_add_i32 s47, s47, 0x200080
	buffer_load_dwordx4 v136, s[64:67], s52 offen lds
	s_mov_b32 m0, s37
	s_nop 0
	buffer_load_dwordx4 v134, s[64:67], s47 offen lds
	s_mov_b32 m0, s68
	s_nop 0
	buffer_load_dwordx4 v136, s[64:67], s47 offen lds
	s_mov_b32 m0, s35
	s_nop 0
	buffer_load_dwordx4 v131, s[60:63], s27 offen lds
	s_mov_b32 m0, s36
	s_nop 0
	buffer_load_dwordx4 v135, s[60:63], s27 offen lds
	s_waitcnt vmcnt(8)
	s_waitcnt lgkmcnt(0)
	s_setprio 1
	s_barrier
	v_mfma_f32_16x16x32_bf16 v[94:97], v[142:145], v[194:197], v[94:97]
	v_mfma_f32_16x16x32_bf16 v[90:93], v[170:173], v[194:197], v[90:93]
	v_mfma_f32_16x16x32_bf16 v[86:89], v[142:145], v[202:205], v[86:89]
	v_mfma_f32_16x16x32_bf16 v[82:85], v[170:173], v[202:205], v[82:85]
	v_mfma_f32_16x16x32_bf16 v[78:81], v[142:145], v[232:235], v[78:81]
	v_mfma_f32_16x16x32_bf16 v[74:77], v[170:173], v[232:235], v[74:77]
	v_mfma_f32_16x16x32_bf16 v[70:73], v[142:145], v[240:243], v[70:73]
	v_mfma_f32_16x16x32_bf16 v[66:69], v[170:173], v[240:243], v[66:69]
	v_mfma_f32_16x16x32_bf16 v[94:97], v[154:157], v[198:201], v[94:97]
	v_mfma_f32_16x16x32_bf16 v[90:93], v[174:177], v[198:201], v[90:93]
	v_mfma_f32_16x16x32_bf16 v[86:89], v[154:157], v[228:231], v[86:89]
	v_mfma_f32_16x16x32_bf16 v[82:85], v[174:177], v[228:231], v[82:85]
	v_mfma_f32_16x16x32_bf16 v[78:81], v[154:157], v[236:239], v[78:81]
	v_mfma_f32_16x16x32_bf16 v[74:77], v[174:177], v[236:239], v[74:77]
	v_mfma_f32_16x16x32_bf16 v[70:73], v[154:157], v[244:247], v[70:73]
	v_mfma_f32_16x16x32_bf16 v[66:69], v[174:177], v[244:247], v[66:69]
	v_mfma_f32_16x16x32_bf16 v[30:33], v[178:181], v[194:197], v[30:33]
	v_mfma_f32_16x16x32_bf16 v[26:29], v[186:189], v[194:197], v[26:29]
	v_mfma_f32_16x16x32_bf16 v[22:25], v[178:181], v[202:205], v[22:25]
	v_mfma_f32_16x16x32_bf16 v[18:21], v[186:189], v[202:205], v[18:21]
	v_mfma_f32_16x16x32_bf16 v[14:17], v[178:181], v[232:235], v[14:17]
	v_mfma_f32_16x16x32_bf16 v[10:13], v[186:189], v[232:235], v[10:13]
	v_mfma_f32_16x16x32_bf16 v[6:9], v[178:181], v[240:243], v[6:9]
	v_mfma_f32_16x16x32_bf16 v[2:5], v[186:189], v[240:243], v[2:5]
	v_mfma_f32_16x16x32_bf16 v[30:33], v[182:185], v[198:201], v[30:33]
	v_mfma_f32_16x16x32_bf16 v[26:29], v[190:193], v[198:201], v[26:29]
	v_mfma_f32_16x16x32_bf16 v[22:25], v[182:185], v[228:231], v[22:25]
	v_mfma_f32_16x16x32_bf16 v[18:21], v[190:193], v[228:231], v[18:21]
	v_mfma_f32_16x16x32_bf16 v[14:17], v[182:185], v[236:239], v[14:17]
	v_mfma_f32_16x16x32_bf16 v[10:13], v[190:193], v[236:239], v[10:13]
	v_mfma_f32_16x16x32_bf16 v[6:9], v[182:185], v[244:247], v[6:9]
	v_mfma_f32_16x16x32_bf16 v[2:5], v[190:193], v[244:247], v[2:5]
	s_barrier
	s_setprio 0
	s_add_i32 s26, s26, 2
	s_addk_i32 s19, 0x100
	s_addk_i32 s22, 0x100
	s_cmpk_gt_u32 s26, 0x7d

.LBB0_1252:
	s_lshl_b32 s12, s73, 20
	s_and_b64 s[8:9], s[40:41], exec
	s_cselect_b32 s8, s12, s26
	s_lshl_b32 s22, s82, 20
	s_and_b64 s[70:71], s[40:41], exec
	s_cselect_b32 s9, s22, s27
	s_add_i32 s26, s26, 0x80080
	s_addk_i32 s27, 0x100
	s_mov_b32 s83, -2
	v_add_u32_e32 v141, 0x10000, v139
	ds_read_b128 v[142:145], v141
	ds_read_b128 v[154:157], v141 offset:1024
	ds_read_b128 v[170:173], v141 offset:2048
	ds_read_b128 v[174:177], v141 offset:3072
	v_add_u32_e32 v141, 0x14000, v139
	ds_read_b128 v[178:181], v141
	ds_read_b128 v[182:185], v141 offset:1024
	ds_read_b128 v[186:189], v141 offset:2048
	ds_read_b128 v[190:193], v141 offset:3072
	s_add_i32 s52, s26, 0xfff80080
	s_cmp_eq_u32 s83, 28
	s_cselect_b32 s52, s8, s52
	s_cselect_b32 s85, s9, s27
	s_or_b32 s84, s52, 0x80
	s_mov_b32 m0, s72
	ds_read_b128 v[194:197], v140
	ds_read_b128 v[198:201], v140 offset:1024
	ds_read_b128 v[202:205], v140 offset:2048
	ds_read_b128 v[228:231], v140 offset:3072
	ds_read_b128 v[232:235], v140 offset:4096
	ds_read_b128 v[236:239], v140 offset:5120
	ds_read_b128 v[240:243], v140 offset:6144
	ds_read_b128 v[244:247], v140 offset:7168
	buffer_load_dwordx4 v131, s[60:63], s26 offen lds
	s_mov_b32 m0, s46
	s_nop 0
	buffer_load_dwordx4 v135, s[60:63], s26 offen lds
	s_waitcnt vmcnt(8)
	s_waitcnt lgkmcnt(0)
	s_setprio 1
	s_barrier
	v_mfma_f32_16x16x32_bf16 v[126:129], v[142:145], v[194:197], 0
	v_mfma_f32_16x16x32_bf16 v[122:125], v[170:173], v[194:197], 0
	v_mfma_f32_16x16x32_bf16 v[118:121], v[142:145], v[202:205], 0
	v_mfma_f32_16x16x32_bf16 v[114:117], v[170:173], v[202:205], 0
	v_mfma_f32_16x16x32_bf16 v[110:113], v[142:145], v[232:235], 0
	v_mfma_f32_16x16x32_bf16 v[106:109], v[170:173], v[232:235], 0
	v_mfma_f32_16x16x32_bf16 v[102:105], v[142:145], v[240:243], 0
	v_mfma_f32_16x16x32_bf16 v[98:101], v[170:173], v[240:243], 0
	v_mfma_f32_16x16x32_bf16 v[126:129], v[154:157], v[198:201], v[126:129]
	v_mfma_f32_16x16x32_bf16 v[122:125], v[174:177], v[198:201], v[122:125]
	v_mfma_f32_16x16x32_bf16 v[118:121], v[154:157], v[228:231], v[118:121]
	v_mfma_f32_16x16x32_bf16 v[114:117], v[174:177], v[228:231], v[114:117]
	v_mfma_f32_16x16x32_bf16 v[110:113], v[154:157], v[236:239], v[110:113]
	v_mfma_f32_16x16x32_bf16 v[106:109], v[174:177], v[236:239], v[106:109]
	v_mfma_f32_16x16x32_bf16 v[102:105], v[154:157], v[244:247], v[102:105]
	v_mfma_f32_16x16x32_bf16 v[98:101], v[174:177], v[244:247], v[98:101]
	v_mfma_f32_16x16x32_bf16 v[62:65], v[178:181], v[194:197], 0
	v_mfma_f32_16x16x32_bf16 v[58:61], v[186:189], v[194:197], 0
	v_mfma_f32_16x16x32_bf16 v[54:57], v[178:181], v[202:205], 0
	v_mfma_f32_16x16x32_bf16 v[50:53], v[186:189], v[202:205], 0
	v_mfma_f32_16x16x32_bf16 v[46:49], v[178:181], v[232:235], 0
	v_mfma_f32_16x16x32_bf16 v[42:45], v[186:189], v[232:235], 0
	v_mfma_f32_16x16x32_bf16 v[38:41], v[178:181], v[240:243], 0
	v_mfma_f32_16x16x32_bf16 v[34:37], v[186:189], v[240:243], 0
	v_mfma_f32_16x16x32_bf16 v[62:65], v[182:185], v[198:201], v[62:65]
	v_mfma_f32_16x16x32_bf16 v[58:61], v[190:193], v[198:201], v[58:61]
	v_mfma_f32_16x16x32_bf16 v[54:57], v[182:185], v[228:231], v[54:57]
	v_mfma_f32_16x16x32_bf16 v[50:53], v[190:193], v[228:231], v[50:53]
	v_mfma_f32_16x16x32_bf16 v[46:49], v[182:185], v[236:239], v[46:49]
	v_mfma_f32_16x16x32_bf16 v[42:45], v[190:193], v[236:239], v[42:45]
	v_mfma_f32_16x16x32_bf16 v[38:41], v[182:185], v[244:247], v[38:41]
	v_mfma_f32_16x16x32_bf16 v[34:37], v[190:193], v[244:247], v[34:37]
	s_barrier
	s_setprio 0
	s_mov_b32 m0, s21
	s_mov_b32 s70, s62
	s_mov_b32 s71, s63
	ds_read_b128 v[194:197], v140 offset:16384
	ds_read_b128 v[198:201], v140 offset:17408
	ds_read_b128 v[202:205], v140 offset:18432
	ds_read_b128 v[228:231], v140 offset:19456
	ds_read_b128 v[232:235], v140 offset:20480
	ds_read_b128 v[236:239], v140 offset:21504
	ds_read_b128 v[240:243], v140 offset:22528
	ds_read_b128 v[244:247], v140 offset:23552
	buffer_load_dwordx4 v134, s[68:71], s85 offen lds
	s_mov_b32 m0, s23
	s_add_i32 s53, s85, 0x80000
	buffer_load_dwordx4 v136, s[68:71], s85 offen lds
	s_mov_b32 m0, s24
	s_nop 0
	buffer_load_dwordx4 v134, s[68:71], s53 offen lds
	s_mov_b32 m0, s25
	s_nop 0
	buffer_load_dwordx4 v136, s[68:71], s53 offen lds
	s_mov_b32 m0, s16
	s_nop 0
	buffer_load_dwordx4 v131, s[60:63], s52 offen lds
	s_mov_b32 m0, s30
	s_nop 0
	buffer_load_dwordx4 v135, s[60:63], s52 offen lds
	s_waitcnt vmcnt(8)
	s_waitcnt lgkmcnt(0)
	s_setprio 1
	s_barrier
	v_mfma_f32_16x16x32_bf16 v[94:97], v[142:145], v[194:197], 0
	v_mfma_f32_16x16x32_bf16 v[90:93], v[170:173], v[194:197], 0
	v_mfma_f32_16x16x32_bf16 v[86:89], v[142:145], v[202:205], 0
	v_mfma_f32_16x16x32_bf16 v[82:85], v[170:173], v[202:205], 0
	v_mfma_f32_16x16x32_bf16 v[78:81], v[142:145], v[232:235], 0
	v_mfma_f32_16x16x32_bf16 v[74:77], v[170:173], v[232:235], 0
	v_mfma_f32_16x16x32_bf16 v[70:73], v[142:145], v[240:243], 0
	v_mfma_f32_16x16x32_bf16 v[66:69], v[170:173], v[240:243], 0
	v_mfma_f32_16x16x32_bf16 v[94:97], v[154:157], v[198:201], v[94:97]
	v_mfma_f32_16x16x32_bf16 v[90:93], v[174:177], v[198:201], v[90:93]
	v_mfma_f32_16x16x32_bf16 v[86:89], v[154:157], v[228:231], v[86:89]
	v_mfma_f32_16x16x32_bf16 v[82:85], v[174:177], v[228:231], v[82:85]
	v_mfma_f32_16x16x32_bf16 v[78:81], v[154:157], v[236:239], v[78:81]
	v_mfma_f32_16x16x32_bf16 v[74:77], v[174:177], v[236:239], v[74:77]
	v_mfma_f32_16x16x32_bf16 v[70:73], v[154:157], v[244:247], v[70:73]
	v_mfma_f32_16x16x32_bf16 v[66:69], v[174:177], v[244:247], v[66:69]
	v_mfma_f32_16x16x32_bf16 v[30:33], v[178:181], v[194:197], 0
	v_mfma_f32_16x16x32_bf16 v[26:29], v[186:189], v[194:197], 0
	v_mfma_f32_16x16x32_bf16 v[22:25], v[178:181], v[202:205], 0
	v_mfma_f32_16x16x32_bf16 v[18:21], v[186:189], v[202:205], 0
	v_mfma_f32_16x16x32_bf16 v[14:17], v[178:181], v[232:235], 0
	v_mfma_f32_16x16x32_bf16 v[10:13], v[186:189], v[232:235], 0
	v_mfma_f32_16x16x32_bf16 v[6:9], v[178:181], v[240:243], 0
	v_mfma_f32_16x16x32_bf16 v[2:5], v[186:189], v[240:243], 0
	v_mfma_f32_16x16x32_bf16 v[30:33], v[182:185], v[198:201], v[30:33]
	v_mfma_f32_16x16x32_bf16 v[26:29], v[190:193], v[198:201], v[26:29]
	v_mfma_f32_16x16x32_bf16 v[22:25], v[182:185], v[228:231], v[22:25]
	v_mfma_f32_16x16x32_bf16 v[18:21], v[190:193], v[228:231], v[18:21]
	v_mfma_f32_16x16x32_bf16 v[14:17], v[182:185], v[236:239], v[14:17]
	v_mfma_f32_16x16x32_bf16 v[10:13], v[190:193], v[236:239], v[10:13]
	v_mfma_f32_16x16x32_bf16 v[6:9], v[182:185], v[244:247], v[6:9]
	v_mfma_f32_16x16x32_bf16 v[2:5], v[190:193], v[244:247], v[2:5]
	s_barrier
	s_setprio 0
	v_add_u32_e32 v141, 0x18000, v139
	ds_read_b128 v[142:145], v141
	ds_read_b128 v[154:157], v141 offset:1024
	ds_read_b128 v[170:173], v141 offset:2048
	ds_read_b128 v[174:177], v141 offset:3072
	v_add_u32_e32 v141, 0x1c000, v139
	ds_read_b128 v[178:181], v141
	ds_read_b128 v[182:185], v141 offset:1024
	ds_read_b128 v[186:189], v141 offset:2048
	ds_read_b128 v[190:193], v141 offset:3072
	s_add_i32 s52, s52, 0x80000
	s_mov_b32 m0, s31
	ds_read_b128 v[194:197], v140 offset:32768
	ds_read_b128 v[198:201], v140 offset:33792
	ds_read_b128 v[202:205], v140 offset:34816
	ds_read_b128 v[228:231], v140 offset:35840
	ds_read_b128 v[232:235], v140 offset:36864
	ds_read_b128 v[236:239], v140 offset:37888
	ds_read_b128 v[240:243], v140 offset:38912
	ds_read_b128 v[244:247], v140 offset:39936
	buffer_load_dwordx4 v131, s[60:63], s52 offen lds
	s_mov_b32 m0, s33
	s_nop 0
	buffer_load_dwordx4 v135, s[60:63], s52 offen lds
	s_waitcnt vmcnt(8)
	s_waitcnt lgkmcnt(0)
	s_setprio 1
	s_barrier
	v_mfma_f32_16x16x32_bf16 v[126:129], v[142:145], v[194:197], v[126:129]
	v_mfma_f32_16x16x32_bf16 v[122:125], v[170:173], v[194:197], v[122:125]
	v_mfma_f32_16x16x32_bf16 v[118:121], v[142:145], v[202:205], v[118:121]
	v_mfma_f32_16x16x32_bf16 v[114:117], v[170:173], v[202:205], v[114:117]
	v_mfma_f32_16x16x32_bf16 v[110:113], v[142:145], v[232:235], v[110:113]
	v_mfma_f32_16x16x32_bf16 v[106:109], v[170:173], v[232:235], v[106:109]
	v_mfma_f32_16x16x32_bf16 v[102:105], v[142:145], v[240:243], v[102:105]
	v_mfma_f32_16x16x32_bf16 v[98:101], v[170:173], v[240:243], v[98:101]
	v_mfma_f32_16x16x32_bf16 v[126:129], v[154:157], v[198:201], v[126:129]
	v_mfma_f32_16x16x32_bf16 v[122:125], v[174:177], v[198:201], v[122:125]
	v_mfma_f32_16x16x32_bf16 v[118:121], v[154:157], v[228:231], v[118:121]
	v_mfma_f32_16x16x32_bf16 v[114:117], v[174:177], v[228:231], v[114:117]
	v_mfma_f32_16x16x32_bf16 v[110:113], v[154:157], v[236:239], v[110:113]
	v_mfma_f32_16x16x32_bf16 v[106:109], v[174:177], v[236:239], v[106:109]
	v_mfma_f32_16x16x32_bf16 v[102:105], v[154:157], v[244:247], v[102:105]
	v_mfma_f32_16x16x32_bf16 v[98:101], v[174:177], v[244:247], v[98:101]
	v_mfma_f32_16x16x32_bf16 v[62:65], v[178:181], v[194:197], v[62:65]
	v_mfma_f32_16x16x32_bf16 v[58:61], v[186:189], v[194:197], v[58:61]
	v_mfma_f32_16x16x32_bf16 v[54:57], v[178:181], v[202:205], v[54:57]
	v_mfma_f32_16x16x32_bf16 v[50:53], v[186:189], v[202:205], v[50:53]
	v_mfma_f32_16x16x32_bf16 v[46:49], v[178:181], v[232:235], v[46:49]
	v_mfma_f32_16x16x32_bf16 v[42:45], v[186:189], v[232:235], v[42:45]
	v_mfma_f32_16x16x32_bf16 v[38:41], v[178:181], v[240:243], v[38:41]
	v_mfma_f32_16x16x32_bf16 v[34:37], v[186:189], v[240:243], v[34:37]
	v_mfma_f32_16x16x32_bf16 v[62:65], v[182:185], v[198:201], v[62:65]
	v_mfma_f32_16x16x32_bf16 v[58:61], v[190:193], v[198:201], v[58:61]
	v_mfma_f32_16x16x32_bf16 v[54:57], v[182:185], v[228:231], v[54:57]
	v_mfma_f32_16x16x32_bf16 v[50:53], v[190:193], v[228:231], v[50:53]
	v_mfma_f32_16x16x32_bf16 v[46:49], v[182:185], v[236:239], v[46:49]
	v_mfma_f32_16x16x32_bf16 v[42:45], v[190:193], v[236:239], v[42:45]
	v_mfma_f32_16x16x32_bf16 v[38:41], v[182:185], v[244:247], v[38:41]
	v_mfma_f32_16x16x32_bf16 v[34:37], v[190:193], v[244:247], v[34:37]
	s_barrier
	s_setprio 0
	s_mov_b32 m0, s34
	s_or_b32 s52, s85, 0x80
	ds_read_b128 v[194:197], v140 offset:49152
	ds_read_b128 v[198:201], v140 offset:50176
	ds_read_b128 v[202:205], v140 offset:51200
	ds_read_b128 v[228:231], v140 offset:52224
	ds_read_b128 v[232:235], v140 offset:53248
	ds_read_b128 v[236:239], v140 offset:54272
	ds_read_b128 v[240:243], v140 offset:55296
	ds_read_b128 v[244:247], v140 offset:56320
	buffer_load_dwordx4 v134, s[68:71], s52 offen lds
	s_mov_b32 m0, s35
	s_add_i32 s85, s85, 0x80080
	buffer_load_dwordx4 v136, s[68:71], s52 offen lds
	s_mov_b32 m0, s37
	s_nop 0
	buffer_load_dwordx4 v134, s[68:71], s85 offen lds
	s_mov_b32 m0, s65
	s_nop 0
	buffer_load_dwordx4 v136, s[68:71], s85 offen lds
	s_mov_b32 m0, s14
	s_nop 0
	buffer_load_dwordx4 v131, s[60:63], s84 offen lds
	s_mov_b32 m0, s36
	s_nop 0
	buffer_load_dwordx4 v135, s[60:63], s84 offen lds
	s_waitcnt vmcnt(8)
	s_waitcnt lgkmcnt(0)
	s_setprio 1
	s_barrier
	v_mfma_f32_16x16x32_bf16 v[94:97], v[142:145], v[194:197], v[94:97]
	v_mfma_f32_16x16x32_bf16 v[90:93], v[170:173], v[194:197], v[90:93]
	v_mfma_f32_16x16x32_bf16 v[86:89], v[142:145], v[202:205], v[86:89]
	v_mfma_f32_16x16x32_bf16 v[82:85], v[170:173], v[202:205], v[82:85]
	v_mfma_f32_16x16x32_bf16 v[78:81], v[142:145], v[232:235], v[78:81]
	v_mfma_f32_16x16x32_bf16 v[74:77], v[170:173], v[232:235], v[74:77]
	v_mfma_f32_16x16x32_bf16 v[70:73], v[142:145], v[240:243], v[70:73]
	v_mfma_f32_16x16x32_bf16 v[66:69], v[170:173], v[240:243], v[66:69]
	v_mfma_f32_16x16x32_bf16 v[94:97], v[154:157], v[198:201], v[94:97]
	v_mfma_f32_16x16x32_bf16 v[90:93], v[174:177], v[198:201], v[90:93]
	v_mfma_f32_16x16x32_bf16 v[86:89], v[154:157], v[228:231], v[86:89]
	v_mfma_f32_16x16x32_bf16 v[82:85], v[174:177], v[228:231], v[82:85]
	v_mfma_f32_16x16x32_bf16 v[78:81], v[154:157], v[236:239], v[78:81]
	v_mfma_f32_16x16x32_bf16 v[74:77], v[174:177], v[236:239], v[74:77]
	v_mfma_f32_16x16x32_bf16 v[70:73], v[154:157], v[244:247], v[70:73]
	v_mfma_f32_16x16x32_bf16 v[66:69], v[174:177], v[244:247], v[66:69]
	v_mfma_f32_16x16x32_bf16 v[30:33], v[178:181], v[194:197], v[30:33]
	v_mfma_f32_16x16x32_bf16 v[26:29], v[186:189], v[194:197], v[26:29]
	v_mfma_f32_16x16x32_bf16 v[22:25], v[178:181], v[202:205], v[22:25]
	v_mfma_f32_16x16x32_bf16 v[18:21], v[186:189], v[202:205], v[18:21]
	v_mfma_f32_16x16x32_bf16 v[14:17], v[178:181], v[232:235], v[14:17]
	v_mfma_f32_16x16x32_bf16 v[10:13], v[186:189], v[232:235], v[10:13]
	v_mfma_f32_16x16x32_bf16 v[6:9], v[178:181], v[240:243], v[6:9]
	v_mfma_f32_16x16x32_bf16 v[2:5], v[186:189], v[240:243], v[2:5]
	v_mfma_f32_16x16x32_bf16 v[30:33], v[182:185], v[198:201], v[30:33]
	v_mfma_f32_16x16x32_bf16 v[26:29], v[190:193], v[198:201], v[26:29]
	v_mfma_f32_16x16x32_bf16 v[22:25], v[182:185], v[228:231], v[22:25]
	v_mfma_f32_16x16x32_bf16 v[18:21], v[190:193], v[228:231], v[18:21]
	v_mfma_f32_16x16x32_bf16 v[14:17], v[182:185], v[236:239], v[14:17]
	v_mfma_f32_16x16x32_bf16 v[10:13], v[190:193], v[236:239], v[10:13]
	v_mfma_f32_16x16x32_bf16 v[6:9], v[182:185], v[244:247], v[6:9]
	v_mfma_f32_16x16x32_bf16 v[2:5], v[190:193], v[244:247], v[2:5]
	s_barrier
	s_setprio 0
	s_add_i32 s83, s83, 2
	s_addk_i32 s26, 0x100
	s_addk_i32 s27, 0x100
	s_cmp_gt_u32 s83, 29

.LBB0_1282:
	s_lshl_b32 s46, s85, 20
	s_and_b64 s[8:9], s[40:41], exec
	s_cselect_b32 s8, s46, s19
	s_lshl_b32 s47, s14, 20
	s_and_b64 s[26:27], s[40:41], exec
	s_cselect_b32 s9, s47, s22
	s_add_i32 s19, s19, 0x80080
	s_addk_i32 s22, 0x100
	s_mov_b32 s26, -2
	v_add_u32_e32 v141, 0x10000, v139
	ds_read_b128 v[142:145], v141
	ds_read_b128 v[154:157], v141 offset:1024
	ds_read_b128 v[170:173], v141 offset:2048
	ds_read_b128 v[174:177], v141 offset:3072
	v_add_u32_e32 v141, 0x14000, v139
	ds_read_b128 v[178:181], v141
	ds_read_b128 v[182:185], v141 offset:1024
	ds_read_b128 v[186:189], v141 offset:2048
	ds_read_b128 v[190:193], v141 offset:3072
	s_add_i32 s27, s19, 0xfff80080
	s_cmp_eq_u32 s26, 28
	s_cselect_b32 s52, s8, s27
	s_cselect_b32 s83, s9, s22
	s_or_b32 s27, s52, 0x80
	s_mov_b32 m0, s73
	ds_read_b128 v[194:197], v140
	ds_read_b128 v[198:201], v140 offset:1024
	ds_read_b128 v[202:205], v140 offset:2048
	ds_read_b128 v[228:231], v140 offset:3072
	ds_read_b128 v[232:235], v140 offset:4096
	ds_read_b128 v[236:239], v140 offset:5120
	ds_read_b128 v[240:243], v140 offset:6144
	ds_read_b128 v[244:247], v140 offset:7168
	buffer_load_dwordx4 v131, s[60:63], s19 offen lds
	s_mov_b32 m0, s82
	s_nop 0
	buffer_load_dwordx4 v135, s[60:63], s19 offen lds
	s_waitcnt vmcnt(8)
	s_waitcnt lgkmcnt(0)
	s_setprio 1
	s_barrier
	v_mfma_f32_16x16x32_bf16 v[126:129], v[142:145], v[194:197], 0
	v_mfma_f32_16x16x32_bf16 v[122:125], v[170:173], v[194:197], 0
	v_mfma_f32_16x16x32_bf16 v[118:121], v[142:145], v[202:205], 0
	v_mfma_f32_16x16x32_bf16 v[114:117], v[170:173], v[202:205], 0
	v_mfma_f32_16x16x32_bf16 v[110:113], v[142:145], v[232:235], 0
	v_mfma_f32_16x16x32_bf16 v[106:109], v[170:173], v[232:235], 0
	v_mfma_f32_16x16x32_bf16 v[102:105], v[142:145], v[240:243], 0
	v_mfma_f32_16x16x32_bf16 v[98:101], v[170:173], v[240:243], 0
	v_mfma_f32_16x16x32_bf16 v[126:129], v[154:157], v[198:201], v[126:129]
	v_mfma_f32_16x16x32_bf16 v[122:125], v[174:177], v[198:201], v[122:125]
	v_mfma_f32_16x16x32_bf16 v[118:121], v[154:157], v[228:231], v[118:121]
	v_mfma_f32_16x16x32_bf16 v[114:117], v[174:177], v[228:231], v[114:117]
	v_mfma_f32_16x16x32_bf16 v[110:113], v[154:157], v[236:239], v[110:113]
	v_mfma_f32_16x16x32_bf16 v[106:109], v[174:177], v[236:239], v[106:109]
	v_mfma_f32_16x16x32_bf16 v[102:105], v[154:157], v[244:247], v[102:105]
	v_mfma_f32_16x16x32_bf16 v[98:101], v[174:177], v[244:247], v[98:101]
	v_mfma_f32_16x16x32_bf16 v[62:65], v[178:181], v[194:197], 0
	v_mfma_f32_16x16x32_bf16 v[58:61], v[186:189], v[194:197], 0
	v_mfma_f32_16x16x32_bf16 v[54:57], v[178:181], v[202:205], 0
	v_mfma_f32_16x16x32_bf16 v[50:53], v[186:189], v[202:205], 0
	v_mfma_f32_16x16x32_bf16 v[46:49], v[178:181], v[232:235], 0
	v_mfma_f32_16x16x32_bf16 v[42:45], v[186:189], v[232:235], 0
	v_mfma_f32_16x16x32_bf16 v[38:41], v[178:181], v[240:243], 0
	v_mfma_f32_16x16x32_bf16 v[34:37], v[186:189], v[240:243], 0
	v_mfma_f32_16x16x32_bf16 v[62:65], v[182:185], v[198:201], v[62:65]
	v_mfma_f32_16x16x32_bf16 v[58:61], v[190:193], v[198:201], v[58:61]
	v_mfma_f32_16x16x32_bf16 v[54:57], v[182:185], v[228:231], v[54:57]
	v_mfma_f32_16x16x32_bf16 v[50:53], v[190:193], v[228:231], v[50:53]
	v_mfma_f32_16x16x32_bf16 v[46:49], v[182:185], v[236:239], v[46:49]
	v_mfma_f32_16x16x32_bf16 v[42:45], v[190:193], v[236:239], v[42:45]
	v_mfma_f32_16x16x32_bf16 v[38:41], v[182:185], v[244:247], v[38:41]
	v_mfma_f32_16x16x32_bf16 v[34:37], v[190:193], v[244:247], v[34:37]
	s_barrier
	s_setprio 0
	s_mov_b32 m0, s21
	s_mov_b32 s70, s62
	s_mov_b32 s71, s63
	ds_read_b128 v[194:197], v140 offset:16384
	ds_read_b128 v[198:201], v140 offset:17408
	ds_read_b128 v[202:205], v140 offset:18432
	ds_read_b128 v[228:231], v140 offset:19456
	ds_read_b128 v[232:235], v140 offset:20480
	ds_read_b128 v[236:239], v140 offset:21504
	ds_read_b128 v[240:243], v140 offset:22528
	ds_read_b128 v[244:247], v140 offset:23552
	buffer_load_dwordx4 v134, s[68:71], s83 offen lds
	s_mov_b32 m0, s23
	s_add_i32 s53, s83, 0x80000
	buffer_load_dwordx4 v136, s[68:71], s83 offen lds
	s_mov_b32 m0, s24
	s_nop 0
	buffer_load_dwordx4 v134, s[68:71], s53 offen lds
	s_mov_b32 m0, s25
	s_nop 0
	buffer_load_dwordx4 v136, s[68:71], s53 offen lds
	s_mov_b32 m0, s2
	s_nop 0
	buffer_load_dwordx4 v131, s[60:63], s52 offen lds
	s_mov_b32 m0, s30
	s_nop 0
	buffer_load_dwordx4 v135, s[60:63], s52 offen lds
	s_waitcnt vmcnt(8)
	s_waitcnt lgkmcnt(0)
	s_setprio 1
	s_barrier
	v_mfma_f32_16x16x32_bf16 v[94:97], v[142:145], v[194:197], 0
	v_mfma_f32_16x16x32_bf16 v[90:93], v[170:173], v[194:197], 0
	v_mfma_f32_16x16x32_bf16 v[86:89], v[142:145], v[202:205], 0
	v_mfma_f32_16x16x32_bf16 v[82:85], v[170:173], v[202:205], 0
	v_mfma_f32_16x16x32_bf16 v[78:81], v[142:145], v[232:235], 0
	v_mfma_f32_16x16x32_bf16 v[74:77], v[170:173], v[232:235], 0
	v_mfma_f32_16x16x32_bf16 v[70:73], v[142:145], v[240:243], 0
	v_mfma_f32_16x16x32_bf16 v[66:69], v[170:173], v[240:243], 0
	v_mfma_f32_16x16x32_bf16 v[94:97], v[154:157], v[198:201], v[94:97]
	v_mfma_f32_16x16x32_bf16 v[90:93], v[174:177], v[198:201], v[90:93]
	v_mfma_f32_16x16x32_bf16 v[86:89], v[154:157], v[228:231], v[86:89]
	v_mfma_f32_16x16x32_bf16 v[82:85], v[174:177], v[228:231], v[82:85]
	v_mfma_f32_16x16x32_bf16 v[78:81], v[154:157], v[236:239], v[78:81]
	v_mfma_f32_16x16x32_bf16 v[74:77], v[174:177], v[236:239], v[74:77]
	v_mfma_f32_16x16x32_bf16 v[70:73], v[154:157], v[244:247], v[70:73]
	v_mfma_f32_16x16x32_bf16 v[66:69], v[174:177], v[244:247], v[66:69]
	v_mfma_f32_16x16x32_bf16 v[30:33], v[178:181], v[194:197], 0
	v_mfma_f32_16x16x32_bf16 v[26:29], v[186:189], v[194:197], 0
	v_mfma_f32_16x16x32_bf16 v[22:25], v[178:181], v[202:205], 0
	v_mfma_f32_16x16x32_bf16 v[18:21], v[186:189], v[202:205], 0
	v_mfma_f32_16x16x32_bf16 v[14:17], v[178:181], v[232:235], 0
	v_mfma_f32_16x16x32_bf16 v[10:13], v[186:189], v[232:235], 0
	v_mfma_f32_16x16x32_bf16 v[6:9], v[178:181], v[240:243], 0
	v_mfma_f32_16x16x32_bf16 v[2:5], v[186:189], v[240:243], 0
	v_mfma_f32_16x16x32_bf16 v[30:33], v[182:185], v[198:201], v[30:33]
	v_mfma_f32_16x16x32_bf16 v[26:29], v[190:193], v[198:201], v[26:29]
	v_mfma_f32_16x16x32_bf16 v[22:25], v[182:185], v[228:231], v[22:25]
	v_mfma_f32_16x16x32_bf16 v[18:21], v[190:193], v[228:231], v[18:21]
	v_mfma_f32_16x16x32_bf16 v[14:17], v[182:185], v[236:239], v[14:17]
	v_mfma_f32_16x16x32_bf16 v[10:13], v[190:193], v[236:239], v[10:13]
	v_mfma_f32_16x16x32_bf16 v[6:9], v[182:185], v[244:247], v[6:9]
	v_mfma_f32_16x16x32_bf16 v[2:5], v[190:193], v[244:247], v[2:5]
	s_barrier
	s_setprio 0
	v_add_u32_e32 v141, 0x18000, v139
	ds_read_b128 v[142:145], v141
	ds_read_b128 v[154:157], v141 offset:1024
	ds_read_b128 v[170:173], v141 offset:2048
	ds_read_b128 v[174:177], v141 offset:3072
	v_add_u32_e32 v141, 0x1c000, v139
	ds_read_b128 v[178:181], v141
	ds_read_b128 v[182:185], v141 offset:1024
	ds_read_b128 v[186:189], v141 offset:2048
	ds_read_b128 v[190:193], v141 offset:3072
	s_add_i32 s52, s52, 0x80000
	s_mov_b32 m0, s31
	ds_read_b128 v[194:197], v140 offset:32768
	ds_read_b128 v[198:201], v140 offset:33792
	ds_read_b128 v[202:205], v140 offset:34816
	ds_read_b128 v[228:231], v140 offset:35840
	ds_read_b128 v[232:235], v140 offset:36864
	ds_read_b128 v[236:239], v140 offset:37888
	ds_read_b128 v[240:243], v140 offset:38912
	ds_read_b128 v[244:247], v140 offset:39936
	buffer_load_dwordx4 v131, s[60:63], s52 offen lds
	s_mov_b32 m0, s33
	s_nop 0
	buffer_load_dwordx4 v135, s[60:63], s52 offen lds
	s_waitcnt vmcnt(8)
	s_waitcnt lgkmcnt(0)
	s_setprio 1
	s_barrier
	v_mfma_f32_16x16x32_bf16 v[126:129], v[142:145], v[194:197], v[126:129]
	v_mfma_f32_16x16x32_bf16 v[122:125], v[170:173], v[194:197], v[122:125]
	v_mfma_f32_16x16x32_bf16 v[118:121], v[142:145], v[202:205], v[118:121]
	v_mfma_f32_16x16x32_bf16 v[114:117], v[170:173], v[202:205], v[114:117]
	v_mfma_f32_16x16x32_bf16 v[110:113], v[142:145], v[232:235], v[110:113]
	v_mfma_f32_16x16x32_bf16 v[106:109], v[170:173], v[232:235], v[106:109]
	v_mfma_f32_16x16x32_bf16 v[102:105], v[142:145], v[240:243], v[102:105]
	v_mfma_f32_16x16x32_bf16 v[98:101], v[170:173], v[240:243], v[98:101]
	v_mfma_f32_16x16x32_bf16 v[126:129], v[154:157], v[198:201], v[126:129]
	v_mfma_f32_16x16x32_bf16 v[122:125], v[174:177], v[198:201], v[122:125]
	v_mfma_f32_16x16x32_bf16 v[118:121], v[154:157], v[228:231], v[118:121]
	v_mfma_f32_16x16x32_bf16 v[114:117], v[174:177], v[228:231], v[114:117]
	v_mfma_f32_16x16x32_bf16 v[110:113], v[154:157], v[236:239], v[110:113]
	v_mfma_f32_16x16x32_bf16 v[106:109], v[174:177], v[236:239], v[106:109]
	v_mfma_f32_16x16x32_bf16 v[102:105], v[154:157], v[244:247], v[102:105]
	v_mfma_f32_16x16x32_bf16 v[98:101], v[174:177], v[244:247], v[98:101]
	v_mfma_f32_16x16x32_bf16 v[62:65], v[178:181], v[194:197], v[62:65]
	v_mfma_f32_16x16x32_bf16 v[58:61], v[186:189], v[194:197], v[58:61]
	v_mfma_f32_16x16x32_bf16 v[54:57], v[178:181], v[202:205], v[54:57]
	v_mfma_f32_16x16x32_bf16 v[50:53], v[186:189], v[202:205], v[50:53]
	v_mfma_f32_16x16x32_bf16 v[46:49], v[178:181], v[232:235], v[46:49]
	v_mfma_f32_16x16x32_bf16 v[42:45], v[186:189], v[232:235], v[42:45]
	v_mfma_f32_16x16x32_bf16 v[38:41], v[178:181], v[240:243], v[38:41]
	v_mfma_f32_16x16x32_bf16 v[34:37], v[186:189], v[240:243], v[34:37]
	v_mfma_f32_16x16x32_bf16 v[62:65], v[182:185], v[198:201], v[62:65]
	v_mfma_f32_16x16x32_bf16 v[58:61], v[190:193], v[198:201], v[58:61]
	v_mfma_f32_16x16x32_bf16 v[54:57], v[182:185], v[228:231], v[54:57]
	v_mfma_f32_16x16x32_bf16 v[50:53], v[190:193], v[228:231], v[50:53]
	v_mfma_f32_16x16x32_bf16 v[46:49], v[182:185], v[236:239], v[46:49]
	v_mfma_f32_16x16x32_bf16 v[42:45], v[190:193], v[236:239], v[42:45]
	v_mfma_f32_16x16x32_bf16 v[38:41], v[182:185], v[244:247], v[38:41]
	v_mfma_f32_16x16x32_bf16 v[34:37], v[190:193], v[244:247], v[34:37]
	s_barrier
	s_setprio 0
	s_mov_b32 m0, s34
	s_or_b32 s52, s83, 0x80
	ds_read_b128 v[194:197], v140 offset:49152
	ds_read_b128 v[198:201], v140 offset:50176
	ds_read_b128 v[202:205], v140 offset:51200
	ds_read_b128 v[228:231], v140 offset:52224
	ds_read_b128 v[232:235], v140 offset:53248
	ds_read_b128 v[236:239], v140 offset:54272
	ds_read_b128 v[240:243], v140 offset:55296
	ds_read_b128 v[244:247], v140 offset:56320
	buffer_load_dwordx4 v134, s[68:71], s52 offen lds
	s_mov_b32 m0, s35
	s_add_i32 s83, s83, 0x80080
	buffer_load_dwordx4 v136, s[68:71], s52 offen lds
	s_mov_b32 m0, s65
	s_nop 0
	buffer_load_dwordx4 v134, s[68:71], s83 offen lds
	s_mov_b32 m0, s66
	s_nop 0
	buffer_load_dwordx4 v136, s[68:71], s83 offen lds
	s_mov_b32 m0, s36
	s_nop 0
	buffer_load_dwordx4 v131, s[60:63], s27 offen lds
	s_mov_b32 m0, s37
	s_nop 0
	buffer_load_dwordx4 v135, s[60:63], s27 offen lds
	s_waitcnt vmcnt(8)
	s_waitcnt lgkmcnt(0)
	s_setprio 1
	s_barrier
	v_mfma_f32_16x16x32_bf16 v[94:97], v[142:145], v[194:197], v[94:97]
	v_mfma_f32_16x16x32_bf16 v[90:93], v[170:173], v[194:197], v[90:93]
	v_mfma_f32_16x16x32_bf16 v[86:89], v[142:145], v[202:205], v[86:89]
	v_mfma_f32_16x16x32_bf16 v[82:85], v[170:173], v[202:205], v[82:85]
	v_mfma_f32_16x16x32_bf16 v[78:81], v[142:145], v[232:235], v[78:81]
	v_mfma_f32_16x16x32_bf16 v[74:77], v[170:173], v[232:235], v[74:77]
	v_mfma_f32_16x16x32_bf16 v[70:73], v[142:145], v[240:243], v[70:73]
	v_mfma_f32_16x16x32_bf16 v[66:69], v[170:173], v[240:243], v[66:69]
	v_mfma_f32_16x16x32_bf16 v[94:97], v[154:157], v[198:201], v[94:97]
	v_mfma_f32_16x16x32_bf16 v[90:93], v[174:177], v[198:201], v[90:93]
	v_mfma_f32_16x16x32_bf16 v[86:89], v[154:157], v[228:231], v[86:89]
	v_mfma_f32_16x16x32_bf16 v[82:85], v[174:177], v[228:231], v[82:85]
	v_mfma_f32_16x16x32_bf16 v[78:81], v[154:157], v[236:239], v[78:81]
	v_mfma_f32_16x16x32_bf16 v[74:77], v[174:177], v[236:239], v[74:77]
	v_mfma_f32_16x16x32_bf16 v[70:73], v[154:157], v[244:247], v[70:73]
	v_mfma_f32_16x16x32_bf16 v[66:69], v[174:177], v[244:247], v[66:69]
	v_mfma_f32_16x16x32_bf16 v[30:33], v[178:181], v[194:197], v[30:33]
	v_mfma_f32_16x16x32_bf16 v[26:29], v[186:189], v[194:197], v[26:29]
	v_mfma_f32_16x16x32_bf16 v[22:25], v[178:181], v[202:205], v[22:25]
	v_mfma_f32_16x16x32_bf16 v[18:21], v[186:189], v[202:205], v[18:21]
	v_mfma_f32_16x16x32_bf16 v[14:17], v[178:181], v[232:235], v[14:17]
	v_mfma_f32_16x16x32_bf16 v[10:13], v[186:189], v[232:235], v[10:13]
	v_mfma_f32_16x16x32_bf16 v[6:9], v[178:181], v[240:243], v[6:9]
	v_mfma_f32_16x16x32_bf16 v[2:5], v[186:189], v[240:243], v[2:5]
	v_mfma_f32_16x16x32_bf16 v[30:33], v[182:185], v[198:201], v[30:33]
	v_mfma_f32_16x16x32_bf16 v[26:29], v[190:193], v[198:201], v[26:29]
	v_mfma_f32_16x16x32_bf16 v[22:25], v[182:185], v[228:231], v[22:25]
	v_mfma_f32_16x16x32_bf16 v[18:21], v[190:193], v[228:231], v[18:21]
	v_mfma_f32_16x16x32_bf16 v[14:17], v[182:185], v[236:239], v[14:17]
	v_mfma_f32_16x16x32_bf16 v[10:13], v[190:193], v[236:239], v[10:13]
	v_mfma_f32_16x16x32_bf16 v[6:9], v[182:185], v[244:247], v[6:9]
	v_mfma_f32_16x16x32_bf16 v[2:5], v[190:193], v[244:247], v[2:5]
	s_barrier
	s_setprio 0
	s_add_i32 s26, s26, 2
	s_addk_i32 s19, 0x100
	s_addk_i32 s22, 0x100
	s_cmp_gt_u32 s26, 29

.LBB0_1588:
	s_lshl_b32 s85, s84, 20
	s_and_b64 s[8:9], s[42:43], exec
	s_cselect_b32 s8, s85, s13
	s_lshl_b32 s48, s73, 20
	s_and_b64 s[22:23], s[42:43], exec
	s_cselect_b32 s9, s48, s21
	s_add_i32 s13, s13, 0x80080
	s_addk_i32 s21, 0x100
	s_mov_b32 s22, -2
	s_waitcnt lgkmcnt(0)
	v_add_u32_e32 v170, 0x10000, v140
	v_add_u32_e32 v186, 0x14000, v140
	ds_read_b128 v[132:135], v170
	ds_read_b128 v[142:145], v170 offset:1024
	ds_read_b128 v[154:157], v170 offset:2048
	ds_read_b128 v[170:173], v170 offset:3072
	ds_read_b128 v[174:177], v186
	ds_read_b128 v[178:181], v186 offset:1024
	ds_read_b128 v[182:185], v186 offset:2048
	ds_read_b128 v[186:189], v186 offset:3072
	s_add_i32 s23, s13, 0xfff80080
	s_cmp_eq_u32 s22, 28
	s_cselect_b32 s27, s8, s23
	s_cselect_b32 s26, s9, s21
	s_or_b32 s23, s27, 0x80
	s_mov_b32 m0, s70
	ds_read_b128 v[190:193], v141
	ds_read_b128 v[194:197], v141 offset:1024
	ds_read_b128 v[198:201], v141 offset:2048
	ds_read_b128 v[202:205], v141 offset:3072
	ds_read_b128 v[228:231], v141 offset:4096
	ds_read_b128 v[232:235], v141 offset:5120
	ds_read_b128 v[236:239], v141 offset:6144
	ds_read_b128 v[240:243], v141 offset:7168
	buffer_load_dwordx4 v136, s[60:63], s13 offen lds
	s_mov_b32 m0, s72
	s_nop 0
	buffer_load_dwordx4 v138, s[60:63], s13 offen lds
	s_waitcnt vmcnt(8)
	s_waitcnt lgkmcnt(0)
	s_setprio 1
	s_barrier
	v_mfma_f32_16x16x32_bf16 v[126:129], v[132:135], v[190:193], 0
	v_mfma_f32_16x16x32_bf16 v[106:109], v[154:157], v[190:193], 0
	v_mfma_f32_16x16x32_bf16 v[118:121], v[132:135], v[198:201], 0
	v_mfma_f32_16x16x32_bf16 v[114:117], v[154:157], v[198:201], 0
	v_mfma_f32_16x16x32_bf16 v[94:97], v[132:135], v[228:231], 0
	v_mfma_f32_16x16x32_bf16 v[90:93], v[154:157], v[228:231], 0
	v_mfma_f32_16x16x32_bf16 v[78:81], v[132:135], v[236:239], 0
	v_mfma_f32_16x16x32_bf16 v[74:77], v[154:157], v[236:239], 0
	v_mfma_f32_16x16x32_bf16 v[126:129], v[142:145], v[194:197], v[126:129]
	v_mfma_f32_16x16x32_bf16 v[106:109], v[170:173], v[194:197], v[106:109]
	v_mfma_f32_16x16x32_bf16 v[118:121], v[142:145], v[202:205], v[118:121]
	v_mfma_f32_16x16x32_bf16 v[114:117], v[170:173], v[202:205], v[114:117]
	v_mfma_f32_16x16x32_bf16 v[94:97], v[142:145], v[232:235], v[94:97]
	v_mfma_f32_16x16x32_bf16 v[90:93], v[170:173], v[232:235], v[90:93]
	v_mfma_f32_16x16x32_bf16 v[78:81], v[142:145], v[240:243], v[78:81]
	v_mfma_f32_16x16x32_bf16 v[74:77], v[170:173], v[240:243], v[74:77]
	v_mfma_f32_16x16x32_bf16 v[122:125], v[174:177], v[190:193], 0
	v_mfma_f32_16x16x32_bf16 v[110:113], v[182:185], v[190:193], 0
	v_mfma_f32_16x16x32_bf16 v[102:105], v[174:177], v[198:201], 0
	v_mfma_f32_16x16x32_bf16 v[98:101], v[182:185], v[198:201], 0
	v_mfma_f32_16x16x32_bf16 v[86:89], v[174:177], v[228:231], 0
	v_mfma_f32_16x16x32_bf16 v[82:85], v[182:185], v[228:231], 0
	v_mfma_f32_16x16x32_bf16 v[70:73], v[174:177], v[236:239], 0
	v_mfma_f32_16x16x32_bf16 v[66:69], v[182:185], v[236:239], 0
	v_mfma_f32_16x16x32_bf16 v[122:125], v[178:181], v[194:197], v[122:125]
	v_mfma_f32_16x16x32_bf16 v[110:113], v[186:189], v[194:197], v[110:113]
	v_mfma_f32_16x16x32_bf16 v[102:105], v[178:181], v[202:205], v[102:105]
	v_mfma_f32_16x16x32_bf16 v[98:101], v[186:189], v[202:205], v[98:101]
	v_mfma_f32_16x16x32_bf16 v[86:89], v[178:181], v[232:235], v[86:89]
	v_mfma_f32_16x16x32_bf16 v[82:85], v[186:189], v[232:235], v[82:85]
	v_mfma_f32_16x16x32_bf16 v[70:73], v[178:181], v[240:243], v[70:73]
	v_mfma_f32_16x16x32_bf16 v[66:69], v[186:189], v[240:243], v[66:69]
	s_barrier
	s_setprio 0
	s_mov_b32 m0, s15
	s_mov_b32 s46, s62
	s_mov_b32 s47, s63
	ds_read_b128 v[190:193], v141 offset:16384
	ds_read_b128 v[194:197], v141 offset:17408
	ds_read_b128 v[198:201], v141 offset:18432
	ds_read_b128 v[202:205], v141 offset:19456
	ds_read_b128 v[228:231], v141 offset:20480
	ds_read_b128 v[232:235], v141 offset:21504
	ds_read_b128 v[236:239], v141 offset:22528
	ds_read_b128 v[240:243], v141 offset:23552
	buffer_load_dwordx4 v137, s[44:47], s26 offen lds
	s_mov_b32 m0, s16
	s_add_i32 s49, s26, 0x80000
	buffer_load_dwordx4 v139, s[44:47], s26 offen lds
	s_mov_b32 m0, s18
	s_nop 0
	buffer_load_dwordx4 v137, s[44:47], s49 offen lds
	s_mov_b32 m0, s19
	s_nop 0
	buffer_load_dwordx4 v139, s[44:47], s49 offen lds
	s_mov_b32 m0, s14
	s_nop 0
	buffer_load_dwordx4 v136, s[60:63], s27 offen lds
	s_mov_b32 m0, s24
	s_nop 0
	buffer_load_dwordx4 v138, s[60:63], s27 offen lds
	s_waitcnt vmcnt(8)
	s_waitcnt lgkmcnt(0)
	s_setprio 1
	s_barrier
	v_mfma_f32_16x16x32_bf16 v[62:65], v[132:135], v[190:193], 0
	v_mfma_f32_16x16x32_bf16 v[58:61], v[154:157], v[190:193], 0
	v_mfma_f32_16x16x32_bf16 v[46:49], v[132:135], v[198:201], 0
	v_mfma_f32_16x16x32_bf16 v[42:45], v[154:157], v[198:201], 0
	v_mfma_f32_16x16x32_bf16 v[30:33], v[132:135], v[228:231], 0
	v_mfma_f32_16x16x32_bf16 v[26:29], v[154:157], v[228:231], 0
	v_mfma_f32_16x16x32_bf16 v[14:17], v[132:135], v[236:239], 0
	v_mfma_f32_16x16x32_bf16 v[10:13], v[154:157], v[236:239], 0
	v_mfma_f32_16x16x32_bf16 v[62:65], v[142:145], v[194:197], v[62:65]
	v_mfma_f32_16x16x32_bf16 v[58:61], v[170:173], v[194:197], v[58:61]
	v_mfma_f32_16x16x32_bf16 v[46:49], v[142:145], v[202:205], v[46:49]
	v_mfma_f32_16x16x32_bf16 v[42:45], v[170:173], v[202:205], v[42:45]
	v_mfma_f32_16x16x32_bf16 v[30:33], v[142:145], v[232:235], v[30:33]
	v_mfma_f32_16x16x32_bf16 v[26:29], v[170:173], v[232:235], v[26:29]
	v_mfma_f32_16x16x32_bf16 v[14:17], v[142:145], v[240:243], v[14:17]
	v_mfma_f32_16x16x32_bf16 v[10:13], v[170:173], v[240:243], v[10:13]
	v_mfma_f32_16x16x32_bf16 v[54:57], v[174:177], v[190:193], 0
	v_mfma_f32_16x16x32_bf16 v[50:53], v[182:185], v[190:193], 0
	v_mfma_f32_16x16x32_bf16 v[38:41], v[174:177], v[198:201], 0
	v_mfma_f32_16x16x32_bf16 v[34:37], v[182:185], v[198:201], 0
	v_mfma_f32_16x16x32_bf16 v[22:25], v[174:177], v[228:231], 0
	v_mfma_f32_16x16x32_bf16 v[18:21], v[182:185], v[228:231], 0
	v_mfma_f32_16x16x32_bf16 v[6:9], v[174:177], v[236:239], 0
	v_mfma_f32_16x16x32_bf16 v[2:5], v[182:185], v[236:239], 0
	v_mfma_f32_16x16x32_bf16 v[54:57], v[178:181], v[194:197], v[54:57]
	v_mfma_f32_16x16x32_bf16 v[50:53], v[186:189], v[194:197], v[50:53]
	v_mfma_f32_16x16x32_bf16 v[38:41], v[178:181], v[202:205], v[38:41]
	v_mfma_f32_16x16x32_bf16 v[34:37], v[186:189], v[202:205], v[34:37]
	v_mfma_f32_16x16x32_bf16 v[22:25], v[178:181], v[232:235], v[22:25]
	v_mfma_f32_16x16x32_bf16 v[18:21], v[186:189], v[232:235], v[18:21]
	v_mfma_f32_16x16x32_bf16 v[6:9], v[178:181], v[240:243], v[6:9]
	v_mfma_f32_16x16x32_bf16 v[2:5], v[186:189], v[240:243], v[2:5]
	s_barrier
	s_setprio 0
	v_add_u32_e32 v170, 0x18000, v140
	v_add_u32_e32 v186, 0x1c000, v140
	ds_read_b128 v[132:135], v170
	ds_read_b128 v[142:145], v170 offset:1024
	ds_read_b128 v[154:157], v170 offset:2048
	ds_read_b128 v[170:173], v170 offset:3072
	ds_read_b128 v[174:177], v186
	ds_read_b128 v[178:181], v186 offset:1024
	ds_read_b128 v[182:185], v186 offset:2048
	ds_read_b128 v[186:189], v186 offset:3072
	s_add_i32 s27, s27, 0x80000
	s_mov_b32 m0, s25
	ds_read_b128 v[190:193], v141 offset:32768
	ds_read_b128 v[194:197], v141 offset:33792
	ds_read_b128 v[198:201], v141 offset:34816
	ds_read_b128 v[202:205], v141 offset:35840
	ds_read_b128 v[228:231], v141 offset:36864
	ds_read_b128 v[232:235], v141 offset:37888
	ds_read_b128 v[236:239], v141 offset:38912
	ds_read_b128 v[240:243], v141 offset:39936
	buffer_load_dwordx4 v136, s[60:63], s27 offen lds
	s_mov_b32 m0, s30
	s_nop 0
	buffer_load_dwordx4 v138, s[60:63], s27 offen lds
	s_waitcnt vmcnt(8)
	s_waitcnt lgkmcnt(0)
	s_setprio 1
	s_barrier
	v_mfma_f32_16x16x32_bf16 v[126:129], v[132:135], v[190:193], v[126:129]
	v_mfma_f32_16x16x32_bf16 v[106:109], v[154:157], v[190:193], v[106:109]
	v_mfma_f32_16x16x32_bf16 v[118:121], v[132:135], v[198:201], v[118:121]
	v_mfma_f32_16x16x32_bf16 v[114:117], v[154:157], v[198:201], v[114:117]
	v_mfma_f32_16x16x32_bf16 v[94:97], v[132:135], v[228:231], v[94:97]
	v_mfma_f32_16x16x32_bf16 v[90:93], v[154:157], v[228:231], v[90:93]
	v_mfma_f32_16x16x32_bf16 v[78:81], v[132:135], v[236:239], v[78:81]
	v_mfma_f32_16x16x32_bf16 v[74:77], v[154:157], v[236:239], v[74:77]
	v_mfma_f32_16x16x32_bf16 v[126:129], v[142:145], v[194:197], v[126:129]
	v_mfma_f32_16x16x32_bf16 v[106:109], v[170:173], v[194:197], v[106:109]
	v_mfma_f32_16x16x32_bf16 v[118:121], v[142:145], v[202:205], v[118:121]
	v_mfma_f32_16x16x32_bf16 v[114:117], v[170:173], v[202:205], v[114:117]
	v_mfma_f32_16x16x32_bf16 v[94:97], v[142:145], v[232:235], v[94:97]
	v_mfma_f32_16x16x32_bf16 v[90:93], v[170:173], v[232:235], v[90:93]
	v_mfma_f32_16x16x32_bf16 v[78:81], v[142:145], v[240:243], v[78:81]
	v_mfma_f32_16x16x32_bf16 v[74:77], v[170:173], v[240:243], v[74:77]
	v_mfma_f32_16x16x32_bf16 v[122:125], v[174:177], v[190:193], v[122:125]
	v_mfma_f32_16x16x32_bf16 v[110:113], v[182:185], v[190:193], v[110:113]
	v_mfma_f32_16x16x32_bf16 v[102:105], v[174:177], v[198:201], v[102:105]
	v_mfma_f32_16x16x32_bf16 v[98:101], v[182:185], v[198:201], v[98:101]
	v_mfma_f32_16x16x32_bf16 v[86:89], v[174:177], v[228:231], v[86:89]
	v_mfma_f32_16x16x32_bf16 v[82:85], v[182:185], v[228:231], v[82:85]
	v_mfma_f32_16x16x32_bf16 v[70:73], v[174:177], v[236:239], v[70:73]
	v_mfma_f32_16x16x32_bf16 v[66:69], v[182:185], v[236:239], v[66:69]
	v_mfma_f32_16x16x32_bf16 v[122:125], v[178:181], v[194:197], v[122:125]
	v_mfma_f32_16x16x32_bf16 v[110:113], v[186:189], v[194:197], v[110:113]
	v_mfma_f32_16x16x32_bf16 v[102:105], v[178:181], v[202:205], v[102:105]
	v_mfma_f32_16x16x32_bf16 v[98:101], v[186:189], v[202:205], v[98:101]
	v_mfma_f32_16x16x32_bf16 v[86:89], v[178:181], v[232:235], v[86:89]
	v_mfma_f32_16x16x32_bf16 v[82:85], v[186:189], v[232:235], v[82:85]
	v_mfma_f32_16x16x32_bf16 v[70:73], v[178:181], v[240:243], v[70:73]
	v_mfma_f32_16x16x32_bf16 v[66:69], v[186:189], v[240:243], v[66:69]
	s_barrier
	s_setprio 0
	s_mov_b32 m0, s36
	s_or_b32 s27, s26, 0x80
	ds_read_b128 v[190:193], v141 offset:49152
	ds_read_b128 v[194:197], v141 offset:50176
	ds_read_b128 v[198:201], v141 offset:51200
	ds_read_b128 v[202:205], v141 offset:52224
	ds_read_b128 v[228:231], v141 offset:53248
	ds_read_b128 v[232:235], v141 offset:54272
	ds_read_b128 v[236:239], v141 offset:55296
	ds_read_b128 v[240:243], v141 offset:56320
	buffer_load_dwordx4 v137, s[44:47], s27 offen lds
	s_mov_b32 m0, s37
	s_add_i32 s26, s26, 0x80080
	buffer_load_dwordx4 v139, s[44:47], s27 offen lds
	s_mov_b32 m0, s68
	s_nop 0
	buffer_load_dwordx4 v137, s[44:47], s26 offen lds
	s_mov_b32 m0, s69
	s_nop 0
	buffer_load_dwordx4 v139, s[44:47], s26 offen lds
	s_mov_b32 m0, s66
	s_nop 0
	buffer_load_dwordx4 v136, s[60:63], s23 offen lds
	s_mov_b32 m0, s67
	s_nop 0
	buffer_load_dwordx4 v138, s[60:63], s23 offen lds
	s_waitcnt vmcnt(8)
	s_waitcnt lgkmcnt(0)
	s_setprio 1
	s_barrier
	v_mfma_f32_16x16x32_bf16 v[62:65], v[132:135], v[190:193], v[62:65]
	v_mfma_f32_16x16x32_bf16 v[58:61], v[154:157], v[190:193], v[58:61]
	v_mfma_f32_16x16x32_bf16 v[46:49], v[132:135], v[198:201], v[46:49]
	v_mfma_f32_16x16x32_bf16 v[42:45], v[154:157], v[198:201], v[42:45]
	v_mfma_f32_16x16x32_bf16 v[30:33], v[132:135], v[228:231], v[30:33]
	v_mfma_f32_16x16x32_bf16 v[26:29], v[154:157], v[228:231], v[26:29]
	v_mfma_f32_16x16x32_bf16 v[14:17], v[132:135], v[236:239], v[14:17]
	v_mfma_f32_16x16x32_bf16 v[10:13], v[154:157], v[236:239], v[10:13]
	v_mfma_f32_16x16x32_bf16 v[62:65], v[142:145], v[194:197], v[62:65]
	v_mfma_f32_16x16x32_bf16 v[58:61], v[170:173], v[194:197], v[58:61]
	v_mfma_f32_16x16x32_bf16 v[46:49], v[142:145], v[202:205], v[46:49]
	v_mfma_f32_16x16x32_bf16 v[42:45], v[170:173], v[202:205], v[42:45]
	v_mfma_f32_16x16x32_bf16 v[30:33], v[142:145], v[232:235], v[30:33]
	v_mfma_f32_16x16x32_bf16 v[26:29], v[170:173], v[232:235], v[26:29]
	v_mfma_f32_16x16x32_bf16 v[14:17], v[142:145], v[240:243], v[14:17]
	v_mfma_f32_16x16x32_bf16 v[10:13], v[170:173], v[240:243], v[10:13]
	v_mfma_f32_16x16x32_bf16 v[54:57], v[174:177], v[190:193], v[54:57]
	v_mfma_f32_16x16x32_bf16 v[50:53], v[182:185], v[190:193], v[50:53]
	v_mfma_f32_16x16x32_bf16 v[38:41], v[174:177], v[198:201], v[38:41]
	v_mfma_f32_16x16x32_bf16 v[34:37], v[182:185], v[198:201], v[34:37]
	v_mfma_f32_16x16x32_bf16 v[22:25], v[174:177], v[228:231], v[22:25]
	v_mfma_f32_16x16x32_bf16 v[18:21], v[182:185], v[228:231], v[18:21]
	v_mfma_f32_16x16x32_bf16 v[6:9], v[174:177], v[236:239], v[6:9]
	v_mfma_f32_16x16x32_bf16 v[2:5], v[182:185], v[236:239], v[2:5]
	v_mfma_f32_16x16x32_bf16 v[54:57], v[178:181], v[194:197], v[54:57]
	v_mfma_f32_16x16x32_bf16 v[50:53], v[186:189], v[194:197], v[50:53]
	v_mfma_f32_16x16x32_bf16 v[38:41], v[178:181], v[202:205], v[38:41]
	v_mfma_f32_16x16x32_bf16 v[34:37], v[186:189], v[202:205], v[34:37]
	v_mfma_f32_16x16x32_bf16 v[22:25], v[178:181], v[232:235], v[22:25]
	v_mfma_f32_16x16x32_bf16 v[18:21], v[186:189], v[232:235], v[18:21]
	v_mfma_f32_16x16x32_bf16 v[6:9], v[178:181], v[240:243], v[6:9]
	v_mfma_f32_16x16x32_bf16 v[2:5], v[186:189], v[240:243], v[2:5]
	s_barrier
	s_setprio 0
	s_add_i32 s22, s22, 2
	s_addk_i32 s13, 0x100
	s_addk_i32 s21, 0x100
	s_cmp_gt_u32 s22, 29

.LBB0_1879:
	s_lshl_b32 s18, s91, 20
	s_and_b64 s[8:9], s[48:49], exec
	s_cselect_b32 s8, s18, s95
	s_lshl_b32 s19, s92, 20
	s_and_b64 s[42:43], s[48:49], exec
	s_cselect_b32 s9, s19, s94
	s_add_i32 vcc_lo, s95, 0x80080
	s_add_i32 vcc_hi, s94, 0x100
	s_mov_b32 s94, -2
	v_add_u32_e32 v139, 0x10000, v136
	ds_read_b128 v[140:143], v139
	ds_read_b128 v[154:157], v139 offset:1024
	ds_read_b128 v[170:173], v139 offset:2048
	ds_read_b128 v[174:177], v139 offset:3072
	v_add_u32_e32 v139, 0x14000, v136
	ds_read_b128 v[178:181], v139
	ds_read_b128 v[182:185], v139 offset:1024
	ds_read_b128 v[186:189], v139 offset:2048
	ds_read_b128 v[190:193], v139 offset:3072
	s_add_i32 s42, vcc_lo, 0xfff80080
	s_cmp_eq_u32 s94, 28
	s_cselect_b32 s52, s8, s42
	s_cselect_b32 s96, s9, vcc_hi
	s_or_b32 s95, s52, 0x80
	s_mov_b32 m0, s72
	ds_read_b128 v[194:197], v137
	ds_read_b128 v[198:201], v137 offset:1024
	ds_read_b128 v[202:205], v137 offset:2048
	ds_read_b128 v[228:231], v137 offset:3072
	ds_read_b128 v[232:235], v137 offset:4096
	ds_read_b128 v[236:239], v137 offset:5120
	ds_read_b128 v[240:243], v137 offset:6144
	ds_read_b128 v[244:247], v137 offset:7168
	buffer_load_dwordx4 v132, s[60:63], vcc_lo offen lds
	s_mov_b32 m0, s47
	s_nop 0
	buffer_load_dwordx4 v134, s[60:63], vcc_lo offen lds
	s_waitcnt vmcnt(8)
	s_waitcnt lgkmcnt(0)
	s_setprio 1
	s_barrier
	v_mfma_f32_16x16x32_bf16 v[114:117], v[140:143], v[194:197], 0
	v_mfma_f32_16x16x32_bf16 v[110:113], v[170:173], v[194:197], 0
	v_mfma_f32_16x16x32_bf16 v[106:109], v[140:143], v[202:205], 0
	v_mfma_f32_16x16x32_bf16 v[102:105], v[170:173], v[202:205], 0
	v_mfma_f32_16x16x32_bf16 v[94:97], v[140:143], v[232:235], 0
	v_mfma_f32_16x16x32_bf16 v[86:89], v[170:173], v[232:235], 0
	v_mfma_f32_16x16x32_bf16 v[78:81], v[140:143], v[240:243], 0
	v_mfma_f32_16x16x32_bf16 v[70:73], v[170:173], v[240:243], 0
	v_mfma_f32_16x16x32_bf16 v[114:117], v[154:157], v[198:201], v[114:117]
	v_mfma_f32_16x16x32_bf16 v[110:113], v[174:177], v[198:201], v[110:113]
	v_mfma_f32_16x16x32_bf16 v[106:109], v[154:157], v[228:231], v[106:109]
	v_mfma_f32_16x16x32_bf16 v[102:105], v[174:177], v[228:231], v[102:105]
	v_mfma_f32_16x16x32_bf16 v[94:97], v[154:157], v[236:239], v[94:97]
	v_mfma_f32_16x16x32_bf16 v[86:89], v[174:177], v[236:239], v[86:89]
	v_mfma_f32_16x16x32_bf16 v[78:81], v[154:157], v[244:247], v[78:81]
	v_mfma_f32_16x16x32_bf16 v[70:73], v[174:177], v[244:247], v[70:73]
	v_mfma_f32_16x16x32_bf16 v[126:129], v[178:181], v[194:197], 0
	v_mfma_f32_16x16x32_bf16 v[122:125], v[186:189], v[194:197], 0
	v_mfma_f32_16x16x32_bf16 v[118:121], v[178:181], v[202:205], 0
	v_mfma_f32_16x16x32_bf16 v[98:101], v[186:189], v[202:205], 0
	v_mfma_f32_16x16x32_bf16 v[90:93], v[178:181], v[232:235], 0
	v_mfma_f32_16x16x32_bf16 v[82:85], v[186:189], v[232:235], 0
	v_mfma_f32_16x16x32_bf16 v[74:77], v[178:181], v[240:243], 0
	v_mfma_f32_16x16x32_bf16 v[66:69], v[186:189], v[240:243], 0
	v_mfma_f32_16x16x32_bf16 v[126:129], v[182:185], v[198:201], v[126:129]
	v_mfma_f32_16x16x32_bf16 v[122:125], v[190:193], v[198:201], v[122:125]
	v_mfma_f32_16x16x32_bf16 v[118:121], v[182:185], v[228:231], v[118:121]
	v_mfma_f32_16x16x32_bf16 v[98:101], v[190:193], v[228:231], v[98:101]
	v_mfma_f32_16x16x32_bf16 v[90:93], v[182:185], v[236:239], v[90:93]
	v_mfma_f32_16x16x32_bf16 v[82:85], v[190:193], v[236:239], v[82:85]
	v_mfma_f32_16x16x32_bf16 v[74:77], v[182:185], v[244:247], v[74:77]
	v_mfma_f32_16x16x32_bf16 v[66:69], v[190:193], v[244:247], v[66:69]
	s_barrier
	s_setprio 0
	s_mov_b32 m0, s13
	s_mov_b32 s42, s62
	s_mov_b32 s43, s63
	ds_read_b128 v[194:197], v137 offset:16384
	ds_read_b128 v[198:201], v137 offset:17408
	ds_read_b128 v[202:205], v137 offset:18432
	ds_read_b128 v[228:231], v137 offset:19456
	ds_read_b128 v[232:235], v137 offset:20480
	ds_read_b128 v[236:239], v137 offset:21504
	ds_read_b128 v[240:243], v137 offset:22528
	ds_read_b128 v[244:247], v137 offset:23552
	buffer_load_dwordx4 v133, s[40:43], s96 offen lds
	s_mov_b32 m0, s14
	s_add_i32 s53, s96, 0x80000
	buffer_load_dwordx4 v135, s[40:43], s96 offen lds
	s_mov_b32 m0, s15
	s_nop 0
	buffer_load_dwordx4 v133, s[40:43], s53 offen lds
	s_mov_b32 m0, s16
	s_nop 0
	buffer_load_dwordx4 v135, s[40:43], s53 offen lds
	s_mov_b32 m0, s2
	s_nop 0
	buffer_load_dwordx4 v132, s[60:63], s52 offen lds
	s_mov_b32 m0, s21
	s_nop 0
	buffer_load_dwordx4 v134, s[60:63], s52 offen lds
	s_waitcnt vmcnt(8)
	s_waitcnt lgkmcnt(0)
	s_setprio 1
	s_barrier
	v_mfma_f32_16x16x32_bf16 v[62:65], v[140:143], v[194:197], 0
	v_mfma_f32_16x16x32_bf16 v[54:57], v[170:173], v[194:197], 0
	v_mfma_f32_16x16x32_bf16 v[46:49], v[140:143], v[202:205], 0
	v_mfma_f32_16x16x32_bf16 v[38:41], v[170:173], v[202:205], 0
	v_mfma_f32_16x16x32_bf16 v[30:33], v[140:143], v[232:235], 0
	v_mfma_f32_16x16x32_bf16 v[22:25], v[170:173], v[232:235], 0
	v_mfma_f32_16x16x32_bf16 v[14:17], v[140:143], v[240:243], 0
	v_mfma_f32_16x16x32_bf16 v[6:9], v[170:173], v[240:243], 0
	v_mfma_f32_16x16x32_bf16 v[62:65], v[154:157], v[198:201], v[62:65]
	v_mfma_f32_16x16x32_bf16 v[54:57], v[174:177], v[198:201], v[54:57]
	v_mfma_f32_16x16x32_bf16 v[46:49], v[154:157], v[228:231], v[46:49]
	v_mfma_f32_16x16x32_bf16 v[38:41], v[174:177], v[228:231], v[38:41]
	v_mfma_f32_16x16x32_bf16 v[30:33], v[154:157], v[236:239], v[30:33]
	v_mfma_f32_16x16x32_bf16 v[22:25], v[174:177], v[236:239], v[22:25]
	v_mfma_f32_16x16x32_bf16 v[14:17], v[154:157], v[244:247], v[14:17]
	v_mfma_f32_16x16x32_bf16 v[6:9], v[174:177], v[244:247], v[6:9]
	v_mfma_f32_16x16x32_bf16 v[58:61], v[178:181], v[194:197], 0
	v_mfma_f32_16x16x32_bf16 v[50:53], v[186:189], v[194:197], 0
	v_mfma_f32_16x16x32_bf16 v[42:45], v[178:181], v[202:205], 0
	v_mfma_f32_16x16x32_bf16 v[34:37], v[186:189], v[202:205], 0
	v_mfma_f32_16x16x32_bf16 v[26:29], v[178:181], v[232:235], 0
	v_mfma_f32_16x16x32_bf16 v[18:21], v[186:189], v[232:235], 0
	v_mfma_f32_16x16x32_bf16 v[10:13], v[178:181], v[240:243], 0
	v_mfma_f32_16x16x32_bf16 v[2:5], v[186:189], v[240:243], 0
	v_mfma_f32_16x16x32_bf16 v[58:61], v[182:185], v[198:201], v[58:61]
	v_mfma_f32_16x16x32_bf16 v[50:53], v[190:193], v[198:201], v[50:53]
	v_mfma_f32_16x16x32_bf16 v[42:45], v[182:185], v[228:231], v[42:45]
	v_mfma_f32_16x16x32_bf16 v[34:37], v[190:193], v[228:231], v[34:37]
	v_mfma_f32_16x16x32_bf16 v[26:29], v[182:185], v[236:239], v[26:29]
	v_mfma_f32_16x16x32_bf16 v[18:21], v[190:193], v[236:239], v[18:21]
	v_mfma_f32_16x16x32_bf16 v[10:13], v[182:185], v[244:247], v[10:13]
	v_mfma_f32_16x16x32_bf16 v[2:5], v[190:193], v[244:247], v[2:5]
	s_barrier
	s_setprio 0
	v_add_u32_e32 v139, 0x18000, v136
	ds_read_b128 v[140:143], v139
	ds_read_b128 v[154:157], v139 offset:1024
	ds_read_b128 v[170:173], v139 offset:2048
	ds_read_b128 v[174:177], v139 offset:3072
	v_add_u32_e32 v139, 0x1c000, v136
	ds_read_b128 v[178:181], v139
	ds_read_b128 v[182:185], v139 offset:1024
	ds_read_b128 v[186:189], v139 offset:2048
	ds_read_b128 v[190:193], v139 offset:3072
	s_add_i32 s52, s52, 0x80000
	s_mov_b32 m0, s23
	ds_read_b128 v[194:197], v137 offset:32768
	ds_read_b128 v[198:201], v137 offset:33792
	ds_read_b128 v[202:205], v137 offset:34816
	ds_read_b128 v[228:231], v137 offset:35840
	ds_read_b128 v[232:235], v137 offset:36864
	ds_read_b128 v[236:239], v137 offset:37888
	ds_read_b128 v[240:243], v137 offset:38912
	ds_read_b128 v[244:247], v137 offset:39936
	buffer_load_dwordx4 v132, s[60:63], s52 offen lds
	s_mov_b32 m0, s24
	s_nop 0
	buffer_load_dwordx4 v134, s[60:63], s52 offen lds
	s_waitcnt vmcnt(8)
	s_waitcnt lgkmcnt(0)
	s_setprio 1
	s_barrier
	v_mfma_f32_16x16x32_bf16 v[114:117], v[140:143], v[194:197], v[114:117]
	v_mfma_f32_16x16x32_bf16 v[110:113], v[170:173], v[194:197], v[110:113]
	v_mfma_f32_16x16x32_bf16 v[106:109], v[140:143], v[202:205], v[106:109]
	v_mfma_f32_16x16x32_bf16 v[102:105], v[170:173], v[202:205], v[102:105]
	v_mfma_f32_16x16x32_bf16 v[94:97], v[140:143], v[232:235], v[94:97]
	v_mfma_f32_16x16x32_bf16 v[86:89], v[170:173], v[232:235], v[86:89]
	v_mfma_f32_16x16x32_bf16 v[78:81], v[140:143], v[240:243], v[78:81]
	v_mfma_f32_16x16x32_bf16 v[70:73], v[170:173], v[240:243], v[70:73]
	v_mfma_f32_16x16x32_bf16 v[114:117], v[154:157], v[198:201], v[114:117]
	v_mfma_f32_16x16x32_bf16 v[110:113], v[174:177], v[198:201], v[110:113]
	v_mfma_f32_16x16x32_bf16 v[106:109], v[154:157], v[228:231], v[106:109]
	v_mfma_f32_16x16x32_bf16 v[102:105], v[174:177], v[228:231], v[102:105]
	v_mfma_f32_16x16x32_bf16 v[94:97], v[154:157], v[236:239], v[94:97]
	v_mfma_f32_16x16x32_bf16 v[86:89], v[174:177], v[236:239], v[86:89]
	v_mfma_f32_16x16x32_bf16 v[78:81], v[154:157], v[244:247], v[78:81]
	v_mfma_f32_16x16x32_bf16 v[70:73], v[174:177], v[244:247], v[70:73]
	v_mfma_f32_16x16x32_bf16 v[126:129], v[178:181], v[194:197], v[126:129]
	v_mfma_f32_16x16x32_bf16 v[122:125], v[186:189], v[194:197], v[122:125]
	v_mfma_f32_16x16x32_bf16 v[118:121], v[178:181], v[202:205], v[118:121]
	v_mfma_f32_16x16x32_bf16 v[98:101], v[186:189], v[202:205], v[98:101]
	v_mfma_f32_16x16x32_bf16 v[90:93], v[178:181], v[232:235], v[90:93]
	v_mfma_f32_16x16x32_bf16 v[82:85], v[186:189], v[232:235], v[82:85]
	v_mfma_f32_16x16x32_bf16 v[74:77], v[178:181], v[240:243], v[74:77]
	v_mfma_f32_16x16x32_bf16 v[66:69], v[186:189], v[240:243], v[66:69]
	v_mfma_f32_16x16x32_bf16 v[126:129], v[182:185], v[198:201], v[126:129]
	v_mfma_f32_16x16x32_bf16 v[122:125], v[190:193], v[198:201], v[122:125]
	v_mfma_f32_16x16x32_bf16 v[118:121], v[182:185], v[228:231], v[118:121]
	v_mfma_f32_16x16x32_bf16 v[98:101], v[190:193], v[228:231], v[98:101]
	v_mfma_f32_16x16x32_bf16 v[90:93], v[182:185], v[236:239], v[90:93]
	v_mfma_f32_16x16x32_bf16 v[82:85], v[190:193], v[236:239], v[82:85]
	v_mfma_f32_16x16x32_bf16 v[74:77], v[182:185], v[244:247], v[74:77]
	v_mfma_f32_16x16x32_bf16 v[66:69], v[190:193], v[244:247], v[66:69]
	s_barrier
	s_setprio 0
	s_mov_b32 m0, s31
	s_or_b32 s52, s96, 0x80
	ds_read_b128 v[194:197], v137 offset:49152
	ds_read_b128 v[198:201], v137 offset:50176
	ds_read_b128 v[202:205], v137 offset:51200
	ds_read_b128 v[228:231], v137 offset:52224
	ds_read_b128 v[232:235], v137 offset:53248
	ds_read_b128 v[236:239], v137 offset:54272
	ds_read_b128 v[240:243], v137 offset:55296
	ds_read_b128 v[244:247], v137 offset:56320
	buffer_load_dwordx4 v133, s[40:43], s52 offen lds
	s_mov_b32 m0, s33
	s_add_i32 s96, s96, 0x80080
	buffer_load_dwordx4 v135, s[40:43], s52 offen lds
	s_mov_b32 m0, s36
	s_nop 0
	buffer_load_dwordx4 v133, s[40:43], s96 offen lds
	s_mov_b32 m0, s37
	s_nop 0
	buffer_load_dwordx4 v135, s[40:43], s96 offen lds
	s_mov_b32 m0, s34
	s_nop 0
	buffer_load_dwordx4 v132, s[60:63], s95 offen lds
	s_mov_b32 m0, s35
	s_nop 0
	buffer_load_dwordx4 v134, s[60:63], s95 offen lds
	s_waitcnt vmcnt(8)
	s_waitcnt lgkmcnt(0)
	s_setprio 1
	s_barrier
	v_mfma_f32_16x16x32_bf16 v[62:65], v[140:143], v[194:197], v[62:65]
	v_mfma_f32_16x16x32_bf16 v[54:57], v[170:173], v[194:197], v[54:57]
	v_mfma_f32_16x16x32_bf16 v[46:49], v[140:143], v[202:205], v[46:49]
	v_mfma_f32_16x16x32_bf16 v[38:41], v[170:173], v[202:205], v[38:41]
	v_mfma_f32_16x16x32_bf16 v[30:33], v[140:143], v[232:235], v[30:33]
	v_mfma_f32_16x16x32_bf16 v[22:25], v[170:173], v[232:235], v[22:25]
	v_mfma_f32_16x16x32_bf16 v[14:17], v[140:143], v[240:243], v[14:17]
	v_mfma_f32_16x16x32_bf16 v[6:9], v[170:173], v[240:243], v[6:9]
	v_mfma_f32_16x16x32_bf16 v[62:65], v[154:157], v[198:201], v[62:65]
	v_mfma_f32_16x16x32_bf16 v[54:57], v[174:177], v[198:201], v[54:57]
	v_mfma_f32_16x16x32_bf16 v[46:49], v[154:157], v[228:231], v[46:49]
	v_mfma_f32_16x16x32_bf16 v[38:41], v[174:177], v[228:231], v[38:41]
	v_mfma_f32_16x16x32_bf16 v[30:33], v[154:157], v[236:239], v[30:33]
	v_mfma_f32_16x16x32_bf16 v[22:25], v[174:177], v[236:239], v[22:25]
	v_mfma_f32_16x16x32_bf16 v[14:17], v[154:157], v[244:247], v[14:17]
	v_mfma_f32_16x16x32_bf16 v[6:9], v[174:177], v[244:247], v[6:9]
	v_mfma_f32_16x16x32_bf16 v[58:61], v[178:181], v[194:197], v[58:61]
	v_mfma_f32_16x16x32_bf16 v[50:53], v[186:189], v[194:197], v[50:53]
	v_mfma_f32_16x16x32_bf16 v[42:45], v[178:181], v[202:205], v[42:45]
	v_mfma_f32_16x16x32_bf16 v[34:37], v[186:189], v[202:205], v[34:37]
	v_mfma_f32_16x16x32_bf16 v[26:29], v[178:181], v[232:235], v[26:29]
	v_mfma_f32_16x16x32_bf16 v[18:21], v[186:189], v[232:235], v[18:21]
	v_mfma_f32_16x16x32_bf16 v[10:13], v[178:181], v[240:243], v[10:13]
	v_mfma_f32_16x16x32_bf16 v[2:5], v[186:189], v[240:243], v[2:5]
	v_mfma_f32_16x16x32_bf16 v[58:61], v[182:185], v[198:201], v[58:61]
	v_mfma_f32_16x16x32_bf16 v[50:53], v[190:193], v[198:201], v[50:53]
	v_mfma_f32_16x16x32_bf16 v[42:45], v[182:185], v[228:231], v[42:45]
	v_mfma_f32_16x16x32_bf16 v[34:37], v[190:193], v[228:231], v[34:37]
	v_mfma_f32_16x16x32_bf16 v[26:29], v[182:185], v[236:239], v[26:29]
	v_mfma_f32_16x16x32_bf16 v[18:21], v[190:193], v[236:239], v[18:21]
	v_mfma_f32_16x16x32_bf16 v[10:13], v[182:185], v[244:247], v[10:13]
	v_mfma_f32_16x16x32_bf16 v[2:5], v[190:193], v[244:247], v[2:5]
	s_barrier
	s_setprio 0
	s_add_i32 s94, s94, 2
	s_addk_i32 vcc_lo, 0x100
	s_addk_i32 vcc_hi, 0x100
	s_cmp_gt_u32 s94, 29

.LBB0_2155:
	s_mul_i32 s49, s48, 0x2c0000
	s_and_b64 s[8:9], s[42:43], exec
	s_mul_i32 s23, s15, 0x2c0000
	s_cselect_b32 s8, s49, s21
	s_cselect_b32 s9, s23, s13
	s_addk_i32 s13, 0x100
	s_add_i32 s21, s21, 0xc000
	s_mov_b32 s22, -2
	s_waitcnt lgkmcnt(0)
	v_add_u32_e32 v170, 0x10000, v140
	v_add_u32_e32 v186, 0x14000, v140
	ds_read_b128 v[132:135], v170
	ds_read_b128 v[142:145], v170 offset:1024
	ds_read_b128 v[154:157], v170 offset:2048
	ds_read_b128 v[170:173], v170 offset:3072
	ds_read_b128 v[174:177], v186
	ds_read_b128 v[178:181], v186 offset:1024
	ds_read_b128 v[182:185], v186 offset:2048
	ds_read_b128 v[186:189], v186 offset:3072
	s_add_i32 s26, s21, 0x4000
	s_cmpk_eq_i32 s22, 0x54
	s_cselect_b32 s52, s8, s26
	s_cselect_b32 s27, s9, s13
	s_or_b32 s26, s52, 0x8000
	s_mov_b32 m0, s84
	ds_read_b128 v[190:193], v141
	ds_read_b128 v[194:197], v141 offset:1024
	ds_read_b128 v[198:201], v141 offset:2048
	ds_read_b128 v[202:205], v141 offset:3072
	ds_read_b128 v[228:231], v141 offset:4096
	ds_read_b128 v[232:235], v141 offset:5120
	ds_read_b128 v[236:239], v141 offset:6144
	ds_read_b128 v[240:243], v141 offset:7168
	buffer_load_dwordx4 v136, s[60:63], s21 offen lds
	s_mov_b32 m0, s16
	s_nop 0
	buffer_load_dwordx4 v138, s[60:63], s21 offen lds
	s_waitcnt vmcnt(8)
	s_waitcnt lgkmcnt(0)
	s_setprio 1
	s_barrier
	v_mfma_f32_16x16x32_bf16 v[126:129], v[132:135], v[190:193], 0
	v_mfma_f32_16x16x32_bf16 v[106:109], v[154:157], v[190:193], 0
	v_mfma_f32_16x16x32_bf16 v[118:121], v[132:135], v[198:201], 0
	v_mfma_f32_16x16x32_bf16 v[114:117], v[154:157], v[198:201], 0
	v_mfma_f32_16x16x32_bf16 v[94:97], v[132:135], v[228:231], 0
	v_mfma_f32_16x16x32_bf16 v[90:93], v[154:157], v[228:231], 0
	v_mfma_f32_16x16x32_bf16 v[78:81], v[132:135], v[236:239], 0
	v_mfma_f32_16x16x32_bf16 v[74:77], v[154:157], v[236:239], 0
	v_mfma_f32_16x16x32_bf16 v[126:129], v[142:145], v[194:197], v[126:129]
	v_mfma_f32_16x16x32_bf16 v[106:109], v[170:173], v[194:197], v[106:109]
	v_mfma_f32_16x16x32_bf16 v[118:121], v[142:145], v[202:205], v[118:121]
	v_mfma_f32_16x16x32_bf16 v[114:117], v[170:173], v[202:205], v[114:117]
	v_mfma_f32_16x16x32_bf16 v[94:97], v[142:145], v[232:235], v[94:97]
	v_mfma_f32_16x16x32_bf16 v[90:93], v[170:173], v[232:235], v[90:93]
	v_mfma_f32_16x16x32_bf16 v[78:81], v[142:145], v[240:243], v[78:81]
	v_mfma_f32_16x16x32_bf16 v[74:77], v[170:173], v[240:243], v[74:77]
	v_mfma_f32_16x16x32_bf16 v[122:125], v[174:177], v[190:193], 0
	v_mfma_f32_16x16x32_bf16 v[110:113], v[182:185], v[190:193], 0
	v_mfma_f32_16x16x32_bf16 v[102:105], v[174:177], v[198:201], 0
	v_mfma_f32_16x16x32_bf16 v[98:101], v[182:185], v[198:201], 0
	v_mfma_f32_16x16x32_bf16 v[86:89], v[174:177], v[228:231], 0
	v_mfma_f32_16x16x32_bf16 v[82:85], v[182:185], v[228:231], 0
	v_mfma_f32_16x16x32_bf16 v[70:73], v[174:177], v[236:239], 0
	v_mfma_f32_16x16x32_bf16 v[66:69], v[182:185], v[236:239], 0
	v_mfma_f32_16x16x32_bf16 v[122:125], v[178:181], v[194:197], v[122:125]
	v_mfma_f32_16x16x32_bf16 v[110:113], v[186:189], v[194:197], v[110:113]
	v_mfma_f32_16x16x32_bf16 v[102:105], v[178:181], v[202:205], v[102:105]
	v_mfma_f32_16x16x32_bf16 v[98:101], v[186:189], v[202:205], v[98:101]
	v_mfma_f32_16x16x32_bf16 v[86:89], v[178:181], v[232:235], v[86:89]
	v_mfma_f32_16x16x32_bf16 v[82:85], v[186:189], v[232:235], v[82:85]
	v_mfma_f32_16x16x32_bf16 v[70:73], v[178:181], v[240:243], v[70:73]
	v_mfma_f32_16x16x32_bf16 v[66:69], v[186:189], v[240:243], v[66:69]
	s_barrier
	s_setprio 0
	s_mov_b32 m0, s18
	s_mov_b32 s46, s62
	s_mov_b32 s47, s63
	ds_read_b128 v[190:193], v141 offset:16384
	ds_read_b128 v[194:197], v141 offset:17408
	ds_read_b128 v[198:201], v141 offset:18432
	ds_read_b128 v[202:205], v141 offset:19456
	ds_read_b128 v[228:231], v141 offset:20480
	ds_read_b128 v[232:235], v141 offset:21504
	ds_read_b128 v[236:239], v141 offset:22528
	ds_read_b128 v[240:243], v141 offset:23552
	buffer_load_dwordx4 v137, s[44:47], s27 offen lds
	s_mov_b32 m0, s19
	s_add_i32 s53, s27, 0x160000
	buffer_load_dwordx4 v139, s[44:47], s27 offen lds
	s_mov_b32 m0, s24
	s_nop 0
	buffer_load_dwordx4 v137, s[44:47], s53 offen lds
	s_mov_b32 m0, s25
	s_nop 0
	buffer_load_dwordx4 v139, s[44:47], s53 offen lds
	s_mov_b32 m0, s14
	s_nop 0
	buffer_load_dwordx4 v136, s[60:63], s52 offen lds
	s_mov_b32 m0, s30
	s_nop 0
	buffer_load_dwordx4 v138, s[60:63], s52 offen lds
	s_waitcnt vmcnt(8)
	s_waitcnt lgkmcnt(0)
	s_setprio 1
	s_barrier
	v_mfma_f32_16x16x32_bf16 v[62:65], v[132:135], v[190:193], 0
	v_mfma_f32_16x16x32_bf16 v[58:61], v[154:157], v[190:193], 0
	v_mfma_f32_16x16x32_bf16 v[46:49], v[132:135], v[198:201], 0
	v_mfma_f32_16x16x32_bf16 v[42:45], v[154:157], v[198:201], 0
	v_mfma_f32_16x16x32_bf16 v[30:33], v[132:135], v[228:231], 0
	v_mfma_f32_16x16x32_bf16 v[26:29], v[154:157], v[228:231], 0
	v_mfma_f32_16x16x32_bf16 v[14:17], v[132:135], v[236:239], 0
	v_mfma_f32_16x16x32_bf16 v[10:13], v[154:157], v[236:239], 0
	v_mfma_f32_16x16x32_bf16 v[62:65], v[142:145], v[194:197], v[62:65]
	v_mfma_f32_16x16x32_bf16 v[58:61], v[170:173], v[194:197], v[58:61]
	v_mfma_f32_16x16x32_bf16 v[46:49], v[142:145], v[202:205], v[46:49]
	v_mfma_f32_16x16x32_bf16 v[42:45], v[170:173], v[202:205], v[42:45]
	v_mfma_f32_16x16x32_bf16 v[30:33], v[142:145], v[232:235], v[30:33]
	v_mfma_f32_16x16x32_bf16 v[26:29], v[170:173], v[232:235], v[26:29]
	v_mfma_f32_16x16x32_bf16 v[14:17], v[142:145], v[240:243], v[14:17]
	v_mfma_f32_16x16x32_bf16 v[10:13], v[170:173], v[240:243], v[10:13]
	v_mfma_f32_16x16x32_bf16 v[54:57], v[174:177], v[190:193], 0
	v_mfma_f32_16x16x32_bf16 v[50:53], v[182:185], v[190:193], 0
	v_mfma_f32_16x16x32_bf16 v[38:41], v[174:177], v[198:201], 0
	v_mfma_f32_16x16x32_bf16 v[34:37], v[182:185], v[198:201], 0
	v_mfma_f32_16x16x32_bf16 v[22:25], v[174:177], v[228:231], 0
	v_mfma_f32_16x16x32_bf16 v[18:21], v[182:185], v[228:231], 0
	v_mfma_f32_16x16x32_bf16 v[6:9], v[174:177], v[236:239], 0
	v_mfma_f32_16x16x32_bf16 v[2:5], v[182:185], v[236:239], 0
	v_mfma_f32_16x16x32_bf16 v[54:57], v[178:181], v[194:197], v[54:57]
	v_mfma_f32_16x16x32_bf16 v[50:53], v[186:189], v[194:197], v[50:53]
	v_mfma_f32_16x16x32_bf16 v[38:41], v[178:181], v[202:205], v[38:41]
	v_mfma_f32_16x16x32_bf16 v[34:37], v[186:189], v[202:205], v[34:37]
	v_mfma_f32_16x16x32_bf16 v[22:25], v[178:181], v[232:235], v[22:25]
	v_mfma_f32_16x16x32_bf16 v[18:21], v[186:189], v[232:235], v[18:21]
	v_mfma_f32_16x16x32_bf16 v[6:9], v[178:181], v[240:243], v[6:9]
	v_mfma_f32_16x16x32_bf16 v[2:5], v[186:189], v[240:243], v[2:5]
	s_barrier
	s_setprio 0
	v_add_u32_e32 v170, 0x18000, v140
	v_add_u32_e32 v186, 0x1c000, v140
	ds_read_b128 v[132:135], v170
	ds_read_b128 v[142:145], v170 offset:1024
	ds_read_b128 v[154:157], v170 offset:2048
	ds_read_b128 v[170:173], v170 offset:3072
	ds_read_b128 v[174:177], v186
	ds_read_b128 v[178:181], v186 offset:1024
	ds_read_b128 v[182:185], v186 offset:2048
	ds_read_b128 v[186:189], v186 offset:3072
	s_bitset1_b32 s52, 14
	s_mov_b32 m0, s31
	ds_read_b128 v[190:193], v141 offset:32768
	ds_read_b128 v[194:197], v141 offset:33792
	ds_read_b128 v[198:201], v141 offset:34816
	ds_read_b128 v[202:205], v141 offset:35840
	ds_read_b128 v[228:231], v141 offset:36864
	ds_read_b128 v[232:235], v141 offset:37888
	ds_read_b128 v[236:239], v141 offset:38912
	ds_read_b128 v[240:243], v141 offset:39936
	buffer_load_dwordx4 v136, s[60:63], s52 offen lds
	s_mov_b32 m0, s33
	s_nop 0
	buffer_load_dwordx4 v138, s[60:63], s52 offen lds
	s_waitcnt vmcnt(8)
	s_waitcnt lgkmcnt(0)
	s_setprio 1
	s_barrier
	v_mfma_f32_16x16x32_bf16 v[126:129], v[132:135], v[190:193], v[126:129]
	v_mfma_f32_16x16x32_bf16 v[106:109], v[154:157], v[190:193], v[106:109]
	v_mfma_f32_16x16x32_bf16 v[118:121], v[132:135], v[198:201], v[118:121]
	v_mfma_f32_16x16x32_bf16 v[114:117], v[154:157], v[198:201], v[114:117]
	v_mfma_f32_16x16x32_bf16 v[94:97], v[132:135], v[228:231], v[94:97]
	v_mfma_f32_16x16x32_bf16 v[90:93], v[154:157], v[228:231], v[90:93]
	v_mfma_f32_16x16x32_bf16 v[78:81], v[132:135], v[236:239], v[78:81]
	v_mfma_f32_16x16x32_bf16 v[74:77], v[154:157], v[236:239], v[74:77]
	v_mfma_f32_16x16x32_bf16 v[126:129], v[142:145], v[194:197], v[126:129]
	v_mfma_f32_16x16x32_bf16 v[106:109], v[170:173], v[194:197], v[106:109]
	v_mfma_f32_16x16x32_bf16 v[118:121], v[142:145], v[202:205], v[118:121]
	v_mfma_f32_16x16x32_bf16 v[114:117], v[170:173], v[202:205], v[114:117]
	v_mfma_f32_16x16x32_bf16 v[94:97], v[142:145], v[232:235], v[94:97]
	v_mfma_f32_16x16x32_bf16 v[90:93], v[170:173], v[232:235], v[90:93]
	v_mfma_f32_16x16x32_bf16 v[78:81], v[142:145], v[240:243], v[78:81]
	v_mfma_f32_16x16x32_bf16 v[74:77], v[170:173], v[240:243], v[74:77]
	v_mfma_f32_16x16x32_bf16 v[122:125], v[174:177], v[190:193], v[122:125]
	v_mfma_f32_16x16x32_bf16 v[110:113], v[182:185], v[190:193], v[110:113]
	v_mfma_f32_16x16x32_bf16 v[102:105], v[174:177], v[198:201], v[102:105]
	v_mfma_f32_16x16x32_bf16 v[98:101], v[182:185], v[198:201], v[98:101]
	v_mfma_f32_16x16x32_bf16 v[86:89], v[174:177], v[228:231], v[86:89]
	v_mfma_f32_16x16x32_bf16 v[82:85], v[182:185], v[228:231], v[82:85]
	v_mfma_f32_16x16x32_bf16 v[70:73], v[174:177], v[236:239], v[70:73]
	v_mfma_f32_16x16x32_bf16 v[66:69], v[182:185], v[236:239], v[66:69]
	v_mfma_f32_16x16x32_bf16 v[122:125], v[178:181], v[194:197], v[122:125]
	v_mfma_f32_16x16x32_bf16 v[110:113], v[186:189], v[194:197], v[110:113]
	v_mfma_f32_16x16x32_bf16 v[102:105], v[178:181], v[202:205], v[102:105]
	v_mfma_f32_16x16x32_bf16 v[98:101], v[186:189], v[202:205], v[98:101]
	v_mfma_f32_16x16x32_bf16 v[86:89], v[178:181], v[232:235], v[86:89]
	v_mfma_f32_16x16x32_bf16 v[82:85], v[186:189], v[232:235], v[82:85]
	v_mfma_f32_16x16x32_bf16 v[70:73], v[178:181], v[240:243], v[70:73]
	v_mfma_f32_16x16x32_bf16 v[66:69], v[186:189], v[240:243], v[66:69]
	s_barrier
	s_setprio 0
	s_mov_b32 m0, s68
	s_or_b32 s52, s27, 0x80
	ds_read_b128 v[190:193], v141 offset:49152
	ds_read_b128 v[194:197], v141 offset:50176
	ds_read_b128 v[198:201], v141 offset:51200
	ds_read_b128 v[202:205], v141 offset:52224
	ds_read_b128 v[228:231], v141 offset:53248
	ds_read_b128 v[232:235], v141 offset:54272
	ds_read_b128 v[236:239], v141 offset:55296
	ds_read_b128 v[240:243], v141 offset:56320
	buffer_load_dwordx4 v137, s[44:47], s52 offen lds
	s_mov_b32 m0, s69
	s_add_i32 s27, s27, 0x160080
	buffer_load_dwordx4 v139, s[44:47], s52 offen lds
	s_mov_b32 m0, s72
	s_nop 0
	buffer_load_dwordx4 v137, s[44:47], s27 offen lds
	s_mov_b32 m0, s73
	s_nop 0
	buffer_load_dwordx4 v139, s[44:47], s27 offen lds
	s_mov_b32 m0, s70
	s_nop 0
	buffer_load_dwordx4 v136, s[60:63], s26 offen lds
	s_mov_b32 m0, s71
	s_nop 0
	buffer_load_dwordx4 v138, s[60:63], s26 offen lds
	s_waitcnt vmcnt(8)
	s_waitcnt lgkmcnt(0)
	s_setprio 1
	s_barrier
	v_mfma_f32_16x16x32_bf16 v[62:65], v[132:135], v[190:193], v[62:65]
	v_mfma_f32_16x16x32_bf16 v[58:61], v[154:157], v[190:193], v[58:61]
	v_mfma_f32_16x16x32_bf16 v[46:49], v[132:135], v[198:201], v[46:49]
	v_mfma_f32_16x16x32_bf16 v[42:45], v[154:157], v[198:201], v[42:45]
	v_mfma_f32_16x16x32_bf16 v[30:33], v[132:135], v[228:231], v[30:33]
	v_mfma_f32_16x16x32_bf16 v[26:29], v[154:157], v[228:231], v[26:29]
	v_mfma_f32_16x16x32_bf16 v[14:17], v[132:135], v[236:239], v[14:17]
	v_mfma_f32_16x16x32_bf16 v[10:13], v[154:157], v[236:239], v[10:13]
	v_mfma_f32_16x16x32_bf16 v[62:65], v[142:145], v[194:197], v[62:65]
	v_mfma_f32_16x16x32_bf16 v[58:61], v[170:173], v[194:197], v[58:61]
	v_mfma_f32_16x16x32_bf16 v[46:49], v[142:145], v[202:205], v[46:49]
	v_mfma_f32_16x16x32_bf16 v[42:45], v[170:173], v[202:205], v[42:45]
	v_mfma_f32_16x16x32_bf16 v[30:33], v[142:145], v[232:235], v[30:33]
	v_mfma_f32_16x16x32_bf16 v[26:29], v[170:173], v[232:235], v[26:29]
	v_mfma_f32_16x16x32_bf16 v[14:17], v[142:145], v[240:243], v[14:17]
	v_mfma_f32_16x16x32_bf16 v[10:13], v[170:173], v[240:243], v[10:13]
	v_mfma_f32_16x16x32_bf16 v[54:57], v[174:177], v[190:193], v[54:57]
	v_mfma_f32_16x16x32_bf16 v[50:53], v[182:185], v[190:193], v[50:53]
	v_mfma_f32_16x16x32_bf16 v[38:41], v[174:177], v[198:201], v[38:41]
	v_mfma_f32_16x16x32_bf16 v[34:37], v[182:185], v[198:201], v[34:37]
	v_mfma_f32_16x16x32_bf16 v[22:25], v[174:177], v[228:231], v[22:25]
	v_mfma_f32_16x16x32_bf16 v[18:21], v[182:185], v[228:231], v[18:21]
	v_mfma_f32_16x16x32_bf16 v[6:9], v[174:177], v[236:239], v[6:9]
	v_mfma_f32_16x16x32_bf16 v[2:5], v[182:185], v[236:239], v[2:5]
	v_mfma_f32_16x16x32_bf16 v[54:57], v[178:181], v[194:197], v[54:57]
	v_mfma_f32_16x16x32_bf16 v[50:53], v[186:189], v[194:197], v[50:53]
	v_mfma_f32_16x16x32_bf16 v[38:41], v[178:181], v[202:205], v[38:41]
	v_mfma_f32_16x16x32_bf16 v[34:37], v[186:189], v[202:205], v[34:37]
	v_mfma_f32_16x16x32_bf16 v[22:25], v[178:181], v[232:235], v[22:25]
	v_mfma_f32_16x16x32_bf16 v[18:21], v[186:189], v[232:235], v[18:21]
	v_mfma_f32_16x16x32_bf16 v[6:9], v[178:181], v[240:243], v[6:9]
	v_mfma_f32_16x16x32_bf16 v[2:5], v[186:189], v[240:243], v[2:5]
	s_barrier
	s_setprio 0
	s_addk_i32 s13, 0x100
	s_add_i32 s22, s22, 2
	s_add_i32 s21, s21, 0x10000
	s_cmpk_gt_u32 s22, 0x55

.LBB0_2173:
	v_mov_b32_e32 v125, 0
	s_mul_i32 s69, s68, s12
	s_mul_i32 s70, s67, s12
	s_andn2_b64 vcc, exec, s[34:35]
	v_mov_b32_e32 v124, v125
	v_mov_b32_e32 v123, v125
	v_mov_b32_e32 v122, v125
	v_mov_b32_e32 v129, v125
	v_mov_b32_e32 v128, v125
	v_mov_b32_e32 v127, v125
	v_mov_b32_e32 v126, v125
	v_mov_b32_e32 v113, v125
	v_mov_b32_e32 v112, v125
	v_mov_b32_e32 v111, v125
	v_mov_b32_e32 v110, v125
	v_mov_b32_e32 v109, v125
	v_mov_b32_e32 v108, v125
	v_mov_b32_e32 v107, v125
	v_mov_b32_e32 v106, v125
	v_mov_b32_e32 v97, v125
	v_mov_b32_e32 v96, v125
	v_mov_b32_e32 v95, v125
	v_mov_b32_e32 v94, v125
	v_mov_b32_e32 v93, v125
	v_mov_b32_e32 v92, v125
	v_mov_b32_e32 v91, v125
	v_mov_b32_e32 v90, v125
	v_mov_b32_e32 v81, v125
	v_mov_b32_e32 v80, v125
	v_mov_b32_e32 v79, v125
	v_mov_b32_e32 v78, v125
	v_mov_b32_e32 v77, v125
	v_mov_b32_e32 v76, v125
	v_mov_b32_e32 v75, v125
	v_mov_b32_e32 v74, v125
	v_mov_b32_e32 v121, v125
	v_mov_b32_e32 v120, v125
	v_mov_b32_e32 v119, v125
	v_mov_b32_e32 v118, v125
	v_mov_b32_e32 v117, v125
	v_mov_b32_e32 v116, v125
	v_mov_b32_e32 v115, v125
	v_mov_b32_e32 v114, v125
	v_mov_b32_e32 v105, v125
	v_mov_b32_e32 v104, v125
	v_mov_b32_e32 v103, v125
	v_mov_b32_e32 v102, v125
	v_mov_b32_e32 v101, v125
	v_mov_b32_e32 v100, v125
	v_mov_b32_e32 v99, v125
	v_mov_b32_e32 v98, v125
	v_mov_b32_e32 v89, v125
	v_mov_b32_e32 v88, v125
	v_mov_b32_e32 v87, v125
	v_mov_b32_e32 v86, v125
	v_mov_b32_e32 v85, v125
	v_mov_b32_e32 v84, v125
	v_mov_b32_e32 v83, v125
	v_mov_b32_e32 v82, v125
	v_mov_b32_e32 v73, v125
	v_mov_b32_e32 v72, v125
	v_mov_b32_e32 v71, v125
	v_mov_b32_e32 v70, v125
	v_mov_b32_e32 v69, v125
	v_mov_b32_e32 v68, v125
	v_mov_b32_e32 v67, v125
	v_mov_b32_e32 v66, v125
	v_mov_b32_e32 v65, v125
	v_mov_b32_e32 v64, v125
	v_mov_b32_e32 v63, v125
	v_mov_b32_e32 v62, v125
	v_mov_b32_e32 v61, v125
	v_mov_b32_e32 v60, v125
	v_mov_b32_e32 v59, v125
	v_mov_b32_e32 v58, v125
	v_mov_b32_e32 v49, v125
	v_mov_b32_e32 v48, v125
	v_mov_b32_e32 v47, v125
	v_mov_b32_e32 v46, v125
	v_mov_b32_e32 v45, v125
	v_mov_b32_e32 v44, v125
	v_mov_b32_e32 v43, v125
	v_mov_b32_e32 v42, v125
	v_mov_b32_e32 v33, v125
	v_mov_b32_e32 v32, v125
	v_mov_b32_e32 v31, v125
	v_mov_b32_e32 v30, v125
	v_mov_b32_e32 v29, v125
	v_mov_b32_e32 v28, v125
	v_mov_b32_e32 v27, v125
	v_mov_b32_e32 v26, v125
	v_mov_b32_e32 v17, v125
	v_mov_b32_e32 v16, v125
	v_mov_b32_e32 v15, v125
	v_mov_b32_e32 v14, v125
	v_mov_b32_e32 v13, v125
	v_mov_b32_e32 v12, v125
	v_mov_b32_e32 v11, v125
	v_mov_b32_e32 v10, v125
	v_mov_b32_e32 v57, v125
	v_mov_b32_e32 v56, v125
	v_mov_b32_e32 v55, v125
	v_mov_b32_e32 v54, v125
	v_mov_b32_e32 v53, v125
	v_mov_b32_e32 v52, v125
	v_mov_b32_e32 v51, v125
	v_mov_b32_e32 v50, v125
	v_mov_b32_e32 v41, v125
	v_mov_b32_e32 v40, v125
	v_mov_b32_e32 v39, v125
	v_mov_b32_e32 v38, v125
	v_mov_b32_e32 v37, v125
	v_mov_b32_e32 v36, v125
	v_mov_b32_e32 v35, v125
	v_mov_b32_e32 v34, v125
	v_mov_b32_e32 v25, v125
	v_mov_b32_e32 v24, v125
	v_mov_b32_e32 v23, v125
	v_mov_b32_e32 v22, v125
	v_mov_b32_e32 v21, v125
	v_mov_b32_e32 v20, v125
	v_mov_b32_e32 v19, v125
	v_mov_b32_e32 v18, v125
	v_mov_b32_e32 v9, v125
	v_mov_b32_e32 v8, v125
	v_mov_b32_e32 v7, v125
	v_mov_b32_e32 v6, v125
	v_mov_b32_e32 v5, v125
	v_mov_b32_e32 v4, v125
	v_mov_b32_e32 v3, v125
	v_mov_b32_e32 v2, v125
	s_cbranch_vccnz .LBB0_2177
	s_and_b64 s[8:9], s[40:41], exec
	s_cselect_b32 s8, s69, s73
	s_cselect_b32 s9, s70, s82
	s_addk_i32 s73, 0x80
	s_addk_i32 s82, 0x100
	s_mov_b32 s83, 0
	v_add_u32_e32 v144, 0x10000, v134
	ds_read_b128 v[136:139], v144
	ds_read_b128 v[140:143], v144 offset:1024
	ds_read_b128 v[154:157], v144 offset:2048
	ds_read_b128 v[170:173], v144 offset:3072
	v_add_u32_e32 v144, 0x14000, v134
	ds_read_b128 v[174:177], v144
	ds_read_b128 v[178:181], v144 offset:1024
	ds_read_b128 v[182:185], v144 offset:2048
	ds_read_b128 v[186:189], v144 offset:3072
	s_add_i32 s46, s73, 0x80
	s_cmp_eq_u32 s49, s83
	s_cselect_b32 s52, s8, s46
	s_cselect_b32 s85, s9, s82
	s_add_i32 s84, s52, 0x80
	s_add_i32 s46, s2, s73
	s_mov_b32 m0, s64
	ds_read_b128 v[190:193], v135
	ds_read_b128 v[194:197], v135 offset:1024
	ds_read_b128 v[198:201], v135 offset:2048
	ds_read_b128 v[202:205], v135 offset:3072
	ds_read_b128 v[228:231], v135 offset:4096
	ds_read_b128 v[232:235], v135 offset:5120
	ds_read_b128 v[236:239], v135 offset:6144
	ds_read_b128 v[240:243], v135 offset:7168
	buffer_load_dwordx4 v130, s[60:63], s46 offen lds
	s_mov_b32 m0, s65
	s_nop 0
	buffer_load_dwordx4 v132, s[60:63], s46 offen lds
	s_waitcnt vmcnt(8)
	s_waitcnt lgkmcnt(0)
	s_setprio 1
	s_barrier
	v_mfma_f32_16x16x32_bf16 v[122:125], v[136:139], v[190:193], 0
	v_mfma_f32_16x16x32_bf16 v[126:129], v[154:157], v[190:193], 0
	v_mfma_f32_16x16x32_bf16 v[110:113], v[136:139], v[198:201], 0
	v_mfma_f32_16x16x32_bf16 v[106:109], v[154:157], v[198:201], 0
	v_mfma_f32_16x16x32_bf16 v[94:97], v[136:139], v[228:231], 0
	v_mfma_f32_16x16x32_bf16 v[90:93], v[154:157], v[228:231], 0
	v_mfma_f32_16x16x32_bf16 v[78:81], v[136:139], v[236:239], 0
	v_mfma_f32_16x16x32_bf16 v[74:77], v[154:157], v[236:239], 0
	v_mfma_f32_16x16x32_bf16 v[122:125], v[140:143], v[194:197], v[122:125]
	v_mfma_f32_16x16x32_bf16 v[126:129], v[170:173], v[194:197], v[126:129]
	v_mfma_f32_16x16x32_bf16 v[110:113], v[140:143], v[202:205], v[110:113]
	v_mfma_f32_16x16x32_bf16 v[106:109], v[170:173], v[202:205], v[106:109]
	v_mfma_f32_16x16x32_bf16 v[94:97], v[140:143], v[232:235], v[94:97]
	v_mfma_f32_16x16x32_bf16 v[90:93], v[170:173], v[232:235], v[90:93]
	v_mfma_f32_16x16x32_bf16 v[78:81], v[140:143], v[240:243], v[78:81]
	v_mfma_f32_16x16x32_bf16 v[74:77], v[170:173], v[240:243], v[74:77]
	v_mfma_f32_16x16x32_bf16 v[118:121], v[174:177], v[190:193], 0
	v_mfma_f32_16x16x32_bf16 v[114:117], v[182:185], v[190:193], 0
	v_mfma_f32_16x16x32_bf16 v[102:105], v[174:177], v[198:201], 0
	v_mfma_f32_16x16x32_bf16 v[98:101], v[182:185], v[198:201], 0
	v_mfma_f32_16x16x32_bf16 v[86:89], v[174:177], v[228:231], 0
	v_mfma_f32_16x16x32_bf16 v[82:85], v[182:185], v[228:231], 0
	v_mfma_f32_16x16x32_bf16 v[70:73], v[174:177], v[236:239], 0
	v_mfma_f32_16x16x32_bf16 v[66:69], v[182:185], v[236:239], 0
	v_mfma_f32_16x16x32_bf16 v[118:121], v[178:181], v[194:197], v[118:121]
	v_mfma_f32_16x16x32_bf16 v[114:117], v[186:189], v[194:197], v[114:117]
	v_mfma_f32_16x16x32_bf16 v[102:105], v[178:181], v[202:205], v[102:105]
	v_mfma_f32_16x16x32_bf16 v[98:101], v[186:189], v[202:205], v[98:101]
	v_mfma_f32_16x16x32_bf16 v[86:89], v[178:181], v[232:235], v[86:89]
	v_mfma_f32_16x16x32_bf16 v[82:85], v[186:189], v[232:235], v[82:85]
	v_mfma_f32_16x16x32_bf16 v[70:73], v[178:181], v[240:243], v[70:73]
	v_mfma_f32_16x16x32_bf16 v[66:69], v[186:189], v[240:243], v[66:69]
	s_barrier
	s_setprio 0
	s_mov_b32 m0, s14
	s_mov_b32 s46, s62
	s_mov_b32 s47, s63
	ds_read_b128 v[190:193], v135 offset:16384
	ds_read_b128 v[194:197], v135 offset:17408
	ds_read_b128 v[198:201], v135 offset:18432
	ds_read_b128 v[202:205], v135 offset:19456
	ds_read_b128 v[228:231], v135 offset:20480
	ds_read_b128 v[232:235], v135 offset:21504
	ds_read_b128 v[236:239], v135 offset:22528
	ds_read_b128 v[240:243], v135 offset:23552
	buffer_load_dwordx4 v131, s[44:47], s85 offen lds
	s_mov_b32 m0, s15
	s_add_i32 s53, s85, s2
	buffer_load_dwordx4 v133, s[44:47], s85 offen lds
	s_mov_b32 m0, s16
	s_nop 0
	buffer_load_dwordx4 v131, s[44:47], s53 offen lds
	s_mov_b32 m0, s18
	s_nop 0
	buffer_load_dwordx4 v133, s[44:47], s53 offen lds
	s_mov_b32 m0, s13
	s_nop 0
	buffer_load_dwordx4 v130, s[60:63], s52 offen lds
	s_mov_b32 m0, s19
	s_nop 0
	buffer_load_dwordx4 v132, s[60:63], s52 offen lds
	s_waitcnt vmcnt(8)
	s_waitcnt lgkmcnt(0)
	s_setprio 1
	s_barrier
	v_mfma_f32_16x16x32_bf16 v[62:65], v[136:139], v[190:193], 0
	v_mfma_f32_16x16x32_bf16 v[58:61], v[154:157], v[190:193], 0
	v_mfma_f32_16x16x32_bf16 v[46:49], v[136:139], v[198:201], 0
	v_mfma_f32_16x16x32_bf16 v[42:45], v[154:157], v[198:201], 0
	v_mfma_f32_16x16x32_bf16 v[30:33], v[136:139], v[228:231], 0
	v_mfma_f32_16x16x32_bf16 v[26:29], v[154:157], v[228:231], 0
	v_mfma_f32_16x16x32_bf16 v[14:17], v[136:139], v[236:239], 0
	v_mfma_f32_16x16x32_bf16 v[10:13], v[154:157], v[236:239], 0
	v_mfma_f32_16x16x32_bf16 v[62:65], v[140:143], v[194:197], v[62:65]
	v_mfma_f32_16x16x32_bf16 v[58:61], v[170:173], v[194:197], v[58:61]
	v_mfma_f32_16x16x32_bf16 v[46:49], v[140:143], v[202:205], v[46:49]
	v_mfma_f32_16x16x32_bf16 v[42:45], v[170:173], v[202:205], v[42:45]
	v_mfma_f32_16x16x32_bf16 v[30:33], v[140:143], v[232:235], v[30:33]
	v_mfma_f32_16x16x32_bf16 v[26:29], v[170:173], v[232:235], v[26:29]
	v_mfma_f32_16x16x32_bf16 v[14:17], v[140:143], v[240:243], v[14:17]
	v_mfma_f32_16x16x32_bf16 v[10:13], v[170:173], v[240:243], v[10:13]
	v_mfma_f32_16x16x32_bf16 v[54:57], v[174:177], v[190:193], 0
	v_mfma_f32_16x16x32_bf16 v[50:53], v[182:185], v[190:193], 0
	v_mfma_f32_16x16x32_bf16 v[38:41], v[174:177], v[198:201], 0
	v_mfma_f32_16x16x32_bf16 v[34:37], v[182:185], v[198:201], 0
	v_mfma_f32_16x16x32_bf16 v[22:25], v[174:177], v[228:231], 0
	v_mfma_f32_16x16x32_bf16 v[18:21], v[182:185], v[228:231], 0
	v_mfma_f32_16x16x32_bf16 v[6:9], v[174:177], v[236:239], 0
	v_mfma_f32_16x16x32_bf16 v[2:5], v[182:185], v[236:239], 0
	v_mfma_f32_16x16x32_bf16 v[54:57], v[178:181], v[194:197], v[54:57]
	v_mfma_f32_16x16x32_bf16 v[50:53], v[186:189], v[194:197], v[50:53]
	v_mfma_f32_16x16x32_bf16 v[38:41], v[178:181], v[202:205], v[38:41]
	v_mfma_f32_16x16x32_bf16 v[34:37], v[186:189], v[202:205], v[34:37]
	v_mfma_f32_16x16x32_bf16 v[22:25], v[178:181], v[232:235], v[22:25]
	v_mfma_f32_16x16x32_bf16 v[18:21], v[186:189], v[232:235], v[18:21]
	v_mfma_f32_16x16x32_bf16 v[6:9], v[178:181], v[240:243], v[6:9]
	v_mfma_f32_16x16x32_bf16 v[2:5], v[186:189], v[240:243], v[2:5]
	s_barrier
	s_setprio 0
	v_add_u32_e32 v144, 0x18000, v134
	ds_read_b128 v[136:139], v144
	ds_read_b128 v[140:143], v144 offset:1024
	ds_read_b128 v[154:157], v144 offset:2048
	ds_read_b128 v[170:173], v144 offset:3072
	v_add_u32_e32 v144, 0x1c000, v134
	ds_read_b128 v[174:177], v144
	ds_read_b128 v[178:181], v144 offset:1024
	ds_read_b128 v[182:185], v144 offset:2048
	ds_read_b128 v[186:189], v144 offset:3072
	s_add_i32 s52, s52, s2
	s_mov_b32 m0, s21
	ds_read_b128 v[190:193], v135 offset:32768
	ds_read_b128 v[194:197], v135 offset:33792
	ds_read_b128 v[198:201], v135 offset:34816
	ds_read_b128 v[202:205], v135 offset:35840
	ds_read_b128 v[228:231], v135 offset:36864
	ds_read_b128 v[232:235], v135 offset:37888
	ds_read_b128 v[236:239], v135 offset:38912
	ds_read_b128 v[240:243], v135 offset:39936
	buffer_load_dwordx4 v130, s[60:63], s52 offen lds
	s_mov_b32 m0, s22
	s_nop 0
	buffer_load_dwordx4 v132, s[60:63], s52 offen lds
	s_waitcnt vmcnt(8)
	s_waitcnt lgkmcnt(0)
	s_setprio 1
	s_barrier
	v_mfma_f32_16x16x32_bf16 v[122:125], v[136:139], v[190:193], v[122:125]
	v_mfma_f32_16x16x32_bf16 v[126:129], v[154:157], v[190:193], v[126:129]
	v_mfma_f32_16x16x32_bf16 v[110:113], v[136:139], v[198:201], v[110:113]
	v_mfma_f32_16x16x32_bf16 v[106:109], v[154:157], v[198:201], v[106:109]
	v_mfma_f32_16x16x32_bf16 v[94:97], v[136:139], v[228:231], v[94:97]
	v_mfma_f32_16x16x32_bf16 v[90:93], v[154:157], v[228:231], v[90:93]
	v_mfma_f32_16x16x32_bf16 v[78:81], v[136:139], v[236:239], v[78:81]
	v_mfma_f32_16x16x32_bf16 v[74:77], v[154:157], v[236:239], v[74:77]
	v_mfma_f32_16x16x32_bf16 v[122:125], v[140:143], v[194:197], v[122:125]
	v_mfma_f32_16x16x32_bf16 v[126:129], v[170:173], v[194:197], v[126:129]
	v_mfma_f32_16x16x32_bf16 v[110:113], v[140:143], v[202:205], v[110:113]
	v_mfma_f32_16x16x32_bf16 v[106:109], v[170:173], v[202:205], v[106:109]
	v_mfma_f32_16x16x32_bf16 v[94:97], v[140:143], v[232:235], v[94:97]
	v_mfma_f32_16x16x32_bf16 v[90:93], v[170:173], v[232:235], v[90:93]
	v_mfma_f32_16x16x32_bf16 v[78:81], v[140:143], v[240:243], v[78:81]
	v_mfma_f32_16x16x32_bf16 v[74:77], v[170:173], v[240:243], v[74:77]
	v_mfma_f32_16x16x32_bf16 v[118:121], v[174:177], v[190:193], v[118:121]
	v_mfma_f32_16x16x32_bf16 v[114:117], v[182:185], v[190:193], v[114:117]
	v_mfma_f32_16x16x32_bf16 v[102:105], v[174:177], v[198:201], v[102:105]
	v_mfma_f32_16x16x32_bf16 v[98:101], v[182:185], v[198:201], v[98:101]
	v_mfma_f32_16x16x32_bf16 v[86:89], v[174:177], v[228:231], v[86:89]
	v_mfma_f32_16x16x32_bf16 v[82:85], v[182:185], v[228:231], v[82:85]
	v_mfma_f32_16x16x32_bf16 v[70:73], v[174:177], v[236:239], v[70:73]
	v_mfma_f32_16x16x32_bf16 v[66:69], v[182:185], v[236:239], v[66:69]
	v_mfma_f32_16x16x32_bf16 v[118:121], v[178:181], v[194:197], v[118:121]
	v_mfma_f32_16x16x32_bf16 v[114:117], v[186:189], v[194:197], v[114:117]
	v_mfma_f32_16x16x32_bf16 v[102:105], v[178:181], v[202:205], v[102:105]
	v_mfma_f32_16x16x32_bf16 v[98:101], v[186:189], v[202:205], v[98:101]
	v_mfma_f32_16x16x32_bf16 v[86:89], v[178:181], v[232:235], v[86:89]
	v_mfma_f32_16x16x32_bf16 v[82:85], v[186:189], v[232:235], v[82:85]
	v_mfma_f32_16x16x32_bf16 v[70:73], v[178:181], v[240:243], v[70:73]
	v_mfma_f32_16x16x32_bf16 v[66:69], v[186:189], v[240:243], v[66:69]
	s_barrier
	s_setprio 0
	s_mov_b32 m0, s33
	s_add_i32 s52, s85, 0x80
	ds_read_b128 v[190:193], v135 offset:49152
	ds_read_b128 v[194:197], v135 offset:50176
	ds_read_b128 v[198:201], v135 offset:51200
	ds_read_b128 v[202:205], v135 offset:52224
	ds_read_b128 v[228:231], v135 offset:53248
	ds_read_b128 v[232:235], v135 offset:54272
	ds_read_b128 v[236:239], v135 offset:55296
	ds_read_b128 v[240:243], v135 offset:56320
	buffer_load_dwordx4 v131, s[44:47], s52 offen lds
	s_mov_b32 m0, s36
	s_nop 0
	buffer_load_dwordx4 v133, s[44:47], s52 offen lds
	s_add_i32 s52, s52, s2
	s_mov_b32 m0, s43
	s_nop 0
	buffer_load_dwordx4 v131, s[44:47], s52 offen lds
	s_mov_b32 m0, s48
	s_nop 0
	buffer_load_dwordx4 v133, s[44:47], s52 offen lds
	s_mov_b32 m0, s37
	s_nop 0
	buffer_load_dwordx4 v130, s[60:63], s84 offen lds
	s_mov_b32 m0, s42
	s_nop 0
	buffer_load_dwordx4 v132, s[60:63], s84 offen lds
	s_waitcnt vmcnt(8)
	s_waitcnt lgkmcnt(0)
	s_setprio 1
	s_barrier
	v_mfma_f32_16x16x32_bf16 v[62:65], v[136:139], v[190:193], v[62:65]
	v_mfma_f32_16x16x32_bf16 v[58:61], v[154:157], v[190:193], v[58:61]
	v_mfma_f32_16x16x32_bf16 v[46:49], v[136:139], v[198:201], v[46:49]
	v_mfma_f32_16x16x32_bf16 v[42:45], v[154:157], v[198:201], v[42:45]
	v_mfma_f32_16x16x32_bf16 v[30:33], v[136:139], v[228:231], v[30:33]
	v_mfma_f32_16x16x32_bf16 v[26:29], v[154:157], v[228:231], v[26:29]
	v_mfma_f32_16x16x32_bf16 v[14:17], v[136:139], v[236:239], v[14:17]
	v_mfma_f32_16x16x32_bf16 v[10:13], v[154:157], v[236:239], v[10:13]
	v_mfma_f32_16x16x32_bf16 v[62:65], v[140:143], v[194:197], v[62:65]
	v_mfma_f32_16x16x32_bf16 v[58:61], v[170:173], v[194:197], v[58:61]
	v_mfma_f32_16x16x32_bf16 v[46:49], v[140:143], v[202:205], v[46:49]
	v_mfma_f32_16x16x32_bf16 v[42:45], v[170:173], v[202:205], v[42:45]
	v_mfma_f32_16x16x32_bf16 v[30:33], v[140:143], v[232:235], v[30:33]
	v_mfma_f32_16x16x32_bf16 v[26:29], v[170:173], v[232:235], v[26:29]
	v_mfma_f32_16x16x32_bf16 v[14:17], v[140:143], v[240:243], v[14:17]
	v_mfma_f32_16x16x32_bf16 v[10:13], v[170:173], v[240:243], v[10:13]
	v_mfma_f32_16x16x32_bf16 v[54:57], v[174:177], v[190:193], v[54:57]
	v_mfma_f32_16x16x32_bf16 v[50:53], v[182:185], v[190:193], v[50:53]
	v_mfma_f32_16x16x32_bf16 v[38:41], v[174:177], v[198:201], v[38:41]
	v_mfma_f32_16x16x32_bf16 v[34:37], v[182:185], v[198:201], v[34:37]
	v_mfma_f32_16x16x32_bf16 v[22:25], v[174:177], v[228:231], v[22:25]
	v_mfma_f32_16x16x32_bf16 v[18:21], v[182:185], v[228:231], v[18:21]
	v_mfma_f32_16x16x32_bf16 v[6:9], v[174:177], v[236:239], v[6:9]
	v_mfma_f32_16x16x32_bf16 v[2:5], v[182:185], v[236:239], v[2:5]
	v_mfma_f32_16x16x32_bf16 v[54:57], v[178:181], v[194:197], v[54:57]
	v_mfma_f32_16x16x32_bf16 v[50:53], v[186:189], v[194:197], v[50:53]
	v_mfma_f32_16x16x32_bf16 v[38:41], v[178:181], v[202:205], v[38:41]
	v_mfma_f32_16x16x32_bf16 v[34:37], v[186:189], v[202:205], v[34:37]
	v_mfma_f32_16x16x32_bf16 v[22:25], v[178:181], v[232:235], v[22:25]
	v_mfma_f32_16x16x32_bf16 v[18:21], v[186:189], v[232:235], v[18:21]
	v_mfma_f32_16x16x32_bf16 v[6:9], v[178:181], v[240:243], v[6:9]
	v_mfma_f32_16x16x32_bf16 v[2:5], v[186:189], v[240:243], v[2:5]
	s_barrier
	s_setprio 0
	s_add_i32 s83, s83, 2
	s_addk_i32 s73, 0x100
	s_addk_i32 s82, 0x100
	s_cmp_ge_i32 s83, s23

.LBB0_2449:
	s_lshl_b32 s73, s72, 20
	s_and_b64 s[8:9], s[40:41], exec
	s_cselect_b32 s8, s73, s13
	s_lshl_b32 s84, s71, 20
	s_and_b64 s[24:25], s[40:41], exec
	s_cselect_b32 s9, s84, s21
	s_add_i32 s13, s13, 0x80080
	s_addk_i32 s21, 0x100
	s_mov_b32 s22, -2
	s_waitcnt lgkmcnt(0)
	v_add_u32_e32 v142, 0x10000, v188
	v_add_u32_e32 v182, 0x14000, v188
	ds_read_b128 v[130:133], v142
	ds_read_b128 v[134:137], v142 offset:1024
	ds_read_b128 v[138:141], v142 offset:2048
	ds_read_b128 v[142:145], v142 offset:3072
	ds_read_b128 v[154:157], v182
	ds_read_b128 v[174:177], v182 offset:1024
	ds_read_b128 v[178:181], v182 offset:2048
	ds_read_b128 v[190:193], v182 offset:3072
	s_add_i32 s24, s13, 0xfff80080
	s_cmp_eq_u32 s22, 28
	s_cselect_b32 s52, s8, s24
	s_cselect_b32 s25, s9, s21
	s_or_b32 s24, s52, 0x80
	s_mov_b32 m0, s68
	ds_read_b128 v[194:197], v189
	ds_read_b128 v[198:201], v189 offset:1024
	ds_read_b128 v[202:205], v189 offset:2048
	ds_read_b128 v[228:231], v189 offset:3072
	ds_read_b128 v[232:235], v189 offset:4096
	ds_read_b128 v[236:239], v189 offset:5120
	ds_read_b128 v[240:243], v189 offset:6144
	ds_read_b128 v[244:247], v189 offset:7168
	buffer_load_dwordx4 v184, s[60:63], s13 offen lds
	s_mov_b32 m0, s70
	s_nop 0
	buffer_load_dwordx4 v186, s[60:63], s13 offen lds
	s_waitcnt vmcnt(8)
	s_waitcnt lgkmcnt(0)
	s_setprio 1
	s_barrier
	v_mfma_f32_16x16x32_bf16 v[126:129], v[130:133], v[194:197], 0
	v_mfma_f32_16x16x32_bf16 v[122:125], v[138:141], v[194:197], 0
	v_mfma_f32_16x16x32_bf16 v[110:113], v[130:133], v[202:205], 0
	v_mfma_f32_16x16x32_bf16 v[106:109], v[138:141], v[202:205], 0
	v_mfma_f32_16x16x32_bf16 v[94:97], v[130:133], v[232:235], 0
	v_mfma_f32_16x16x32_bf16 v[90:93], v[138:141], v[232:235], 0
	v_mfma_f32_16x16x32_bf16 v[78:81], v[130:133], v[240:243], 0
	v_mfma_f32_16x16x32_bf16 v[74:77], v[138:141], v[240:243], 0
	v_mfma_f32_16x16x32_bf16 v[126:129], v[134:137], v[198:201], v[126:129]
	v_mfma_f32_16x16x32_bf16 v[122:125], v[142:145], v[198:201], v[122:125]
	v_mfma_f32_16x16x32_bf16 v[110:113], v[134:137], v[228:231], v[110:113]
	v_mfma_f32_16x16x32_bf16 v[106:109], v[142:145], v[228:231], v[106:109]
	v_mfma_f32_16x16x32_bf16 v[94:97], v[134:137], v[236:239], v[94:97]
	v_mfma_f32_16x16x32_bf16 v[90:93], v[142:145], v[236:239], v[90:93]
	v_mfma_f32_16x16x32_bf16 v[78:81], v[134:137], v[244:247], v[78:81]
	v_mfma_f32_16x16x32_bf16 v[74:77], v[142:145], v[244:247], v[74:77]
	v_mfma_f32_16x16x32_bf16 v[118:121], v[154:157], v[194:197], 0
	v_mfma_f32_16x16x32_bf16 v[114:117], v[178:181], v[194:197], 0
	v_mfma_f32_16x16x32_bf16 v[102:105], v[154:157], v[202:205], 0
	v_mfma_f32_16x16x32_bf16 v[98:101], v[178:181], v[202:205], 0
	v_mfma_f32_16x16x32_bf16 v[86:89], v[154:157], v[232:235], 0
	v_mfma_f32_16x16x32_bf16 v[82:85], v[178:181], v[232:235], 0
	v_mfma_f32_16x16x32_bf16 v[70:73], v[154:157], v[240:243], 0
	v_mfma_f32_16x16x32_bf16 v[66:69], v[178:181], v[240:243], 0
	v_mfma_f32_16x16x32_bf16 v[118:121], v[174:177], v[198:201], v[118:121]
	v_mfma_f32_16x16x32_bf16 v[114:117], v[190:193], v[198:201], v[114:117]
	v_mfma_f32_16x16x32_bf16 v[102:105], v[174:177], v[228:231], v[102:105]
	v_mfma_f32_16x16x32_bf16 v[98:101], v[190:193], v[228:231], v[98:101]
	v_mfma_f32_16x16x32_bf16 v[86:89], v[174:177], v[236:239], v[86:89]
	v_mfma_f32_16x16x32_bf16 v[82:85], v[190:193], v[236:239], v[82:85]
	v_mfma_f32_16x16x32_bf16 v[70:73], v[174:177], v[244:247], v[70:73]
	v_mfma_f32_16x16x32_bf16 v[66:69], v[190:193], v[244:247], v[66:69]
	s_barrier
	s_setprio 0
	s_mov_b32 m0, s16
	s_mov_b32 s46, s62
	s_mov_b32 s47, s63
	ds_read_b128 v[194:197], v189 offset:16384
	ds_read_b128 v[198:201], v189 offset:17408
	ds_read_b128 v[202:205], v189 offset:18432
	ds_read_b128 v[228:231], v189 offset:19456
	ds_read_b128 v[232:235], v189 offset:20480
	ds_read_b128 v[236:239], v189 offset:21504
	ds_read_b128 v[240:243], v189 offset:22528
	ds_read_b128 v[244:247], v189 offset:23552
	buffer_load_dwordx4 v185, s[44:47], s25 offen lds
	s_mov_b32 m0, s18
	s_add_i32 s53, s25, 0x80000
	buffer_load_dwordx4 v187, s[44:47], s25 offen lds
	s_mov_b32 m0, s19
	s_nop 0
	buffer_load_dwordx4 v185, s[44:47], s53 offen lds
	s_mov_b32 m0, s23
	s_nop 0
	buffer_load_dwordx4 v187, s[44:47], s53 offen lds
	s_mov_b32 m0, s15
	s_nop 0
	buffer_load_dwordx4 v184, s[60:63], s52 offen lds
	s_mov_b32 m0, s26
	s_nop 0
	buffer_load_dwordx4 v186, s[60:63], s52 offen lds
	s_waitcnt vmcnt(8)
	s_waitcnt lgkmcnt(0)
	s_setprio 1
	s_barrier
	v_mfma_f32_16x16x32_bf16 v[62:65], v[130:133], v[194:197], 0
	v_mfma_f32_16x16x32_bf16 v[58:61], v[138:141], v[194:197], 0
	v_mfma_f32_16x16x32_bf16 v[46:49], v[130:133], v[202:205], 0
	v_mfma_f32_16x16x32_bf16 v[42:45], v[138:141], v[202:205], 0
	v_mfma_f32_16x16x32_bf16 v[30:33], v[130:133], v[232:235], 0
	v_mfma_f32_16x16x32_bf16 v[26:29], v[138:141], v[232:235], 0
	v_mfma_f32_16x16x32_bf16 v[14:17], v[130:133], v[240:243], 0
	v_mfma_f32_16x16x32_bf16 v[10:13], v[138:141], v[240:243], 0
	v_mfma_f32_16x16x32_bf16 v[62:65], v[134:137], v[198:201], v[62:65]
	v_mfma_f32_16x16x32_bf16 v[58:61], v[142:145], v[198:201], v[58:61]
	v_mfma_f32_16x16x32_bf16 v[46:49], v[134:137], v[228:231], v[46:49]
	v_mfma_f32_16x16x32_bf16 v[42:45], v[142:145], v[228:231], v[42:45]
	v_mfma_f32_16x16x32_bf16 v[30:33], v[134:137], v[236:239], v[30:33]
	v_mfma_f32_16x16x32_bf16 v[26:29], v[142:145], v[236:239], v[26:29]
	v_mfma_f32_16x16x32_bf16 v[14:17], v[134:137], v[244:247], v[14:17]
	v_mfma_f32_16x16x32_bf16 v[10:13], v[142:145], v[244:247], v[10:13]
	v_mfma_f32_16x16x32_bf16 v[54:57], v[154:157], v[194:197], 0
	v_mfma_f32_16x16x32_bf16 v[50:53], v[178:181], v[194:197], 0
	v_mfma_f32_16x16x32_bf16 v[38:41], v[154:157], v[202:205], 0
	v_mfma_f32_16x16x32_bf16 v[34:37], v[178:181], v[202:205], 0
	v_mfma_f32_16x16x32_bf16 v[22:25], v[154:157], v[232:235], 0
	v_mfma_f32_16x16x32_bf16 v[18:21], v[178:181], v[232:235], 0
	v_mfma_f32_16x16x32_bf16 v[6:9], v[154:157], v[240:243], 0
	v_mfma_f32_16x16x32_bf16 v[2:5], v[178:181], v[240:243], 0
	v_mfma_f32_16x16x32_bf16 v[54:57], v[174:177], v[198:201], v[54:57]
	v_mfma_f32_16x16x32_bf16 v[50:53], v[190:193], v[198:201], v[50:53]
	v_mfma_f32_16x16x32_bf16 v[38:41], v[174:177], v[228:231], v[38:41]
	v_mfma_f32_16x16x32_bf16 v[34:37], v[190:193], v[228:231], v[34:37]
	v_mfma_f32_16x16x32_bf16 v[22:25], v[174:177], v[236:239], v[22:25]
	v_mfma_f32_16x16x32_bf16 v[18:21], v[190:193], v[236:239], v[18:21]
	v_mfma_f32_16x16x32_bf16 v[6:9], v[174:177], v[244:247], v[6:9]
	v_mfma_f32_16x16x32_bf16 v[2:5], v[190:193], v[244:247], v[2:5]
	s_barrier
	s_setprio 0
	v_add_u32_e32 v142, 0x18000, v188
	v_add_u32_e32 v182, 0x1c000, v188
	ds_read_b128 v[130:133], v142
	ds_read_b128 v[134:137], v142 offset:1024
	ds_read_b128 v[138:141], v142 offset:2048
	ds_read_b128 v[142:145], v142 offset:3072
	ds_read_b128 v[154:157], v182
	ds_read_b128 v[174:177], v182 offset:1024
	ds_read_b128 v[178:181], v182 offset:2048
	ds_read_b128 v[190:193], v182 offset:3072
	s_add_i32 s52, s52, 0x80000
	s_mov_b32 m0, s27
	ds_read_b128 v[194:197], v189 offset:32768
	ds_read_b128 v[198:201], v189 offset:33792
	ds_read_b128 v[202:205], v189 offset:34816
	ds_read_b128 v[228:231], v189 offset:35840
	ds_read_b128 v[232:235], v189 offset:36864
	ds_read_b128 v[236:239], v189 offset:37888
	ds_read_b128 v[240:243], v189 offset:38912
	ds_read_b128 v[244:247], v189 offset:39936
	buffer_load_dwordx4 v184, s[60:63], s52 offen lds
	s_mov_b32 m0, s30
	s_nop 0
	buffer_load_dwordx4 v186, s[60:63], s52 offen lds
	s_waitcnt vmcnt(8)
	s_waitcnt lgkmcnt(0)
	s_setprio 1
	s_barrier
	v_mfma_f32_16x16x32_bf16 v[126:129], v[130:133], v[194:197], v[126:129]
	v_mfma_f32_16x16x32_bf16 v[122:125], v[138:141], v[194:197], v[122:125]
	v_mfma_f32_16x16x32_bf16 v[110:113], v[130:133], v[202:205], v[110:113]
	v_mfma_f32_16x16x32_bf16 v[106:109], v[138:141], v[202:205], v[106:109]
	v_mfma_f32_16x16x32_bf16 v[94:97], v[130:133], v[232:235], v[94:97]
	v_mfma_f32_16x16x32_bf16 v[90:93], v[138:141], v[232:235], v[90:93]
	v_mfma_f32_16x16x32_bf16 v[78:81], v[130:133], v[240:243], v[78:81]
	v_mfma_f32_16x16x32_bf16 v[74:77], v[138:141], v[240:243], v[74:77]
	v_mfma_f32_16x16x32_bf16 v[126:129], v[134:137], v[198:201], v[126:129]
	v_mfma_f32_16x16x32_bf16 v[122:125], v[142:145], v[198:201], v[122:125]
	v_mfma_f32_16x16x32_bf16 v[110:113], v[134:137], v[228:231], v[110:113]
	v_mfma_f32_16x16x32_bf16 v[106:109], v[142:145], v[228:231], v[106:109]
	v_mfma_f32_16x16x32_bf16 v[94:97], v[134:137], v[236:239], v[94:97]
	v_mfma_f32_16x16x32_bf16 v[90:93], v[142:145], v[236:239], v[90:93]
	v_mfma_f32_16x16x32_bf16 v[78:81], v[134:137], v[244:247], v[78:81]
	v_mfma_f32_16x16x32_bf16 v[74:77], v[142:145], v[244:247], v[74:77]
	v_mfma_f32_16x16x32_bf16 v[118:121], v[154:157], v[194:197], v[118:121]
	v_mfma_f32_16x16x32_bf16 v[114:117], v[178:181], v[194:197], v[114:117]
	v_mfma_f32_16x16x32_bf16 v[102:105], v[154:157], v[202:205], v[102:105]
	v_mfma_f32_16x16x32_bf16 v[98:101], v[178:181], v[202:205], v[98:101]
	v_mfma_f32_16x16x32_bf16 v[86:89], v[154:157], v[232:235], v[86:89]
	v_mfma_f32_16x16x32_bf16 v[82:85], v[178:181], v[232:235], v[82:85]
	v_mfma_f32_16x16x32_bf16 v[70:73], v[154:157], v[240:243], v[70:73]
	v_mfma_f32_16x16x32_bf16 v[66:69], v[178:181], v[240:243], v[66:69]
	v_mfma_f32_16x16x32_bf16 v[118:121], v[174:177], v[198:201], v[118:121]
	v_mfma_f32_16x16x32_bf16 v[114:117], v[190:193], v[198:201], v[114:117]
	v_mfma_f32_16x16x32_bf16 v[102:105], v[174:177], v[228:231], v[102:105]
	v_mfma_f32_16x16x32_bf16 v[98:101], v[190:193], v[228:231], v[98:101]
	v_mfma_f32_16x16x32_bf16 v[86:89], v[174:177], v[236:239], v[86:89]
	v_mfma_f32_16x16x32_bf16 v[82:85], v[190:193], v[236:239], v[82:85]
	v_mfma_f32_16x16x32_bf16 v[70:73], v[174:177], v[244:247], v[70:73]
	v_mfma_f32_16x16x32_bf16 v[66:69], v[190:193], v[244:247], v[66:69]
	s_barrier
	s_setprio 0
	s_mov_b32 m0, s36
	s_or_b32 s52, s25, 0x80
	ds_read_b128 v[194:197], v189 offset:49152
	ds_read_b128 v[198:201], v189 offset:50176
	ds_read_b128 v[202:205], v189 offset:51200
	ds_read_b128 v[228:231], v189 offset:52224
	ds_read_b128 v[232:235], v189 offset:53248
	ds_read_b128 v[236:239], v189 offset:54272
	ds_read_b128 v[240:243], v189 offset:55296
	ds_read_b128 v[244:247], v189 offset:56320
	buffer_load_dwordx4 v185, s[44:47], s52 offen lds
	s_mov_b32 m0, s37
	s_add_i32 s25, s25, 0x80080
	buffer_load_dwordx4 v187, s[44:47], s52 offen lds
	s_mov_b32 m0, s66
	s_nop 0
	buffer_load_dwordx4 v185, s[44:47], s25 offen lds
	s_mov_b32 m0, s67
	s_nop 0
	buffer_load_dwordx4 v187, s[44:47], s25 offen lds
	s_mov_b32 m0, s48
	s_nop 0
	buffer_load_dwordx4 v184, s[60:63], s24 offen lds
	s_mov_b32 m0, s49
	s_nop 0
	buffer_load_dwordx4 v186, s[60:63], s24 offen lds
	s_waitcnt vmcnt(8)
	s_waitcnt lgkmcnt(0)
	s_setprio 1
	s_barrier
	v_mfma_f32_16x16x32_bf16 v[62:65], v[130:133], v[194:197], v[62:65]
	v_mfma_f32_16x16x32_bf16 v[58:61], v[138:141], v[194:197], v[58:61]
	v_mfma_f32_16x16x32_bf16 v[46:49], v[130:133], v[202:205], v[46:49]
	v_mfma_f32_16x16x32_bf16 v[42:45], v[138:141], v[202:205], v[42:45]
	v_mfma_f32_16x16x32_bf16 v[30:33], v[130:133], v[232:235], v[30:33]
	v_mfma_f32_16x16x32_bf16 v[26:29], v[138:141], v[232:235], v[26:29]
	v_mfma_f32_16x16x32_bf16 v[14:17], v[130:133], v[240:243], v[14:17]
	v_mfma_f32_16x16x32_bf16 v[10:13], v[138:141], v[240:243], v[10:13]
	v_mfma_f32_16x16x32_bf16 v[62:65], v[134:137], v[198:201], v[62:65]
	v_mfma_f32_16x16x32_bf16 v[58:61], v[142:145], v[198:201], v[58:61]
	v_mfma_f32_16x16x32_bf16 v[46:49], v[134:137], v[228:231], v[46:49]
	v_mfma_f32_16x16x32_bf16 v[42:45], v[142:145], v[228:231], v[42:45]
	v_mfma_f32_16x16x32_bf16 v[30:33], v[134:137], v[236:239], v[30:33]
	v_mfma_f32_16x16x32_bf16 v[26:29], v[142:145], v[236:239], v[26:29]
	v_mfma_f32_16x16x32_bf16 v[14:17], v[134:137], v[244:247], v[14:17]
	v_mfma_f32_16x16x32_bf16 v[10:13], v[142:145], v[244:247], v[10:13]
	v_mfma_f32_16x16x32_bf16 v[54:57], v[154:157], v[194:197], v[54:57]
	v_mfma_f32_16x16x32_bf16 v[50:53], v[178:181], v[194:197], v[50:53]
	v_mfma_f32_16x16x32_bf16 v[38:41], v[154:157], v[202:205], v[38:41]
	v_mfma_f32_16x16x32_bf16 v[34:37], v[178:181], v[202:205], v[34:37]
	v_mfma_f32_16x16x32_bf16 v[22:25], v[154:157], v[232:235], v[22:25]
	v_mfma_f32_16x16x32_bf16 v[18:21], v[178:181], v[232:235], v[18:21]
	v_mfma_f32_16x16x32_bf16 v[6:9], v[154:157], v[240:243], v[6:9]
	v_mfma_f32_16x16x32_bf16 v[2:5], v[178:181], v[240:243], v[2:5]
	v_mfma_f32_16x16x32_bf16 v[54:57], v[174:177], v[198:201], v[54:57]
	v_mfma_f32_16x16x32_bf16 v[50:53], v[190:193], v[198:201], v[50:53]
	v_mfma_f32_16x16x32_bf16 v[38:41], v[174:177], v[228:231], v[38:41]
	v_mfma_f32_16x16x32_bf16 v[34:37], v[190:193], v[228:231], v[34:37]
	v_mfma_f32_16x16x32_bf16 v[22:25], v[174:177], v[236:239], v[22:25]
	v_mfma_f32_16x16x32_bf16 v[18:21], v[190:193], v[236:239], v[18:21]
	v_mfma_f32_16x16x32_bf16 v[6:9], v[174:177], v[244:247], v[6:9]
	v_mfma_f32_16x16x32_bf16 v[2:5], v[190:193], v[244:247], v[2:5]
	s_barrier
	s_setprio 0
	s_add_i32 s22, s22, 2
	s_addk_i32 s13, 0x100
	s_addk_i32 s21, 0x100
	s_cmp_gt_u32 s22, 29
